# stack: GLA state loads in flight + rw_finish v2 + packed score subtractions + permlane32 max exchange
# baseline (speedup 1.0000x reference)
; #define MFMA32(a, b, c) __builtin_amdgcn_mfma_f32_32x32x16_bf16((a), (b), (c), 0, 0, 0)
; template <int D>
; DI void attn_pass(const bfr* __restrict__ P, int b, int tq_wave, int qcol, int kcol, int vcol, int key0, int nkt, char* smem, f32x16 (&o)[2]) {
;     ...
;   for (int kt = 0; kt < nkt; ++kt) {
;     bfr* sK = sbase + (kt & 1) * 9216;
;     bfr* sV = sK + 64 * 72;
;     { int c = gt, row = c >> 3, kc = c & 7; *(u32x4*)(sK + row * KP + kc * 8) = kreg[0]; }
;     for (int i = 0; i < 1; ++i) {
;       int c = gt, row = c >> 3, kc = c & 7;
;       unsigned wds[4] = {vreg[i].x, vreg[i].y, vreg[i].z, vreg[i].w};
; #pragma unroll
;       for (int e = 0; e < 4; ++e) {
;         sV[(kc * 8 + 2 * e) * 72 + (row ^ (kc << 3))] = (bfr)(wds[e] & 0xffffu);
;         sV[(kc * 8 + 2 * e + 1) * 72 + (row ^ (kc << 3))] = (bfr)(wds[e] >> 16);
;       }
;     }
;     __syncthreads();
;     if (kt + 1 < nkt) {
;       const bfr* Pn = Pb + (size_t)(kt + 1) * 64 * PW;
;       { int c = gt, row = c >> 3, kc = c & 7; kreg[0] = *(const u32x4*)(Pn + (size_t)row * PW + kcol + kc * 8); vreg[0] = *(const u32x4*)(Pn + (size_t)row * PW + vcol + kc * 8); }
;     }
;     f32x16 s[2];
; #pragma unroll
;     for (int t2 = 0; t2 < 2; ++t2) {
; #pragma unroll
;       for (int i = 0; i < 16; ++i) s[t2][i] = 0.f;
; #pragma unroll
;       for (int ks = 0; ks < KS; ++ks) {
;         bf16x8 a = *(const bf16x8*)(sK + (t2 * 32 + r) * KP + ks * 16 + h * 8);
;         s[t2] = MFMA32(a, qf[ks], s[t2]);
;       }
;     }
;     float mx = s[0][0];
; #pragma unroll
;     for (int i = 0; i < 16; ++i) { mx = fmaxf(mx, s[0][i]); mx = fmaxf(mx, s[1][i]); }
;     mx = fmaxf(mx, __shfl_xor(mx, 32));
;     float mnew = fmaxf(mrun, mx);
;     float alpha = __builtin_amdgcn_exp2f(mrun - mnew);
;     mrun = mnew;
;     float ps = 0.f;
; #pragma unroll
;     for (int i = 0; i < 16; ++i) {
;       s[0][i] = __builtin_amdgcn_exp2f(s[0][i] - mnew); ps += s[0][i];
;       s[1][i] = __builtin_amdgcn_exp2f(s[1][i] - mnew); ps += s[1][i];
;     }
;     lsum = lsum * alpha + ps;
; #pragma unroll
;     for (int i = 0; i < 16; ++i) { accO[0][i] *= alpha; accO[1][i] *= alpha; }
.LBB0_400:
	s_bitcmp1_b32 s10, 0
	s_cselect_b32 s11, 0x4800, 0
	s_add_i32 s11, s11, 0
	v_add3_u32 v32, s11, v115, v90
	v_add_u32_e32 v121, s11, v114
	v_mov_b32_e32 v120, v113
	s_waitcnt vmcnt(1)
	ds_write_b128 v32, v[84:87]
	v_add3_u32 v32, s11, v117, v118
	v_add3_u32 v33, s11, v118, v117
	v_add_u32_e32 v113, v121, v152
	s_waitcnt vmcnt(0)
	ds_write_b16 v32, v80 offset:9216
	ds_write_b16_d16_hi v33, v80 offset:9360
	ds_write_b16 v32, v81 offset:9504
	ds_write_b16_d16_hi v33, v81 offset:9648
	ds_write_b16 v32, v82 offset:9792
	ds_write_b16_d16_hi v33, v82 offset:9936
	ds_write_b16 v32, v83 offset:10080
	ds_write_b16_d16_hi v33, v83 offset:10224
	s_waitcnt lgkmcnt(0)
	s_barrier
	global_load_dwordx4 v[84:87], v[92:93], off
	global_load_dwordx4 v[80:83], v[94:95], off
	ds_read_b128 v[32:35], v113
	ds_read_b128 v[48:51], v113 offset:32
	s_waitcnt lgkmcnt(1)
	v_mfma_f32_32x32x16_bf16 v[32:47], v[32:35], v[76:79], 0
	ds_read_b128 v[122:125], v113 offset:4640
	v_mov_b32_e32 v96, v119
	s_add_i32 s10, s10, 1
	v_lshl_add_u64 v[92:93], v[92:93], 0, s[12:13]
	v_lshl_add_u64 v[94:95], v[94:95], 0, s[12:13]
	s_cmp_lg_u32 s10, 3
	s_waitcnt lgkmcnt(1)
	v_mfma_f32_32x32x16_bf16 v[32:47], v[48:51], v[72:75], v[32:47]
	ds_read_b128 v[48:51], v113 offset:64
	s_waitcnt lgkmcnt(0)
	v_mfma_f32_32x32x16_bf16 v[32:47], v[48:51], v[68:71], v[32:47]
	ds_read_b128 v[48:51], v113 offset:96
	s_waitcnt lgkmcnt(0)
	v_mfma_f32_32x32x16_bf16 v[32:47], v[48:51], v[64:67], v[32:47]
	ds_read_b128 v[48:51], v113 offset:4608
	s_waitcnt lgkmcnt(0)
	v_mfma_f32_32x32x16_bf16 v[48:63], v[48:51], v[76:79], 0
	s_nop 8
	v_max_f32_e32 v119, v32, v32
	v_mfma_f32_32x32x16_bf16 v[48:63], v[122:125], v[72:75], v[48:63]
	ds_read_b128 v[122:125], v113 offset:4672
	s_waitcnt lgkmcnt(0)
	v_mfma_f32_32x32x16_bf16 v[48:63], v[122:125], v[68:71], v[48:63]
	ds_read_b128 v[122:125], v113 offset:4704
	s_waitcnt lgkmcnt(0)
	v_mfma_f32_32x32x16_bf16 v[48:63], v[122:125], v[64:67], v[48:63]
	s_nop 11
	v_max_f32_e32 v113, v48, v48
	v_max_f32_e32 v113, v119, v113
	v_max3_f32 v113, v113, v33, v49
	v_max3_f32 v113, v113, v34, v50
	v_max3_f32 v113, v113, v35, v51
	v_max3_f32 v113, v113, v36, v52
	v_max3_f32 v113, v113, v37, v53
	v_max3_f32 v113, v113, v38, v54
	v_max3_f32 v113, v113, v39, v55
	v_max3_f32 v113, v113, v40, v56
	v_max3_f32 v113, v113, v41, v57
	v_max3_f32 v113, v113, v42, v58
	v_max3_f32 v113, v113, v43, v59
	v_max3_f32 v113, v113, v44, v60
	v_max3_f32 v113, v113, v45, v61
	v_max3_f32 v113, v113, v46, v62
	v_max3_f32 v113, v113, v47, v63
	v_mov_b32_e32 v119, v113
	s_nop 1
	v_permlane32_swap_b32_e32 v113, v119
	s_waitcnt lgkmcnt(0)
	v_max3_f32 v119, v96, v113, v119
	v_pk_add_f32 v[32:33], v[32:33], v[118:119] op_sel:[0,1] op_sel_hi:[1,1] neg_lo:[0,1] neg_hi:[0,1]
	v_pk_add_f32 v[38:39], v[38:39], v[118:119] op_sel:[0,1] op_sel_hi:[1,1] neg_lo:[0,1] neg_hi:[0,1]
	v_exp_f32_e32 v32, v32
	v_pk_add_f32 v[48:49], v[48:49], v[118:119] op_sel:[0,1] op_sel_hi:[1,1] neg_lo:[0,1] neg_hi:[0,1]
	v_pk_add_f32 v[36:37], v[36:37], v[118:119] op_sel:[0,1] op_sel_hi:[1,1] neg_lo:[0,1] neg_hi:[0,1]
	v_exp_f32_e32 v124, v38
	v_pk_add_f32 v[54:55], v[54:55], v[118:119] op_sel:[0,1] op_sel_hi:[1,1] neg_lo:[0,1] neg_hi:[0,1]
	v_exp_f32_e32 v48, v48
	v_exp_f32_e32 v122, v36
	v_sub_f32_e32 v36, v52, v119
	v_exp_f32_e32 v52, v54
	v_exp_f32_e32 v33, v33
	v_exp_f32_e32 v125, v39
	v_exp_f32_e32 v49, v49
	v_pk_add_f32 v[34:35], v[34:35], v[118:119] op_sel:[0,1] op_sel_hi:[1,1] neg_lo:[0,1] neg_hi:[0,1]
	v_exp_f32_e32 v123, v37
	v_sub_f32_e32 v37, v53, v119
	v_exp_f32_e32 v53, v55
	v_pk_add_f32 v[40:41], v[40:41], v[118:119] op_sel:[0,1] op_sel_hi:[1,1] neg_lo:[0,1] neg_hi:[0,1]
	v_pk_add_f32 v[42:43], v[42:43], v[118:119] op_sel:[0,1] op_sel_hi:[1,1] neg_lo:[0,1] neg_hi:[0,1]
	v_pk_add_f32 v[44:45], v[44:45], v[118:119] op_sel:[0,1] op_sel_hi:[1,1] neg_lo:[0,1] neg_hi:[0,1]
	v_exp_f32_e32 v34, v34
	v_pk_add_f32 v[50:51], v[50:51], v[118:119] op_sel:[0,1] op_sel_hi:[1,1] neg_lo:[0,1] neg_hi:[0,1]
	v_exp_f32_e32 v54, v40
	v_sub_f32_e32 v38, v56, v119
	v_exp_f32_e32 v56, v42
	v_sub_f32_e32 v40, v58, v119
	v_exp_f32_e32 v58, v44
	v_sub_f32_e32 v42, v60, v119
	v_add_f32_e32 v60, 0, v32
	v_exp_f32_e32 v50, v50
	v_add_f32_e32 v60, v48, v60
	v_exp_f32_e32 v35, v35
	v_add_f32_e32 v60, v33, v60
	v_exp_f32_e32 v51, v51
	v_add_f32_e32 v60, v49, v60
	v_add_f32_e32 v60, v34, v60
	v_exp_f32_e32 v36, v36
	v_add_f32_e32 v60, v50, v60
	v_add_f32_e32 v60, v35, v60
	v_exp_f32_e32 v37, v37
	v_add_f32_e32 v60, v51, v60
	v_add_f32_e32 v60, v122, v60
	v_add_f32_e32 v60, v36, v60
	v_add_f32_e32 v60, v123, v60
	v_add_f32_e32 v60, v37, v60
	v_add_f32_e32 v60, v124, v60
	v_exp_f32_e32 v38, v38
	v_add_f32_e32 v60, v52, v60
	v_exp_f32_e32 v55, v41
	v_sub_f32_e32 v39, v57, v119
	v_add_f32_e32 v60, v125, v60
	v_exp_f32_e32 v39, v39
	v_add_f32_e32 v60, v53, v60
	v_add_f32_e32 v60, v54, v60
	v_exp_f32_e32 v40, v40
	v_add_f32_e32 v60, v38, v60
	v_exp_f32_e32 v57, v43
	v_sub_f32_e32 v41, v59, v119
	v_add_f32_e32 v60, v55, v60
	v_exp_f32_e32 v41, v41
	v_add_f32_e32 v60, v39, v60
	v_add_f32_e32 v60, v56, v60
	v_exp_f32_e32 v42, v42
	v_add_f32_e32 v60, v40, v60
	v_exp_f32_e32 v59, v45
	v_sub_f32_e32 v43, v61, v119
	v_add_f32_e32 v60, v57, v60
	v_exp_f32_e32 v43, v43
	v_pk_add_f32 v[46:47], v[46:47], v[118:119] op_sel:[0,1] op_sel_hi:[1,1] neg_lo:[0,1] neg_hi:[0,1]
	v_add_f32_e32 v60, v41, v60
	v_exp_f32_e32 v46, v46
	v_pk_add_f32 v[62:63], v[62:63], v[118:119] op_sel:[0,1] op_sel_hi:[1,1] neg_lo:[0,1] neg_hi:[0,1]
	v_add_f32_e32 v60, v58, v60
	v_exp_f32_e32 v44, v62
	v_add_f32_e32 v60, v42, v60
	v_exp_f32_e32 v47, v47
	v_add_f32_e32 v60, v59, v60
	v_exp_f32_e32 v45, v63
	v_add_f32_e32 v60, v43, v60
	v_add_f32_e32 v60, v46, v60
	v_add_f32_e32 v60, v44, v60
	v_add_f32_e32 v60, v47, v60
	v_add_f32_e32 v113, v45, v60
	v_lshl_add_u32 v60, v112, 1, v121
	v_lshl_add_u32 v61, v111, 1, v121
	v_cvt_pk_bf16_f32 v32, v32, v33
	v_cvt_pk_bf16_f32 v33, v34, v35
	v_cvt_pk_bf16_f32 v34, v122, v123
	v_cvt_pk_bf16_f32 v35, v124, v125
	ds_read_b64 v[122:123], v60 offset:9216
	ds_read_b64 v[124:125], v61 offset:9216
	v_sub_f32_e32 v96, v96, v119
	v_exp_f32_e32 v96, v96
	v_add_u32_e32 v61, s11, v116
	v_lshl_add_u32 v62, v110, 1, v61
	v_pk_mul_f32 v[30:31], v[30:31], v[96:97] op_sel_hi:[1,0]
	v_pk_mul_f32 v[28:29], v[28:29], v[96:97] op_sel_hi:[1,0]
	v_pk_mul_f32 v[26:27], v[26:27], v[96:97] op_sel_hi:[1,0]
	v_pk_mul_f32 v[24:25], v[24:25], v[96:97] op_sel_hi:[1,0]
	v_pk_mul_f32 v[22:23], v[22:23], v[96:97] op_sel_hi:[1,0]
	v_pk_mul_f32 v[20:21], v[20:21], v[96:97] op_sel_hi:[1,0]
	v_pk_mul_f32 v[18:19], v[18:19], v[96:97] op_sel_hi:[1,0]
	v_pk_mul_f32 v[16:17], v[16:17], v[96:97] op_sel_hi:[1,0]
	v_pk_mul_f32 v[14:15], v[14:15], v[96:97] op_sel_hi:[1,0]
	v_pk_mul_f32 v[12:13], v[12:13], v[96:97] op_sel_hi:[1,0]
	s_waitcnt lgkmcnt(0)
; template <int D>
; DI void attn_pass(const bfr* __restrict__ P, int b, int tq_wave, int qcol, int kcol, int vcol, int key0, int nkt, char* smem, f32x16 (&o)[2]) {
;     ...
;   for (int kt = 0; kt < nkt; ++kt) {
;     bfr* sK = sbase + (kt & 1) * 9216;
;     bfr* sV = sK + 64 * 72;
;     { int c = gt, row = c >> 3, kc = c & 7; *(u32x4*)(sK + row * KP + kc * 8) = kreg[0]; }
;     for (int i = 0; i < 1; ++i) {
;       int c = gt, row = c >> 3, kc = c & 7;
;       unsigned wds[4] = {vreg[i].x, vreg[i].y, vreg[i].z, vreg[i].w};
; #pragma unroll
;       for (int e = 0; e < 4; ++e) {
;         sV[(kc * 8 + 2 * e) * 72 + (row ^ (kc << 3))] = (bfr)(wds[e] & 0xffffu);
;         sV[(kc * 8 + 2 * e + 1) * 72 + (row ^ (kc << 3))] = (bfr)(wds[e] >> 16);
;       }
;     }
;     __syncthreads();
;     if (kt + 1 < nkt) {
;       const bfr* Pn = Pb + (size_t)(kt + 1) * 64 * PW;
;       { int c = gt, row = c >> 3, kc = c & 7; kreg[0] = *(const u32x4*)(Pn + (size_t)row * PW + kcol + kc * 8); vreg[0] = *(const u32x4*)(Pn + (size_t)row * PW + vcol + kc * 8); }
;     }
;     f32x16 s[2];
; #pragma unroll
;     for (int t2 = 0; t2 < 2; ++t2) {
; #pragma unroll
;       for (int i = 0; i < 16; ++i) s[t2][i] = 0.f;
; #pragma unroll
;       for (int ks = 0; ks < KS; ++ks) {
;         bf16x8 a = *(const bf16x8*)(sK + (t2 * 32 + r) * KP + ks * 16 + h * 8);
;         s[t2] = MFMA32(a, qf[ks], s[t2]);
;       }
;     }
;     float mx = s[0][0];
; #pragma unroll
;     for (int i = 0; i < 16; ++i) { mx = fmaxf(mx, s[0][i]); mx = fmaxf(mx, s[1][i]); }
;     ...
; #pragma unroll
;     for (int t2 = 0; t2 < 2; ++t2)
; #pragma unroll
;       for (int j = 0; j < 2; ++j) {
;         unsigned pk[4];
; #pragma unroll
;         for (int e = 0; e < 4; ++e) pk[e] = pack2(s[t2][8 * j + 2 * e], s[t2][8 * j + 2 * e + 1]);
;         u32x4 pku = {pk[0], pk[1], pk[2], pk[3]};
;         bf16x8 pf = __builtin_bit_cast(bf16x8, pku);
; #pragma unroll
;         for (int dt = 0; dt < 2; ++dt) {
;           const int vsw = (((dt * 32 + r) >> 3) & 7) << 3;
;           const bfr* vrow = sV + (dt * 32 + r) * 72;
;           s16x4 lo = *(const s16x4*)(vrow + ((t2 * 32 + 16 * j + 4 * h) ^ vsw));
;           s16x4 hi = *(const s16x4*)(vrow + ((t2 * 32 + 16 * j + 4 * h + 8) ^ vsw));
;           bf16x8 vf = __builtin_shufflevector(lo, hi, 0, 1, 2, 3, 4, 5, 6, 7);
;           accO[dt] = MFMA32(vf, pf, accO[dt]);
;         }
;       }
	v_mfma_f32_32x32x16_bf16 v[16:31], v[122:125], v[32:35], v[16:31]
	ds_read_b64 v[122:123], v62 offset:9216
	v_lshl_add_u32 v62, v109, 1, v61
	ds_read_b64 v[124:125], v62 offset:9216
	v_mul_f32_e64 v10, v10, v96
	v_mul_f32_e64 v11, v11, v96
	v_pk_mul_f32 v[8:9], v[8:9], v[96:97] op_sel_hi:[1,0]
	v_pk_mul_f32 v[6:7], v[6:7], v[96:97] op_sel_hi:[1,0]
	v_pk_mul_f32 v[4:5], v[4:5], v[96:97] op_sel_hi:[1,0]
	v_pk_mul_f32 v[2:3], v[2:3], v[96:97] op_sel_hi:[1,0]
	v_pk_mul_f32 v[0:1], v[0:1], v[96:97] op_sel_hi:[1,0]
	v_fmac_f32_e32 v113, v120, v96
	s_waitcnt lgkmcnt(0)
	v_mfma_f32_32x32x16_bf16 v[0:15], v[122:125], v[32:35], v[0:15]
	v_cvt_pk_bf16_f32 v32, v54, v55
	v_cvt_pk_bf16_f32 v33, v56, v57
	v_cvt_pk_bf16_f32 v34, v58, v59
	v_cvt_pk_bf16_f32 v35, v46, v47
	v_lshl_add_u32 v46, v108, 1, v121
	ds_read_b64 v[54:55], v46 offset:9216
	v_lshl_add_u32 v46, v107, 1, v121
	ds_read_b64 v[56:57], v46 offset:9216
	v_lshl_add_u32 v46, v106, 1, v61
	s_waitcnt lgkmcnt(0)
	v_mfma_f32_32x32x16_bf16 v[16:31], v[54:57], v[32:35], v[16:31]
	ds_read_b64 v[54:55], v46 offset:9216
	v_lshl_add_u32 v46, v105, 1, v61
	ds_read_b64 v[56:57], v46 offset:9216
	s_waitcnt lgkmcnt(0)
	v_mfma_f32_32x32x16_bf16 v[0:15], v[54:57], v[32:35], v[0:15]
	v_cvt_pk_bf16_f32 v32, v48, v49
	v_cvt_pk_bf16_f32 v33, v50, v51
	v_cvt_pk_bf16_f32 v34, v36, v37
	v_lshl_add_u32 v36, v104, 1, v121
	v_cvt_pk_bf16_f32 v35, v52, v53
	ds_read_b64 v[46:47], v60 offset:9280
	ds_read_b64 v[48:49], v36 offset:9216
	v_lshl_add_u32 v36, v103, 1, v61
	s_waitcnt lgkmcnt(0)
	v_mfma_f32_32x32x16_bf16 v[16:31], v[46:49], v[32:35], v[16:31]
	ds_read_b64 v[46:47], v36 offset:9216
	v_lshl_add_u32 v36, v102, 1, v61
	ds_read_b64 v[48:49], v36 offset:9216
	v_lshl_add_u32 v36, v100, 1, v121
	s_waitcnt lgkmcnt(0)
	v_mfma_f32_32x32x16_bf16 v[0:15], v[46:49], v[32:35], v[0:15]
	v_cvt_pk_bf16_f32 v32, v38, v39
	v_lshl_add_u32 v38, v101, 1, v121
	v_cvt_pk_bf16_f32 v33, v40, v41
	v_cvt_pk_bf16_f32 v34, v42, v43
	v_cvt_pk_bf16_f32 v35, v44, v45
	ds_read_b64 v[36:37], v36 offset:9216
	ds_read_b64 v[38:39], v38 offset:9216
	s_waitcnt lgkmcnt(0)
	v_mfma_f32_32x32x16_bf16 v[16:31], v[36:39], v[32:35], v[16:31]
	v_lshl_add_u32 v36, v99, 1, v61
	v_lshl_add_u32 v38, v98, 1, v61
	ds_read_b64 v[36:37], v36 offset:9216
	ds_read_b64 v[38:39], v38 offset:9216
	s_waitcnt lgkmcnt(0)
	v_mfma_f32_32x32x16_bf16 v[0:15], v[36:39], v[32:35], v[0:15]
	s_cbranch_scc1 .LBB0_400
	v_add3_u32 v32, 0, v115, v90
	s_waitcnt vmcnt(1)
	ds_write_b128 v32, v[84:87] offset:18432
	v_add3_u32 v32, 0, v117, v118
	v_add3_u32 v33, 0, v118, v117
	s_waitcnt vmcnt(0)
	ds_write_b16 v32, v80 offset:27648
	ds_write_b16_d16_hi v33, v80 offset:27792
	ds_write_b16 v32, v81 offset:27936
	ds_write_b16_d16_hi v33, v81 offset:28080
	ds_write_b16 v32, v82 offset:28224
	ds_write_b16_d16_hi v33, v82 offset:28368
	ds_write_b16 v32, v83 offset:28512
	ds_write_b16_d16_hi v33, v83 offset:28656
	v_add_u32_e32 v80, 0, v114
	v_add_u32_e32 v81, v80, v152
	s_waitcnt lgkmcnt(0)
	s_barrier
	ds_read_b128 v[32:35], v81 offset:18432
	ds_read_b128 v[48:51], v81 offset:18464
	s_waitcnt lgkmcnt(1)
	v_mfma_f32_32x32x16_bf16 v[32:47], v[32:35], v[76:79], 0
	v_lshlrev_b32_e32 v152, 1, v88
	s_waitcnt lgkmcnt(0)
	v_mfma_f32_32x32x16_bf16 v[32:47], v[48:51], v[72:75], v[32:47]
	ds_read_b128 v[48:51], v81 offset:18496
	s_waitcnt lgkmcnt(0)
	v_mfma_f32_32x32x16_bf16 v[32:47], v[48:51], v[68:71], v[32:47]
	ds_read_b128 v[48:51], v81 offset:18528
	s_waitcnt lgkmcnt(0)
	v_mfma_f32_32x32x16_bf16 v[32:47], v[48:51], v[64:67], v[32:47]
	ds_read_b128 v[48:51], v81 offset:23040
	s_waitcnt lgkmcnt(0)
	v_mfma_f32_32x32x16_bf16 v[48:63], v[48:51], v[76:79], 0
	ds_read_b128 v[76:79], v81 offset:23072
	s_waitcnt lgkmcnt(0)
	v_mfma_f32_32x32x16_bf16 v[48:63], v[76:79], v[72:75], v[48:63]
	ds_read_b128 v[72:75], v81 offset:23104
	s_waitcnt lgkmcnt(0)
	v_mfma_f32_32x32x16_bf16 v[48:63], v[72:75], v[68:71], v[48:63]
	ds_read_b128 v[68:71], v81 offset:23136
	s_waitcnt lgkmcnt(0)
	v_mfma_f32_32x32x16_bf16 v[48:63], v[68:71], v[64:67], v[48:63]
	v_max_f32_e32 v65, v32, v32
	v_lshl_add_u32 v66, v112, 1, v80
	v_add_u32_e32 v67, 0x1200, v80
	s_nop 8
	v_max_f32_e32 v64, v48, v48
	v_max_f32_e32 v64, v65, v64
	v_max3_f32 v64, v64, v33, v49
	v_max3_f32 v64, v64, v34, v50
	v_max3_f32 v64, v64, v35, v51
	v_max3_f32 v64, v64, v36, v52
	v_max3_f32 v64, v64, v37, v53
	v_max3_f32 v64, v64, v38, v54
	v_max3_f32 v64, v64, v39, v55
	v_max3_f32 v64, v64, v40, v56
	v_max3_f32 v64, v64, v41, v57
	v_max3_f32 v64, v64, v42, v58
	v_max3_f32 v64, v64, v43, v59
	v_max3_f32 v64, v64, v44, v60
	v_max3_f32 v64, v64, v45, v61
	v_max3_f32 v64, v64, v46, v62
	v_max3_f32 v64, v64, v47, v63
	ds_bpermute_b32 v65, v91, v64
	s_waitcnt lgkmcnt(0)
; #define MFMA32(a, b, c) __builtin_amdgcn_mfma_f32_32x32x16_bf16((a), (b), (c), 0, 0, 0)
; DI unsigned pack2(float a, float b) { unsigned r; asm volatile("v_cvt_pk_bf16_f32 %0, %1, %2" : "=v"(r) : "v"(a), "v"(b)); return r; }
; template <int D>
; DI void attn_pass(const bfr* __restrict__ P, int b, int tq_wave, int qcol, int kcol, int vcol, int key0, int nkt, char* smem, f32x16 (&o)[2]) {
;     ...
;     float mnew = fmaxf(mrun, mx);
;     float alpha = __builtin_amdgcn_exp2f(mrun - mnew);
;     mrun = mnew;
;     float ps = 0.f;
; #pragma unroll
;     for (int i = 0; i < 16; ++i) {
;       s[0][i] = __builtin_amdgcn_exp2f(s[0][i] - mnew); ps += s[0][i];
;       s[1][i] = __builtin_amdgcn_exp2f(s[1][i] - mnew); ps += s[1][i];
;     }
;     lsum = lsum * alpha + ps;
; #pragma unroll
;     for (int i = 0; i < 16; ++i) { accO[0][i] *= alpha; accO[1][i] *= alpha; }
; #pragma unroll
;     for (int t2 = 0; t2 < 2; ++t2)
; #pragma unroll
;       for (int j = 0; j < 2; ++j) {
;         unsigned pk[4];
; #pragma unroll
;         for (int e = 0; e < 4; ++e) pk[e] = pack2(s[t2][8 * j + 2 * e], s[t2][8 * j + 2 * e + 1]);
;         u32x4 pku = {pk[0], pk[1], pk[2], pk[3]};
;         bf16x8 pf = __builtin_bit_cast(bf16x8, pku);
; #pragma unroll
;         for (int dt = 0; dt < 2; ++dt) {
;           const int vsw = (((dt * 32 + r) >> 3) & 7) << 3;
;           const bfr* vrow = sV + (dt * 32 + r) * 72;
;           s16x4 lo = *(const s16x4*)(vrow + ((t2 * 32 + 16 * j + 4 * h) ^ vsw));
;           s16x4 hi = *(const s16x4*)(vrow + ((t2 * 32 + 16 * j + 4 * h + 8) ^ vsw));
;           bf16x8 vf = __builtin_shufflevector(lo, hi, 0, 1, 2, 3, 4, 5, 6, 7);
;           accO[dt] = MFMA32(vf, pf, accO[dt]);
;         }
;       }
	v_max3_f32 v65, v119, v64, v65
	v_sub_f32_e32 v64, v119, v65
	v_sub_f32_e32 v32, v32, v65
	v_exp_f32_e32 v64, v64
	v_exp_f32_e32 v32, v32
	v_sub_f32_e32 v48, v48, v65
	v_exp_f32_e32 v48, v48
	v_sub_f32_e32 v33, v33, v65
	v_exp_f32_e32 v33, v33
	v_sub_f32_e32 v49, v49, v65
	v_exp_f32_e32 v49, v49
	v_sub_f32_e32 v34, v34, v65
	v_exp_f32_e32 v34, v34
	v_sub_f32_e32 v50, v50, v65
	v_sub_f32_e32 v35, v35, v65
	v_sub_f32_e32 v51, v51, v65
	v_sub_f32_e32 v36, v36, v65
	v_sub_f32_e32 v52, v52, v65
	v_sub_f32_e32 v37, v37, v65
	v_sub_f32_e32 v53, v53, v65
	v_sub_f32_e32 v38, v38, v65
	v_sub_f32_e32 v54, v54, v65
	v_sub_f32_e32 v39, v39, v65
	v_sub_f32_e32 v55, v55, v65
	v_sub_f32_e32 v40, v40, v65
	v_sub_f32_e32 v56, v56, v65
	v_sub_f32_e32 v41, v41, v65
	v_sub_f32_e32 v57, v57, v65
	v_sub_f32_e32 v42, v42, v65
	v_sub_f32_e32 v58, v58, v65
	v_sub_f32_e32 v43, v43, v65
	v_sub_f32_e32 v59, v59, v65
	v_sub_f32_e32 v44, v44, v65
	v_sub_f32_e32 v60, v60, v65
	v_sub_f32_e32 v45, v45, v65
	v_sub_f32_e32 v61, v61, v65
	v_sub_f32_e32 v46, v46, v65
	v_sub_f32_e32 v62, v62, v65
	v_sub_f32_e32 v47, v47, v65
	v_sub_f32_e32 v63, v63, v65
	v_pk_mul_f32 v[30:31], v[30:31], v[64:65] op_sel_hi:[1,0]
	v_pk_mul_f32 v[28:29], v[28:29], v[64:65] op_sel_hi:[1,0]
	v_pk_mul_f32 v[26:27], v[26:27], v[64:65] op_sel_hi:[1,0]
	v_pk_mul_f32 v[24:25], v[24:25], v[64:65] op_sel_hi:[1,0]
	v_pk_mul_f32 v[22:23], v[22:23], v[64:65] op_sel_hi:[1,0]
	v_pk_mul_f32 v[20:21], v[20:21], v[64:65] op_sel_hi:[1,0]
	v_pk_mul_f32 v[18:19], v[18:19], v[64:65] op_sel_hi:[1,0]
	v_pk_mul_f32 v[16:17], v[16:17], v[64:65] op_sel_hi:[1,0]
	v_pk_mul_f32 v[14:15], v[14:15], v[64:65] op_sel_hi:[1,0]
	v_pk_mul_f32 v[12:13], v[12:13], v[64:65] op_sel_hi:[1,0]
	v_pk_mul_f32 v[10:11], v[10:11], v[64:65] op_sel_hi:[1,0]
	v_pk_mul_f32 v[8:9], v[8:9], v[64:65] op_sel_hi:[1,0]
	v_pk_mul_f32 v[6:7], v[6:7], v[64:65] op_sel_hi:[1,0]
	v_pk_mul_f32 v[4:5], v[4:5], v[64:65] op_sel_hi:[1,0]
	v_pk_mul_f32 v[2:3], v[2:3], v[64:65] op_sel_hi:[1,0]
	v_pk_mul_f32 v[0:1], v[0:1], v[64:65] op_sel_hi:[1,0]
	v_add_f32_e32 v65, 0, v32
	v_exp_f32_e32 v50, v50
	v_add_f32_e32 v65, v48, v65
	v_exp_f32_e32 v35, v35
	v_add_f32_e32 v65, v33, v65
	v_exp_f32_e32 v51, v51
	v_add_f32_e32 v65, v49, v65
	v_exp_f32_e32 v36, v36
	v_add_f32_e32 v65, v34, v65
	v_exp_f32_e32 v52, v52
	v_add_f32_e32 v65, v50, v65
	v_exp_f32_e32 v37, v37
	v_add_f32_e32 v65, v35, v65
	v_exp_f32_e32 v53, v53
	v_add_f32_e32 v65, v51, v65
	v_exp_f32_e32 v38, v38
	v_add_f32_e32 v65, v36, v65
	v_exp_f32_e32 v54, v54
	v_add_f32_e32 v65, v52, v65
	v_exp_f32_e32 v39, v39
	v_add_f32_e32 v65, v37, v65
	v_add_f32_e32 v65, v53, v65
	v_add_f32_e32 v65, v38, v65
	v_add_f32_e32 v65, v54, v65
	v_cvt_pk_bf16_f32 v32, v32, v33
	v_cvt_pk_bf16_f32 v33, v34, v35
	v_cvt_pk_bf16_f32 v34, v36, v37
	v_cvt_pk_bf16_f32 v35, v38, v39
	v_lshl_add_u32 v38, v111, 1, v80
	v_add_f32_e32 v65, v39, v65
	ds_read_b64 v[36:37], v66 offset:27648
	ds_read_b64 v[38:39], v38 offset:27648
	s_waitcnt lgkmcnt(0)
	v_mfma_f32_32x32x16_bf16 v[16:31], v[36:39], v[32:35], v[16:31]
	v_lshl_add_u32 v36, v110, 1, v67
	v_lshl_add_u32 v38, v109, 1, v67
	ds_read_b64 v[36:37], v36 offset:27648
	ds_read_b64 v[38:39], v38 offset:27648
	v_exp_f32_e32 v40, v40
	v_exp_f32_e32 v41, v41
	v_exp_f32_e32 v42, v42
	s_waitcnt lgkmcnt(0)
	v_mfma_f32_32x32x16_bf16 v[0:15], v[36:39], v[32:35], v[0:15]
	v_lshl_add_u32 v36, v108, 1, v80
	v_lshl_add_u32 v38, v107, 1, v80
	v_exp_f32_e32 v43, v43
	v_exp_f32_e32 v44, v44
	v_exp_f32_e32 v45, v45
	v_exp_f32_e32 v46, v46
	v_exp_f32_e32 v47, v47
	v_cvt_pk_bf16_f32 v32, v40, v41
	v_cvt_pk_bf16_f32 v33, v42, v43
	v_cvt_pk_bf16_f32 v34, v44, v45
	v_cvt_pk_bf16_f32 v35, v46, v47
	ds_read_b64 v[36:37], v36 offset:27648
	ds_read_b64 v[38:39], v38 offset:27648
	s_waitcnt lgkmcnt(0)
	v_mfma_f32_32x32x16_bf16 v[16:31], v[36:39], v[32:35], v[16:31]
	v_lshl_add_u32 v36, v106, 1, v67
	v_lshl_add_u32 v38, v105, 1, v67
	ds_read_b64 v[36:37], v36 offset:27648
	ds_read_b64 v[38:39], v38 offset:27648
	v_exp_f32_e32 v55, v55
	v_exp_f32_e32 v56, v56
	v_exp_f32_e32 v57, v57
	s_waitcnt lgkmcnt(0)
	v_mfma_f32_32x32x16_bf16 v[0:15], v[36:39], v[32:35], v[0:15]
	v_lshl_add_u32 v38, v104, 1, v80
	v_cvt_pk_bf16_f32 v32, v48, v49
	v_cvt_pk_bf16_f32 v33, v50, v51
	v_cvt_pk_bf16_f32 v34, v52, v53
	v_cvt_pk_bf16_f32 v35, v54, v55
	ds_read_b64 v[36:37], v66 offset:27712
	ds_read_b64 v[38:39], v38 offset:27648
	s_waitcnt lgkmcnt(0)
; #define MFMA32(a, b, c) __builtin_amdgcn_mfma_f32_32x32x16_bf16((a), (b), (c), 0, 0, 0)
; DI unsigned pack2(float a, float b) { unsigned r; asm volatile("v_cvt_pk_bf16_f32 %0, %1, %2" : "=v"(r) : "v"(a), "v"(b)); return r; }
; template <int D>
; DI void attn_pass(const bfr* __restrict__ P, int b, int tq_wave, int qcol, int kcol, int vcol, int key0, int nkt, char* smem, f32x16 (&o)[2]) {
;     ...
; #pragma unroll
;     for (int t2 = 0; t2 < 2; ++t2)
; #pragma unroll
;       for (int j = 0; j < 2; ++j) {
;         unsigned pk[4];
; #pragma unroll
;         for (int e = 0; e < 4; ++e) pk[e] = pack2(s[t2][8 * j + 2 * e], s[t2][8 * j + 2 * e + 1]);
;         u32x4 pku = {pk[0], pk[1], pk[2], pk[3]};
;         bf16x8 pf = __builtin_bit_cast(bf16x8, pku);
; #pragma unroll
;         for (int dt = 0; dt < 2; ++dt) {
;           const int vsw = (((dt * 32 + r) >> 3) & 7) << 3;
;           const bfr* vrow = sV + (dt * 32 + r) * 72;
;           s16x4 lo = *(const s16x4*)(vrow + ((t2 * 32 + 16 * j + 4 * h) ^ vsw));
;           s16x4 hi = *(const s16x4*)(vrow + ((t2 * 32 + 16 * j + 4 * h + 8) ^ vsw));
;           bf16x8 vf = __builtin_shufflevector(lo, hi, 0, 1, 2, 3, 4, 5, 6, 7);
;           accO[dt] = MFMA32(vf, pf, accO[dt]);
;         }
;       }
;   }
;   lsum += __shfl_xor(lsum, 32);
;   float inv = 1.f / lsum;
; #pragma unroll
;   for (int i = 0; i < 16; ++i) { o[0][i] = accO[0][i] * inv; o[1][i] = accO[1][i] * inv; }
; DI void store_o(bfr* O, int m, int colbase, int h, const f32x16 (&o)[2]) {
; #pragma unroll
;   for (int dt = 0; dt < 2; ++dt)
; #pragma unroll
;     for (int g4 = 0; g4 < 4; ++g4) {
;       int dv = dt * 32 + 8 * g4 + 4 * h;
;       uint2 pk; pk.x = pack2(o[dt][4 * g4], o[dt][4 * g4 + 1]); pk.y = pack2(o[dt][4 * g4 + 2], o[dt][4 * g4 + 3]);
;       *(uint2*)(O + (size_t)m * DM + colbase + dv) = pk;
;     }
; }
	v_mfma_f32_32x32x16_bf16 v[16:31], v[36:39], v[32:35], v[16:31]
	v_lshl_add_u32 v36, v103, 1, v67
	v_lshl_add_u32 v38, v102, 1, v67
	ds_read_b64 v[36:37], v36 offset:27648
	ds_read_b64 v[38:39], v38 offset:27648
	v_exp_f32_e32 v58, v58
	v_exp_f32_e32 v59, v59
	v_exp_f32_e32 v60, v60
	s_waitcnt lgkmcnt(0)
	v_mfma_f32_32x32x16_bf16 v[0:15], v[36:39], v[32:35], v[0:15]
	v_lshl_add_u32 v36, v100, 1, v80
	v_lshl_add_u32 v38, v101, 1, v80
	v_exp_f32_e32 v61, v61
	v_exp_f32_e32 v62, v62
	v_exp_f32_e32 v63, v63
	v_cvt_pk_bf16_f32 v32, v56, v57
	v_cvt_pk_bf16_f32 v33, v58, v59
	v_cvt_pk_bf16_f32 v34, v60, v61
	v_cvt_pk_bf16_f32 v35, v62, v63
	ds_read_b64 v[36:37], v36 offset:27648
	ds_read_b64 v[38:39], v38 offset:27648
	v_add_f32_e32 v65, v55, v65
	v_add_f32_e32 v65, v40, v65
	v_add_f32_e32 v65, v56, v65
	v_add_f32_e32 v65, v41, v65
	v_add_f32_e32 v65, v57, v65
	v_add_f32_e32 v65, v42, v65
	v_add_f32_e32 v65, v58, v65
	v_add_f32_e32 v65, v43, v65
	v_add_f32_e32 v65, v59, v65
	s_waitcnt lgkmcnt(0)
	v_mfma_f32_32x32x16_bf16 v[16:31], v[36:39], v[32:35], v[16:31]
	v_lshl_add_u32 v36, v99, 1, v67
	v_lshl_add_u32 v38, v98, 1, v67
	v_add_f32_e32 v65, v44, v65
	ds_read_b64 v[36:37], v36 offset:27648
	ds_read_b64 v[38:39], v38 offset:27648
	v_add_f32_e32 v65, v60, v65
	v_add_f32_e32 v65, v45, v65
	v_add_f32_e32 v65, v61, v65
	v_add_f32_e32 v65, v46, v65
	v_add_f32_e32 v65, v62, v65
	v_add_f32_e32 v65, v47, v65
	v_add_f32_e32 v65, v63, v65
	v_fmac_f32_e32 v65, v113, v64
	s_waitcnt lgkmcnt(0)
	v_mfma_f32_32x32x16_bf16 v[0:15], v[36:39], v[32:35], v[0:15]
	ds_bpermute_b32 v32, v91, v65
	s_load_dwordx4 s[12:15], s[0:1], 0x100
	s_waitcnt lgkmcnt(0)
	v_add_f32_e32 v32, v65, v32
	v_div_scale_f32 v33, s[10:11], v32, v32, 1.0
	v_rcp_f32_e32 v34, v33
	s_mov_b64 s[10:11], 0x2b7c700
	v_fma_f32 v35, -v33, v34, 1.0
	v_fmac_f32_e32 v34, v35, v34
	v_div_scale_f32 v35, vcc, 1.0, v32, 1.0
	v_mul_f32_e32 v36, v35, v34
	v_fma_f32 v37, -v33, v36, v35
	v_fmac_f32_e32 v36, v37, v34
	v_fma_f32 v33, -v33, v36, v35
	v_div_fmas_f32 v33, v33, v34, v36
	v_div_fixup_f32 v32, v33, v32, 1.0
	v_mul_f32_e32 v33, v0, v32
	v_and_or_b32 v0, v89, 31, v97
	v_mul_f32_e32 v34, v1, v32
	v_ashrrev_i32_e32 v1, 31, v0
	v_lshlrev_b64 v[0:1], 11, v[0:1]
	v_mul_f32_e32 v37, v4, v32
	v_lshl_add_u64 v[0:1], s[14:15], 0, v[0:1]
	v_lshrrev_b32_e32 v4, 2, v89
	v_lshl_add_u64 v[0:1], v[0:1], 0, v[152:153]
	v_and_b32_e32 v152, 8, v4
	v_lshl_add_u64 v[0:1], v[0:1], 0, v[152:153]
	v_mul_f32_e32 v38, v5, v32
	v_lshl_add_u64 v[4:5], v[0:1], 0, s[10:11]
	s_mov_b32 s10, 0x2b7c000
	v_add_co_u32_e32 v0, vcc, s10, v0
	v_mul_f32_e32 v16, v16, v32
	s_nop 0
	v_addc_co_u32_e32 v1, vcc, 0, v1, vcc
	v_mul_f32_e32 v17, v17, v32
	v_mul_f32_e32 v18, v18, v32
	v_mul_f32_e32 v35, v2, v32
	v_mul_f32_e32 v19, v19, v32
	v_mul_f32_e32 v36, v3, v32
	v_mul_f32_e32 v20, v20, v32
	v_mul_f32_e32 v21, v21, v32
	v_mul_f32_e32 v22, v22, v32
	v_mul_f32_e32 v23, v23, v32
	v_cvt_pk_bf16_f32 v2, v16, v17
	v_cvt_pk_bf16_f32 v3, v18, v19
	global_store_dwordx2 v[0:1], v[2:3], off offset:1792
	v_cvt_pk_bf16_f32 v0, v20, v21
	v_cvt_pk_bf16_f32 v1, v22, v23
	v_mul_f32_e32 v24, v24, v32
	v_mul_f32_e32 v25, v25, v32
	v_mul_f32_e32 v26, v26, v32
	v_mul_f32_e32 v27, v27, v32
	global_store_dwordx2 v[4:5], v[0:1], off offset:16
	v_cvt_pk_bf16_f32 v0, v24, v25
	v_cvt_pk_bf16_f32 v1, v26, v27
	v_mul_f32_e32 v28, v28, v32
	v_mul_f32_e32 v29, v29, v32
	v_mul_f32_e32 v30, v30, v32
	v_mul_f32_e32 v31, v31, v32
	global_store_dwordx2 v[4:5], v[0:1], off offset:32
	v_cvt_pk_bf16_f32 v0, v28, v29
	v_cvt_pk_bf16_f32 v1, v30, v31
	global_store_dwordx2 v[4:5], v[0:1], off offset:48
	v_cvt_pk_bf16_f32 v0, v33, v34
	v_cvt_pk_bf16_f32 v1, v35, v36
	v_mul_f32_e32 v6, v6, v32
	v_mul_f32_e32 v7, v7, v32
	global_store_dwordx2 v[4:5], v[0:1], off offset:64
	v_cvt_pk_bf16_f32 v0, v37, v38
	v_cvt_pk_bf16_f32 v1, v6, v7
	v_mul_f32_e32 v8, v8, v32
	v_mul_f32_e32 v9, v9, v32
	v_mul_f32_e32 v10, v10, v32
	v_mul_f32_e32 v11, v11, v32
	global_store_dwordx2 v[4:5], v[0:1], off offset:80
	v_cvt_pk_bf16_f32 v0, v8, v9
	v_cvt_pk_bf16_f32 v1, v10, v11
	v_mul_f32_e32 v12, v12, v32
	v_mul_f32_e32 v13, v13, v32
	v_mul_f32_e32 v14, v14, v32
	v_mul_f32_e32 v15, v15, v32
	global_store_dwordx2 v[4:5], v[0:1], off offset:96
	v_cvt_pk_bf16_f32 v0, v12, v13
	v_cvt_pk_bf16_f32 v1, v14, v15
	global_store_dwordx2 v[4:5], v[0:1], off offset:112

; DI void attn_pass_da(const bfr* __restrict__ P, int b, int tq_wave, int qcol, int kcol, int vcol, int key0, int nkt, char* smem, f32x16 (&o0)[2], f32x16 (&o1)[2]) {
;     ...
;   for (int kt = 0; kt < nkt; ++kt) {
;     bfr* sK = sbase + (kt & 1) * 9216;
;     bfr* sV = sK + 64 * 72;
;     { int c = gt, row = c >> 3, kc = c & 7; *(u32x4*)(sK + row * KP + kc * 8) = kreg[0]; }
;     for (int i = 0; i < 1; ++i) {
;       int c = gt, row = c >> 3, kc = c & 7;
;       unsigned wds[4] = {vreg[i].x, vreg[i].y, vreg[i].z, vreg[i].w};
; #pragma unroll
;       for (int e = 0; e < 4; ++e) {
;         sV[(kc * 8 + 2 * e) * 72 + (row ^ (kc << 3))] = (bfr)(wds[e] & 0xffffu);
;         sV[(kc * 8 + 2 * e + 1) * 72 + (row ^ (kc << 3))] = (bfr)(wds[e] >> 16);
;       }
;     }
;     __syncthreads();
;     if (kt + 1 < nkt) {
;       const bfr* Pn = Pb + (size_t)(kt + 1) * 64 * PW;
;       { int c = gt, row = c >> 3, kc = c & 7; kreg[0] = *(const u32x4*)(Pn + (size_t)row * PW + kcol + kc * 8); vreg[0] = *(const u32x4*)(Pn + (size_t)row * PW + vcol + kc * 8); }
;     }
;     f32x16 s0[2], s1[2];
; #pragma unroll
;     for (int t2 = 0; t2 < 2; ++t2) {
; #pragma unroll
;       for (int i = 0; i < 16; ++i) { s0[t2][i] = 0.f; s1[t2][i] = 0.f; }
; #pragma unroll
;       for (int ks = 0; ks < 2; ++ks) {
;         bf16x8 a0 = *(const bf16x8*)(sK + (t2 * 32 + r) * KP + ks * 16 + h * 8);
;         bf16x8 a1 = *(const bf16x8*)(sK + (t2 * 32 + r) * KP + 32 + ks * 16 + h * 8);
;         s0[t2] = MFMA32(a0, qf[ks], s0[t2]);
;         s1[t2] = MFMA32(a1, qf[2 + ks], s1[t2]);
;       }
;     }
;     float mx0 = s0[0][0], mx1 = s1[0][0];
; #pragma unroll
;     for (int i = 0; i < 16; ++i) { mx0 = fmaxf(mx0, fmaxf(s0[0][i], s0[1][i])); mx1 = fmaxf(mx1, fmaxf(s1[0][i], s1[1][i])); }
;     mx0 = fmaxf(mx0, __shfl_xor(mx0, 32)); mx1 = fmaxf(mx1, __shfl_xor(mx1, 32));
;     const float mn0 = fmaxf(m0, mx0), mn1 = fmaxf(m1, mx1);
;     const float al0 = __builtin_amdgcn_exp2f(m0 - mn0), al1 = __builtin_amdgcn_exp2f(m1 - mn1);
;     m0 = mn0; m1 = mn1;
;     float ps0 = 0.f, ps1 = 0.f;
; #pragma unroll
;     for (int i = 0; i < 16; ++i) {
;       s0[0][i] = __builtin_amdgcn_exp2f(s0[0][i] - mn0); ps0 += s0[0][i];
;       s0[1][i] = __builtin_amdgcn_exp2f(s0[1][i] - mn0); ps0 += s0[1][i];
;       s1[0][i] = __builtin_amdgcn_exp2f(s1[0][i] - mn1); ps1 += s1[0][i];
.LBB0_408:
	s_bitcmp1_b32 s14, 0
	s_cselect_b32 s15, 0x4800, 0
	s_add_i32 s15, s15, 0
	v_add3_u32 v64, s15, v206, v152
	v_add_u32_e32 v194, s15, v205
	s_waitcnt vmcnt(1)
	ds_write_b128 v64, v[148:151]
	v_add3_u32 v64, s15, v207, v208
	v_add3_u32 v65, s15, v208, v207
	v_add_u32_e32 v100, v194, v204
	s_waitcnt vmcnt(0)
	ds_write_b16 v64, v144 offset:9216
	ds_write_b16_d16_hi v65, v144 offset:9360
	ds_write_b16 v64, v145 offset:9504
	ds_write_b16_d16_hi v65, v145 offset:9648
	ds_write_b16 v64, v146 offset:9792
	ds_write_b16_d16_hi v65, v146 offset:9936
	ds_write_b16 v64, v147 offset:10080
	ds_write_b16_d16_hi v65, v147 offset:10224
	s_waitcnt lgkmcnt(0)
	s_barrier
	global_load_dwordx4 v[148:151], v[158:159], off
	global_load_dwordx4 v[144:147], v[158:159], off offset:512
	ds_read_b128 v[64:67], v100 offset:64
	ds_read_b128 v[68:71], v100
	ds_read_b128 v[96:99], v100 offset:32
	ds_read_b128 v[100:103], v100 offset:96
	s_waitcnt lgkmcnt(2)
	v_mfma_f32_32x32x16_bf16 v[80:95], v[68:71], v[140:143], 0
	v_add_u32_e32 v195, s15, v211
	v_add_u32_e32 v192, v195, v204
	v_mov_b32_e32 v160, v209
	v_mov_b32_e32 v161, v210
	s_add_i32 s14, s14, 1
	v_lshl_add_u64 v[158:159], v[158:159], 0, s[16:17]
	s_cmp_lg_u32 s14, 3
	v_mfma_f32_32x32x16_bf16 v[64:79], v[64:67], v[136:139], 0
	s_waitcnt lgkmcnt(1)
	v_mfma_f32_32x32x16_bf16 v[80:95], v[96:99], v[132:135], v[80:95]
	s_waitcnt lgkmcnt(0)
	v_mfma_f32_32x32x16_bf16 v[64:79], v[100:103], v[128:131], v[64:79]
	ds_read_b128 v[96:99], v192 offset:64
	ds_read_b128 v[100:103], v192
	ds_read_b128 v[212:215], v192 offset:32
	ds_read_b128 v[216:219], v192 offset:96
	s_nop 5
	v_max3_f32 v209, v80, v81, v82
	v_max3_f32 v209, v209, v83, v84
	v_max3_f32 v193, v64, v65, v66
	s_waitcnt lgkmcnt(2)
	v_mfma_f32_32x32x16_bf16 v[112:127], v[100:103], v[140:143], 0
	v_mfma_f32_32x32x16_bf16 v[96:111], v[96:99], v[136:139], 0
	s_waitcnt lgkmcnt(1)
	v_mfma_f32_32x32x16_bf16 v[112:127], v[212:215], v[132:135], v[112:127]
	v_max3_f32 v193, v193, v67, v68
	v_max3_f32 v209, v209, v85, v86
	s_waitcnt lgkmcnt(0)
	v_mfma_f32_32x32x16_bf16 v[96:111], v[216:219], v[128:131], v[96:111]
	v_max3_f32 v193, v193, v69, v70
	v_max3_f32 v209, v209, v87, v88
	v_max3_f32 v193, v193, v71, v72
	v_max3_f32 v209, v209, v89, v90
	v_max3_f32 v193, v193, v73, v74
	v_max3_f32 v209, v209, v91, v92
	v_max3_f32 v193, v193, v75, v76
	v_max3_f32 v209, v209, v93, v94
	v_max3_f32 v193, v193, v77, v78
	v_max3_f32 v209, v209, v95, v112
	v_max3_f32 v209, v209, v113, v114
	v_max3_f32 v209, v209, v115, v116
	v_max3_f32 v209, v209, v117, v118
	v_max3_f32 v209, v209, v119, v120
	v_max3_f32 v209, v209, v121, v122
	v_max3_f32 v209, v209, v123, v124
	v_max3_f32 v209, v209, v125, v126
	v_max_f32_e32 v192, v209, v127
	v_max3_f32 v193, v193, v79, v96
	v_max3_f32 v193, v193, v97, v98
	v_max3_f32 v193, v193, v99, v100
	v_max3_f32 v193, v193, v101, v102
	v_max3_f32 v193, v193, v103, v104
	v_max3_f32 v193, v193, v105, v106
	v_max3_f32 v193, v193, v107, v108
	v_max3_f32 v193, v193, v109, v110
	v_max_f32_e32 v193, v193, v111
	v_mov_b32_e32 v210, v193
	v_mov_b32_e32 v209, v192
	s_nop 1
	v_permlane32_swap_b32_e32 v193, v210
	v_permlane32_swap_b32_e32 v192, v209
	s_waitcnt lgkmcnt(1)
	v_max3_f32 v210, v161, v193, v210
	s_waitcnt lgkmcnt(0)
	v_max3_f32 v209, v160, v192, v209
	v_pk_add_f32 v[64:65], v[64:65], v[210:211] op_sel_hi:[1,0] neg_lo:[0,1] neg_hi:[0,1]
	v_pk_add_f32 v[80:81], v[80:81], v[208:209] op_sel:[0,1] op_sel_hi:[1,1] neg_lo:[0,1] neg_hi:[0,1]
	v_exp_f32_e32 v193, v64
	v_pk_add_f32 v[96:97], v[96:97], v[210:211] op_sel_hi:[1,0] neg_lo:[0,1] neg_hi:[0,1]
	v_exp_f32_e32 v192, v80
	v_pk_add_f32 v[112:113], v[112:113], v[208:209] op_sel:[0,1] op_sel_hi:[1,1] neg_lo:[0,1] neg_hi:[0,1]
	v_exp_f32_e32 v213, v96
	v_exp_f32_e32 v212, v112
	v_exp_f32_e32 v80, v81
	v_exp_f32_e32 v96, v113
	v_exp_f32_e32 v81, v65
	v_exp_f32_e32 v97, v97
	v_pk_add_f32 v[82:83], v[82:83], v[208:209] op_sel:[0,1] op_sel_hi:[1,1] neg_lo:[0,1] neg_hi:[0,1]
	v_exp_f32_e32 v112, v82
	v_pk_add_f32 v[114:115], v[114:115], v[208:209] op_sel:[0,1] op_sel_hi:[1,1] neg_lo:[0,1] neg_hi:[0,1]
	v_exp_f32_e32 v214, v114
	v_pk_add_f32 v[66:67], v[66:67], v[210:211] op_sel_hi:[1,0] neg_lo:[0,1] neg_hi:[0,1]
	v_exp_f32_e32 v113, v66
	v_pk_add_f32 v[98:99], v[98:99], v[210:211] op_sel_hi:[1,0] neg_lo:[0,1] neg_hi:[0,1]
	v_exp_f32_e32 v215, v98
	v_exp_f32_e32 v82, v83
	v_exp_f32_e32 v98, v115
	v_exp_f32_e32 v83, v67
	v_exp_f32_e32 v99, v99
	v_pk_add_f32 v[84:85], v[84:85], v[208:209] op_sel:[0,1] op_sel_hi:[1,1] neg_lo:[0,1] neg_hi:[0,1]
	v_exp_f32_e32 v114, v84
	v_pk_add_f32 v[116:117], v[116:117], v[208:209] op_sel:[0,1] op_sel_hi:[1,1] neg_lo:[0,1] neg_hi:[0,1]
	v_exp_f32_e32 v216, v116
	v_pk_add_f32 v[68:69], v[68:69], v[210:211] op_sel_hi:[1,0] neg_lo:[0,1] neg_hi:[0,1]
	v_exp_f32_e32 v115, v68
	v_pk_add_f32 v[100:101], v[100:101], v[210:211] op_sel_hi:[1,0] neg_lo:[0,1] neg_hi:[0,1]
	v_exp_f32_e32 v217, v100
	v_exp_f32_e32 v84, v85
	v_exp_f32_e32 v100, v117
	v_exp_f32_e32 v85, v69
	v_exp_f32_e32 v101, v101
	v_pk_add_f32 v[86:87], v[86:87], v[208:209] op_sel:[0,1] op_sel_hi:[1,1] neg_lo:[0,1] neg_hi:[0,1]
	v_exp_f32_e32 v116, v86
	v_pk_add_f32 v[118:119], v[118:119], v[208:209] op_sel:[0,1] op_sel_hi:[1,1] neg_lo:[0,1] neg_hi:[0,1]
	v_exp_f32_e32 v218, v118
	v_pk_add_f32 v[70:71], v[70:71], v[210:211] op_sel_hi:[1,0] neg_lo:[0,1] neg_hi:[0,1]
	v_exp_f32_e32 v117, v70
	v_pk_add_f32 v[102:103], v[102:103], v[210:211] op_sel_hi:[1,0] neg_lo:[0,1] neg_hi:[0,1]
	v_exp_f32_e32 v219, v102
	v_exp_f32_e32 v70, v87
	v_exp_f32_e32 v86, v119
	v_exp_f32_e32 v71, v71
	v_exp_f32_e32 v87, v103
; DI void attn_pass_da(const bfr* __restrict__ P, int b, int tq_wave, int qcol, int kcol, int vcol, int key0, int nkt, char* smem, f32x16 (&o0)[2], f32x16 (&o1)[2]) {
;     ...
; #pragma unroll
;     for (int i = 0; i < 16; ++i) {
;       s0[0][i] = __builtin_amdgcn_exp2f(s0[0][i] - mn0); ps0 += s0[0][i];
;       s0[1][i] = __builtin_amdgcn_exp2f(s0[1][i] - mn0); ps0 += s0[1][i];
;       s1[0][i] = __builtin_amdgcn_exp2f(s1[0][i] - mn1); ps1 += s1[0][i];
;       s1[1][i] = __builtin_amdgcn_exp2f(s1[1][i] - mn1); ps1 += s1[1][i];
;     }
;     l0 = l0 * al0 + ps0; l1 = l1 * al1 + ps1;
; #pragma unroll
;     for (int i = 0; i < 16; ++i) { acc0[0][i] *= al0; acc0[1][i] *= al0; acc1[0][i] *= al1; acc1[1][i] *= al1; }
	v_pk_add_f32 v[88:89], v[88:89], v[208:209] op_sel:[0,1] op_sel_hi:[1,1] neg_lo:[0,1] neg_hi:[0,1]
	v_exp_f32_e32 v102, v88
	v_pk_add_f32 v[120:121], v[120:121], v[208:209] op_sel:[0,1] op_sel_hi:[1,1] neg_lo:[0,1] neg_hi:[0,1]
	v_exp_f32_e32 v118, v120
	v_pk_add_f32 v[72:73], v[72:73], v[210:211] op_sel_hi:[1,0] neg_lo:[0,1] neg_hi:[0,1]
	v_exp_f32_e32 v103, v72
	v_pk_add_f32 v[104:105], v[104:105], v[210:211] op_sel_hi:[1,0] neg_lo:[0,1] neg_hi:[0,1]
	v_exp_f32_e32 v119, v104
	v_exp_f32_e32 v88, v89
	v_exp_f32_e32 v104, v121
	v_exp_f32_e32 v89, v73
	v_exp_f32_e32 v105, v105
	v_pk_add_f32 v[90:91], v[90:91], v[208:209] op_sel:[0,1] op_sel_hi:[1,1] neg_lo:[0,1] neg_hi:[0,1]
	v_exp_f32_e32 v120, v90
	v_pk_add_f32 v[122:123], v[122:123], v[208:209] op_sel:[0,1] op_sel_hi:[1,1] neg_lo:[0,1] neg_hi:[0,1]
	v_exp_f32_e32 v220, v122
	v_pk_add_f32 v[74:75], v[74:75], v[210:211] op_sel_hi:[1,0] neg_lo:[0,1] neg_hi:[0,1]
	v_exp_f32_e32 v121, v74
	v_pk_add_f32 v[106:107], v[106:107], v[210:211] op_sel_hi:[1,0] neg_lo:[0,1] neg_hi:[0,1]
	v_exp_f32_e32 v221, v106
	v_exp_f32_e32 v90, v91
	v_exp_f32_e32 v106, v123
	v_exp_f32_e32 v91, v75
	v_exp_f32_e32 v107, v107
	v_pk_add_f32 v[92:93], v[92:93], v[208:209] op_sel:[0,1] op_sel_hi:[1,1] neg_lo:[0,1] neg_hi:[0,1]
	v_exp_f32_e32 v122, v92
	v_pk_add_f32 v[124:125], v[124:125], v[208:209] op_sel:[0,1] op_sel_hi:[1,1] neg_lo:[0,1] neg_hi:[0,1]
	v_exp_f32_e32 v222, v124
	v_pk_add_f32 v[76:77], v[76:77], v[210:211] op_sel_hi:[1,0] neg_lo:[0,1] neg_hi:[0,1]
	v_exp_f32_e32 v123, v76
	v_pk_add_f32 v[108:109], v[108:109], v[210:211] op_sel_hi:[1,0] neg_lo:[0,1] neg_hi:[0,1]
	v_exp_f32_e32 v223, v108
	v_exp_f32_e32 v92, v93
	v_exp_f32_e32 v108, v125
	v_exp_f32_e32 v93, v77
	v_exp_f32_e32 v109, v109
	v_pk_add_f32 v[94:95], v[94:95], v[208:209] op_sel:[0,1] op_sel_hi:[1,1] neg_lo:[0,1] neg_hi:[0,1]
	v_exp_f32_e32 v124, v94
	v_pk_add_f32 v[126:127], v[126:127], v[208:209] op_sel:[0,1] op_sel_hi:[1,1] neg_lo:[0,1] neg_hi:[0,1]
	v_exp_f32_e32 v224, v126
	v_pk_add_f32 v[78:79], v[78:79], v[210:211] op_sel_hi:[1,0] neg_lo:[0,1] neg_hi:[0,1]
	v_exp_f32_e32 v125, v78
	v_pk_add_f32 v[110:111], v[110:111], v[210:211] op_sel_hi:[1,0] neg_lo:[0,1] neg_hi:[0,1]
	v_exp_f32_e32 v225, v110
	v_exp_f32_e32 v94, v95
	v_exp_f32_e32 v110, v127
	v_exp_f32_e32 v95, v79
	v_exp_f32_e32 v111, v111
	v_pk_add_f32 v[64:65], v[192:193], 0 op_sel_hi:[1,0]
	v_sub_f32_e32 v161, v161, v210
	v_pk_add_f32 v[64:65], v[212:213], v[64:65]
	v_exp_f32_e32 v161, v161
	v_pk_add_f32 v[64:65], v[80:81], v[64:65]
	v_lshl_add_u32 v74, v180, 1, v194
	v_pk_add_f32 v[64:65], v[96:97], v[64:65]
	v_lshl_add_u32 v76, v179, 1, v195
	v_pk_add_f32 v[64:65], v[112:113], v[64:65]
	v_lshl_add_u32 v78, v178, 1, v195
	v_pk_add_f32 v[64:65], v[214:215], v[64:65]
	v_sub_f32_e32 v160, v160, v209
	v_pk_add_f32 v[64:65], v[82:83], v[64:65]
	v_exp_f32_e32 v160, v160
	v_pk_add_f32 v[64:65], v[98:99], v[64:65]
	v_pk_mul_f32 v[62:63], v[62:63], v[160:161] op_sel_hi:[1,0]
	v_pk_add_f32 v[64:65], v[114:115], v[64:65]
	v_pk_mul_f32 v[60:61], v[60:61], v[160:161] op_sel_hi:[1,0]
	v_pk_add_f32 v[64:65], v[216:217], v[64:65]
	v_pk_mul_f32 v[58:59], v[58:59], v[160:161] op_sel_hi:[1,0]
	v_pk_add_f32 v[64:65], v[84:85], v[64:65]
	v_pk_mul_f32 v[56:57], v[56:57], v[160:161] op_sel_hi:[1,0]
	v_pk_add_f32 v[64:65], v[100:101], v[64:65]
	v_pk_mul_f32 v[54:55], v[54:55], v[160:161] op_sel_hi:[1,0]
	v_pk_add_f32 v[64:65], v[116:117], v[64:65]
	v_pk_mul_f32 v[52:53], v[52:53], v[160:161] op_sel_hi:[1,0]
	v_pk_add_f32 v[64:65], v[218:219], v[64:65]
	v_pk_mul_f32 v[50:51], v[50:51], v[160:161] op_sel_hi:[1,0]
	v_pk_add_f32 v[64:65], v[70:71], v[64:65]
	v_pk_mul_f32 v[48:49], v[48:49], v[160:161] op_sel_hi:[1,0]
	v_pk_add_f32 v[64:65], v[86:87], v[64:65]
	v_pk_mul_f32 v[30:31], v[30:31], v[160:161] op_sel_hi:[1,0]
	v_pk_add_f32 v[64:65], v[102:103], v[64:65]
	v_pk_mul_f32 v[28:29], v[28:29], v[160:161] op_sel_hi:[1,0]
	v_pk_add_f32 v[64:65], v[118:119], v[64:65]
	v_pk_mul_f32 v[26:27], v[26:27], v[160:161] op_sel_hi:[1,0]
	v_pk_add_f32 v[64:65], v[88:89], v[64:65]
	v_pk_mul_f32 v[24:25], v[24:25], v[160:161] op_sel_hi:[1,0]
	v_pk_add_f32 v[64:65], v[104:105], v[64:65]
	v_pk_mul_f32 v[22:23], v[22:23], v[160:161] op_sel_hi:[1,0]
	v_pk_add_f32 v[64:65], v[120:121], v[64:65]
	v_pk_mul_f32 v[20:21], v[20:21], v[160:161] op_sel_hi:[1,0]
	v_pk_add_f32 v[126:127], v[220:221], v[64:65]
	v_cvt_pk_bf16_f32 v64, v192, v80
	v_cvt_pk_bf16_f32 v65, v112, v82
	v_lshl_add_u32 v112, v181, 1, v194
	v_cvt_pk_bf16_f32 v66, v114, v84
	v_cvt_pk_bf16_f32 v67, v116, v70
	v_cvt_pk_bf16_f32 v68, v193, v81
	v_cvt_pk_bf16_f32 v69, v113, v83
	v_cvt_pk_bf16_f32 v70, v115, v85
	v_cvt_pk_bf16_f32 v71, v117, v71
	ds_read_b64 v[72:73], v112 offset:9216
	ds_read_b64 v[74:75], v74 offset:9216
	ds_read_b64 v[76:77], v76 offset:9216
	ds_read_b64 v[78:79], v78 offset:9216
	v_mov_b32_e32 v82, v161
	v_pk_mul_f32 v[46:47], v[46:47], v[82:83] op_sel_hi:[1,0]
	v_pk_mul_f32 v[44:45], v[44:45], v[82:83] op_sel_hi:[1,0]
	v_pk_mul_f32 v[42:43], v[42:43], v[82:83] op_sel_hi:[1,0]
	v_pk_mul_f32 v[40:41], v[40:41], v[82:83] op_sel_hi:[1,0]
	v_pk_mul_f32 v[38:39], v[38:39], v[82:83] op_sel_hi:[1,0]
	v_pk_mul_f32 v[36:37], v[36:37], v[82:83] op_sel_hi:[1,0]
	v_pk_mul_f32 v[34:35], v[34:35], v[82:83] op_sel_hi:[1,0]
	v_pk_mul_f32 v[32:33], v[32:33], v[82:83] op_sel_hi:[1,0]
	v_pk_mul_f32 v[14:15], v[14:15], v[82:83] op_sel_hi:[1,0]
	v_pk_mul_f32 v[12:13], v[12:13], v[82:83] op_sel_hi:[1,0]
	v_pk_mul_f32 v[10:11], v[10:11], v[82:83] op_sel_hi:[1,0]
	v_pk_mul_f32 v[8:9], v[8:9], v[82:83] op_sel_hi:[1,0]
	v_pk_mul_f32 v[6:7], v[6:7], v[82:83] op_sel_hi:[1,0]
	v_pk_mul_f32 v[4:5], v[4:5], v[82:83] op_sel_hi:[1,0]
	v_pk_mul_f32 v[2:3], v[2:3], v[82:83] op_sel_hi:[1,0]
	v_pk_mul_f32 v[0:1], v[0:1], v[82:83] op_sel_hi:[1,0]
	v_pk_add_f32 v[82:83], v[90:91], v[126:127]
	s_waitcnt lgkmcnt(2)
; DI int oidx(int i) { asm volatile("" : "+s"(i)); return i; }
; #define MFMA32(a, b, c) __builtin_amdgcn_mfma_f32_32x32x16_bf16((a), (b), (c), 0, 0, 0)
; DI unsigned pack2(float a, float b) { unsigned r; asm volatile("v_cvt_pk_bf16_f32 %0, %1, %2" : "=v"(r) : "v"(a), "v"(b)); return r; }
; DI void attn_pass_da(const bfr* __restrict__ P, int b, int tq_wave, int qcol, int kcol, int vcol, int key0, int nkt, char* smem, f32x16 (&o0)[2], f32x16 (&o1)[2]) {
;     ...
;     for (int t2 = 0; t2 < 2; ++t2)
; #pragma unroll
;       for (int j = 0; j < 2; ++j) {
;         u32x4 pk0, pk1;
;         pk0.x = pack2(s0[t2][8 * j + 0], s0[t2][8 * j + 1]); pk0.y = pack2(s0[t2][8 * j + 2], s0[t2][8 * j + 3]);
;         pk0.z = pack2(s0[t2][8 * j + 4], s0[t2][8 * j + 5]); pk0.w = pack2(s0[t2][8 * j + 6], s0[t2][8 * j + 7]);
;         pk1.x = pack2(s1[t2][8 * j + 0], s1[t2][8 * j + 1]); pk1.y = pack2(s1[t2][8 * j + 2], s1[t2][8 * j + 3]);
;         pk1.z = pack2(s1[t2][8 * j + 4], s1[t2][8 * j + 5]); pk1.w = pack2(s1[t2][8 * j + 6], s1[t2][8 * j + 7]);
;         const bf16x8 pf0 = __builtin_bit_cast(bf16x8, pk0), pf1 = __builtin_bit_cast(bf16x8, pk1);
; #pragma unroll
;         for (int dt = 0; dt < 2; ++dt) {
;           const int vsw = (((dt * 32 + r) >> 3) & 7) << 3;
;           const bfr* vrow = sV + (dt * 32 + r) * 72;
;           s16x4 lo = *(const s16x4*)(vrow + ((t2 * 32 + 16 * j + 4 * h) ^ vsw));
;           s16x4 hi = *(const s16x4*)(vrow + ((t2 * 32 + 16 * j + 4 * h + 8) ^ vsw));
;           bf16x8 vf = __builtin_shufflevector(lo, hi, 0, 1, 2, 3, 4, 5, 6, 7);
;           acc0[dt] = MFMA32(vf, pf0, acc0[dt]);
;           acc1[dt] = MFMA32(vf, pf1, acc1[dt]);
;         }
;       }
; DN void da_item(const Params& p, int l, int b, int hd, int tq0, int key0, int nkt, char* smem) {
;     ...
;   const float* lv = p.in[oidx(22)] + l * 128;
;   float d01 = (lane < 32) ? lv[lane] * lv[32 + lane] : 0.f;
;   float d23 = (lane < 32) ? lv[64 + lane] * lv[96 + lane] : 0.f;
;   d01 = wave_sum(d01); d23 = wave_sum(d23);
;   float lam_init = 0.8f - 0.6f * expf(-0.3f * (float)l);
;   float lam = expf(d01) - expf(d23) + lam_init;
	v_mfma_f32_32x32x16_bf16 v[48:63], v[72:75], v[64:67], v[48:63]
	v_add_f32_e64 v82, v106, v82
	v_add_f32_e64 v83, v107, v83
	v_cvt_pk_bf16_f32 v80, v102, v88
	v_lshl_add_u32 v88, v177, 1, v194
	v_add_f32_e64 v82, v122, v82
	v_add_f32_e64 v83, v123, v83
	v_pk_mul_f32 v[18:19], v[18:19], v[160:161] op_sel_hi:[1,0]
	v_pk_add_f32 v[82:83], v[222:223], v[82:83]
	v_pk_mul_f32 v[16:17], v[16:17], v[160:161] op_sel_hi:[1,0]
	v_pk_add_f32 v[82:83], v[92:93], v[82:83]
	v_mfma_f32_32x32x16_bf16 v[32:47], v[72:75], v[68:71], v[32:47]
	v_add_f32_e64 v82, v108, v82
	v_add_f32_e64 v83, v109, v83
	v_cvt_pk_bf16_f32 v81, v120, v90
	v_lshl_add_u32 v102, v176, 1, v194
	v_add_f32_e64 v82, v124, v82
	v_add_f32_e64 v83, v125, v83
	v_lshl_add_u32 v113, v175, 1, v195
	v_pk_add_f32 v[82:83], v[224:225], v[82:83]
	v_lshl_add_u32 v114, v174, 1, v195
	v_pk_add_f32 v[82:83], v[94:95], v[82:83]
	s_waitcnt lgkmcnt(0)
	v_mfma_f32_32x32x16_bf16 v[16:31], v[76:79], v[64:67], v[16:31]
	v_add_f32_e64 v84, v110, v82
	v_add_f32_e64 v85, v111, v83
	v_cvt_pk_bf16_f32 v82, v122, v92
	v_cvt_pk_bf16_f32 v83, v124, v94
	v_cvt_pk_bf16_f32 v64, v103, v89
	v_cvt_pk_bf16_f32 v65, v121, v91
	v_cvt_pk_bf16_f32 v66, v123, v93
	v_cvt_pk_bf16_f32 v67, v125, v95
	v_mfma_f32_32x32x16_bf16 v[0:15], v[76:79], v[68:71], v[0:15]
	ds_read_b64 v[68:69], v88 offset:9216
	ds_read_b64 v[70:71], v102 offset:9216
	v_lshl_add_u32 v115, v173, 1, v194
	v_lshl_add_u32 v116, v172, 1, v195
	v_lshl_add_u32 v117, v171, 1, v195
	v_lshl_add_u32 v120, v169, 1, v194
	v_lshl_add_u32 v192, v170, 1, v194
	v_lshl_add_u32 v193, v168, 1, v195
	s_waitcnt lgkmcnt(0)
	v_mfma_f32_32x32x16_bf16 v[48:63], v[68:71], v[80:83], v[48:63]
	v_lshl_add_u32 v194, v167, 1, v195
	v_fma_f32 v156, v156, v160, v84
	v_fma_f32 v157, v157, v161, v85
	v_mfma_f32_32x32x16_bf16 v[32:47], v[68:71], v[64:67], v[32:47]
	ds_read_b64 v[68:69], v113 offset:9216
	ds_read_b64 v[70:71], v114 offset:9216
	s_waitcnt lgkmcnt(0)
	v_mfma_f32_32x32x16_bf16 v[16:31], v[68:71], v[80:83], v[16:31]
	v_mfma_f32_32x32x16_bf16 v[0:15], v[68:71], v[64:67], v[0:15]
	v_cvt_pk_bf16_f32 v64, v212, v96
	v_cvt_pk_bf16_f32 v65, v214, v98
	v_cvt_pk_bf16_f32 v66, v216, v100
	v_cvt_pk_bf16_f32 v67, v218, v86
	v_cvt_pk_bf16_f32 v68, v213, v97
	v_cvt_pk_bf16_f32 v69, v215, v99
	v_cvt_pk_bf16_f32 v70, v217, v101
	v_cvt_pk_bf16_f32 v71, v219, v87
	ds_read_b64 v[72:73], v112 offset:9280
	ds_read_b64 v[74:75], v115 offset:9216
	s_waitcnt lgkmcnt(0)
	v_mfma_f32_32x32x16_bf16 v[48:63], v[72:75], v[64:67], v[48:63]
	v_mfma_f32_32x32x16_bf16 v[32:47], v[72:75], v[68:71], v[32:47]
	ds_read_b64 v[72:73], v116 offset:9216
	ds_read_b64 v[74:75], v117 offset:9216
	s_waitcnt lgkmcnt(0)
	v_mfma_f32_32x32x16_bf16 v[16:31], v[72:75], v[64:67], v[16:31]
	v_cvt_pk_bf16_f32 v64, v118, v104
	v_cvt_pk_bf16_f32 v65, v220, v106
	v_cvt_pk_bf16_f32 v66, v222, v108
	v_cvt_pk_bf16_f32 v67, v224, v110
	v_mfma_f32_32x32x16_bf16 v[0:15], v[72:75], v[68:71], v[0:15]
	v_cvt_pk_bf16_f32 v68, v119, v105
	v_cvt_pk_bf16_f32 v69, v221, v107
	v_cvt_pk_bf16_f32 v70, v223, v109
	v_cvt_pk_bf16_f32 v71, v225, v111
	ds_read_b64 v[72:73], v120 offset:9216
	ds_read_b64 v[74:75], v192 offset:9216
	s_waitcnt lgkmcnt(0)
	v_mfma_f32_32x32x16_bf16 v[48:63], v[72:75], v[64:67], v[48:63]
	v_mfma_f32_32x32x16_bf16 v[32:47], v[72:75], v[68:71], v[32:47]
	ds_read_b64 v[72:73], v193 offset:9216
	ds_read_b64 v[74:75], v194 offset:9216
	s_waitcnt lgkmcnt(0)
	v_mfma_f32_32x32x16_bf16 v[16:31], v[72:75], v[64:67], v[16:31]
	v_mfma_f32_32x32x16_bf16 v[0:15], v[72:75], v[68:71], v[0:15]
	s_cbranch_scc1 .LBB0_408
	v_add3_u32 v64, 0, v206, v152
	s_waitcnt vmcnt(1)
	ds_write_b128 v64, v[148:151] offset:18432
	v_add3_u32 v64, 0, v207, v208
	v_add3_u32 v65, 0, v208, v207
	s_waitcnt vmcnt(0)
	ds_write_b16 v64, v144 offset:27648
	ds_write_b16_d16_hi v65, v144 offset:27792
	ds_write_b16 v64, v145 offset:27936
	ds_write_b16_d16_hi v65, v145 offset:28080
	ds_write_b16 v64, v146 offset:28224
	ds_write_b16_d16_hi v65, v146 offset:28368
	ds_write_b16 v64, v147 offset:28512
	ds_write_b16_d16_hi v65, v147 offset:28656
	v_add_u32_e32 v144, 0, v205
	v_add_u32_e32 v102, v144, v204
	s_waitcnt lgkmcnt(0)
	s_barrier
	ds_read_b128 v[64:67], v102 offset:18432
	ds_read_b128 v[96:99], v102 offset:18464
	s_waitcnt lgkmcnt(1)
	v_mfma_f32_32x32x16_bf16 v[64:79], v[64:67], v[140:143], 0
	ds_read_b128 v[80:83], v102 offset:18496
	v_readlane_b32 s14, v203, 16
	v_readlane_b32 s15, v203, 48
	v_add_u32_e32 v145, 0x1200, v144
	v_mov_b32_e32 v100, s14
	v_mov_b32_e32 v101, s15
	v_pk_add_f32 v[100:101], s[12:13], v[100:101]
	s_mov_b32 s14, 0x3fb8aa3b
	v_add_f32_e32 v146, v100, v101
	v_mul_f32_e32 v104, 0x3fb8aa3b, v146
	v_fma_f32 v105, v146, s14, -v104
	v_rndne_f32_e32 v106, v104
	s_waitcnt lgkmcnt(1)
	v_mfma_f32_32x32x16_bf16 v[64:79], v[96:99], v[132:135], v[64:79]
	v_fmac_f32_e32 v105, 0x32a5705f, v146
	v_sub_f32_e32 v96, v104, v106
	v_add_u32_e32 v147, v145, v204
	v_add_f32_e32 v104, v96, v105
	ds_read_b128 v[96:99], v147 offset:18432
	ds_read_b128 v[100:103], v102 offset:18528
	ds_read_b128 v[112:115], v147 offset:18496
	s_waitcnt lgkmcnt(3)
	v_mfma_f32_32x32x16_bf16 v[80:95], v[80:83], v[136:139], 0
	v_readlane_b32 s12, v202, 16
	v_readlane_b32 s13, v202, 48
	s_mov_b32 s15, 0xc2ce8ed0
	v_mov_b32_e32 v116, s12
	v_mov_b32_e32 v117, s13
	v_pk_add_f32 v[116:117], s[10:11], v[116:117]
	v_cmp_ngt_f32_e32 vcc, s15, v146
	s_waitcnt lgkmcnt(1)
	v_mfma_f32_32x32x16_bf16 v[80:95], v[100:103], v[128:131], v[80:95]
	v_exp_f32_e32 v100, v104
	v_cvt_i32_f32_e32 v101, v106
	v_add_f32_e32 v149, v116, v117
	v_mul_f32_e32 v150, 0x3fb8aa3b, v149
	v_rndne_f32_e32 v151, v150
	v_ldexp_f32 v148, v100, v101
	s_mov_b32 s10, 0x42b17218
	s_waitcnt lgkmcnt(0)
; #define MFMA32(a, b, c) __builtin_amdgcn_mfma_f32_32x32x16_bf16((a), (b), (c), 0, 0, 0)
; DI void attn_pass_da(const bfr* __restrict__ P, int b, int tq_wave, int qcol, int kcol, int vcol, int key0, int nkt, char* smem, f32x16 (&o0)[2], f32x16 (&o1)[2]) {
;     ...
;     f32x16 s0[2], s1[2];
; #pragma unroll
;     for (int t2 = 0; t2 < 2; ++t2) {
; #pragma unroll
;       for (int i = 0; i < 16; ++i) { s0[t2][i] = 0.f; s1[t2][i] = 0.f; }
; #pragma unroll
;       for (int ks = 0; ks < 2; ++ks) {
;         bf16x8 a0 = *(const bf16x8*)(sK + (t2 * 32 + r) * KP + ks * 16 + h * 8);
;         bf16x8 a1 = *(const bf16x8*)(sK + (t2 * 32 + r) * KP + 32 + ks * 16 + h * 8);
;         s0[t2] = MFMA32(a0, qf[ks], s0[t2]);
;         s1[t2] = MFMA32(a1, qf[2 + ks], s1[t2]);
;       }
;     }
;     float mx0 = s0[0][0], mx1 = s1[0][0];
; #pragma unroll
;     for (int i = 0; i < 16; ++i) { mx0 = fmaxf(mx0, fmaxf(s0[0][i], s0[1][i])); mx1 = fmaxf(mx1, fmaxf(s1[0][i], s1[1][i])); }
;     mx0 = fmaxf(mx0, __shfl_xor(mx0, 32)); mx1 = fmaxf(mx1, __shfl_xor(mx1, 32));
	v_mfma_f32_32x32x16_bf16 v[112:127], v[112:115], v[136:139], 0
	v_fma_f32 v136, v149, s14, -v150
	v_fmac_f32_e32 v136, 0x32a5705f, v149
	v_sub_f32_e32 v137, v150, v151
	v_add_f32_e32 v136, v137, v136
	v_exp_f32_e32 v150, v136
	ds_read_b128 v[136:139], v147 offset:18528
	v_readlane_b32 s12, v253, 28
	v_mfma_f32_32x32x16_bf16 v[96:111], v[96:99], v[140:143], 0
	ds_read_b128 v[140:143], v147 offset:18464
	v_readlane_b32 s13, v253, 29
	s_waitcnt lgkmcnt(0)
	v_mfma_f32_32x32x16_bf16 v[96:111], v[140:143], v[132:135], v[96:111]
	v_max_f32_e32 v134, v82, v82
	v_max_f32_e32 v135, v67, v67
	v_cvt_i32_f32_e32 v132, v151
	v_cndmask_b32_e32 v133, 0, v148, vcc
	v_cmp_nlt_f32_e32 vcc, s10, v146
	v_ldexp_f32 v132, v150, v132
	v_mfma_f32_32x32x16_bf16 v[112:127], v[136:139], v[128:131], v[112:127]
	s_nop 4
	v_max_f32_e32 v128, v97, v97
	v_max_f32_e32 v129, v65, v65
	v_max_f32_e32 v128, v129, v128
	v_max_f32_e32 v130, v81, v81
	v_max_f32_e32 v131, v66, v66
	v_max3_f32 v128, v64, v96, v128
	v_cndmask_b32_e32 v133, v201, v133, vcc
	v_max_f32_e32 v129, v113, v113
	v_max_f32_e32 v129, v130, v129
	v_max_f32_e32 v130, v98, v98
	v_max_f32_e32 v130, v131, v130
	v_max_f32_e32 v131, v114, v114
	v_max_f32_e32 v131, v134, v131
	v_max_f32_e32 v134, v99, v99
	v_max_f32_e32 v134, v135, v134
	v_max3_f32 v128, v128, v130, v134
	v_max_f32_e32 v130, v115, v115
	v_max_f32_e32 v134, v83, v83
	v_max3_f32 v129, v80, v112, v129
	v_max_f32_e32 v130, v134, v130
	v_max3_f32 v129, v129, v131, v130
	v_max_f32_e32 v130, v100, v100
	v_max_f32_e32 v131, v68, v68
	v_max_f32_e32 v130, v131, v130
	v_max_f32_e32 v131, v116, v116
	v_max_f32_e32 v134, v84, v84
	v_max_f32_e32 v131, v134, v131
	v_max_f32_e32 v134, v101, v101
	v_max_f32_e32 v135, v69, v69
	v_max_f32_e32 v134, v135, v134
	v_max3_f32 v128, v128, v130, v134
	v_max_f32_e32 v130, v117, v117
	v_max_f32_e32 v134, v85, v85
	v_max_f32_e32 v130, v134, v130
	v_max3_f32 v129, v129, v131, v130
	v_max_f32_e32 v130, v102, v102
	v_max_f32_e32 v131, v70, v70
	v_max_f32_e32 v130, v131, v130
	v_max_f32_e32 v131, v118, v118
	v_max_f32_e32 v134, v86, v86
	v_max_f32_e32 v131, v134, v131
	v_max_f32_e32 v134, v103, v103
	v_max_f32_e32 v135, v71, v71
	v_max_f32_e32 v134, v135, v134
	v_max3_f32 v128, v128, v130, v134
	v_max_f32_e32 v130, v119, v119
	v_max_f32_e32 v134, v87, v87
	v_max_f32_e32 v130, v134, v130
	v_max3_f32 v129, v129, v131, v130
	v_max_f32_e32 v130, v104, v104
	v_max_f32_e32 v131, v72, v72
	v_max_f32_e32 v130, v131, v130
	v_max_f32_e32 v131, v120, v120
	v_max_f32_e32 v134, v88, v88
	v_max_f32_e32 v131, v134, v131
	v_max_f32_e32 v134, v105, v105
	v_max_f32_e32 v135, v73, v73
	v_max_f32_e32 v134, v135, v134
	v_max3_f32 v128, v128, v130, v134
	v_max_f32_e32 v130, v121, v121
	v_max_f32_e32 v134, v89, v89
	v_max_f32_e32 v130, v134, v130
	v_max3_f32 v129, v129, v131, v130
	v_max_f32_e32 v130, v106, v106
	v_max_f32_e32 v131, v74, v74
	v_max_f32_e32 v130, v131, v130
	v_max_f32_e32 v131, v122, v122
	v_max_f32_e32 v134, v90, v90
	v_max_f32_e32 v131, v134, v131
	v_max_f32_e32 v134, v107, v107
	v_max_f32_e32 v135, v75, v75
	v_max_f32_e32 v134, v135, v134
	v_max3_f32 v128, v128, v130, v134
	v_max_f32_e32 v130, v123, v123
	v_max_f32_e32 v134, v91, v91
	v_max_f32_e32 v130, v134, v130
	v_max3_f32 v129, v129, v131, v130
	v_max_f32_e32 v130, v108, v108
	v_max_f32_e32 v131, v76, v76
	v_max_f32_e32 v130, v131, v130
	v_max_f32_e32 v131, v124, v124
	v_max_f32_e32 v134, v92, v92
	v_max_f32_e32 v131, v134, v131
	v_max_f32_e32 v134, v109, v109
	v_max_f32_e32 v135, v77, v77
	v_max_f32_e32 v134, v135, v134
	v_max3_f32 v128, v128, v130, v134
	v_max_f32_e32 v130, v125, v125
	v_max_f32_e32 v134, v93, v93
	v_max_f32_e32 v130, v134, v130
	v_max3_f32 v129, v129, v131, v130
	v_max_f32_e32 v130, v110, v110
	v_max_f32_e32 v131, v78, v78
	v_max_f32_e32 v130, v131, v130
	v_max_f32_e32 v131, v126, v126
	v_max_f32_e32 v134, v94, v94
	v_max_f32_e32 v131, v134, v131
	v_max_f32_e32 v134, v111, v111
	v_max_f32_e32 v135, v79, v79
	v_max_f32_e32 v134, v135, v134
	v_max3_f32 v128, v128, v130, v134
	v_max_f32_e32 v130, v127, v127
	v_max_f32_e32 v134, v95, v95
	v_max_f32_e32 v130, v134, v130
	v_max3_f32 v130, v129, v131, v130
	ds_bpermute_b32 v131, v166, v128
	ds_bpermute_b32 v134, v166, v130
	v_cmp_ngt_f32_e32 vcc, s15, v149
	s_waitcnt lgkmcnt(0)
; DI void attn_pass_da(const bfr* __restrict__ P, int b, int tq_wave, int qcol, int kcol, int vcol, int key0, int nkt, char* smem, f32x16 (&o0)[2], f32x16 (&o1)[2]) {
;     ...
;     const float mn0 = fmaxf(m0, mx0), mn1 = fmaxf(m1, mx1);
;     const float al0 = __builtin_amdgcn_exp2f(m0 - mn0), al1 = __builtin_amdgcn_exp2f(m1 - mn1);
;     m0 = mn0; m1 = mn1;
;     float ps0 = 0.f, ps1 = 0.f;
; #pragma unroll
;     for (int i = 0; i < 16; ++i) {
;       s0[0][i] = __builtin_amdgcn_exp2f(s0[0][i] - mn0); ps0 += s0[0][i];
;       s0[1][i] = __builtin_amdgcn_exp2f(s0[1][i] - mn0); ps0 += s0[1][i];
;       s1[0][i] = __builtin_amdgcn_exp2f(s1[0][i] - mn1); ps1 += s1[0][i];
;       s1[1][i] = __builtin_amdgcn_exp2f(s1[1][i] - mn1); ps1 += s1[1][i];
;     }
;     l0 = l0 * al0 + ps0; l1 = l1 * al1 + ps1;
; #pragma unroll
;     for (int i = 0; i < 16; ++i) { acc0[0][i] *= al0; acc0[1][i] *= al0; acc1[0][i] *= al1; acc1[1][i] *= al1; }
	v_max3_f32 v150, v210, v130, v134
	v_cndmask_b32_e32 v132, 0, v132, vcc
	v_cmp_nlt_f32_e32 vcc, s10, v149
	v_max3_f32 v149, v209, v128, v131
	v_sub_f32_e32 v64, v64, v149
	v_exp_f32_e32 v148, v64
	v_sub_f32_e32 v64, v96, v149
	v_exp_f32_e32 v131, v64
	v_sub_f32_e32 v64, v80, v150
	v_exp_f32_e32 v151, v64
	v_sub_f32_e32 v64, v112, v150
	v_exp_f32_e32 v96, v64
	v_sub_f32_e32 v64, v65, v149
	v_exp_f32_e32 v152, v64
	v_sub_f32_e32 v64, v97, v149
	v_exp_f32_e32 v112, v64
	v_sub_f32_e32 v64, v81, v150
	v_exp_f32_e32 v158, v64
	v_sub_f32_e32 v64, v113, v150
	v_exp_f32_e32 v97, v64
	v_sub_f32_e32 v64, v66, v149
	v_exp_f32_e32 v143, v64
	v_sub_f32_e32 v64, v98, v149
	v_exp_f32_e32 v113, v64
	v_sub_f32_e32 v64, v82, v150
	v_exp_f32_e32 v146, v64
	v_sub_f32_e32 v64, v114, v150
	v_exp_f32_e32 v98, v64
	v_sub_f32_e32 v64, v67, v149
	v_exp_f32_e32 v147, v64
	v_sub_f32_e32 v64, v99, v149
	v_exp_f32_e32 v114, v64
	v_sub_f32_e32 v64, v83, v150
	v_exp_f32_e32 v138, v64
	v_sub_f32_e32 v64, v115, v150
	v_exp_f32_e32 v99, v64
	v_sub_f32_e32 v64, v68, v149
	v_exp_f32_e32 v139, v64
	v_sub_f32_e32 v64, v100, v149
	v_exp_f32_e32 v115, v64
	v_sub_f32_e32 v64, v84, v150
	v_exp_f32_e32 v140, v64
	v_sub_f32_e32 v64, v116, v150
	v_exp_f32_e32 v100, v64
	v_sub_f32_e32 v64, v69, v149
	v_exp_f32_e32 v141, v64
	v_sub_f32_e32 v64, v101, v149
	v_exp_f32_e32 v116, v64
	v_sub_f32_e32 v64, v85, v150
	v_exp_f32_e32 v142, v64
	v_sub_f32_e32 v64, v117, v150
	v_exp_f32_e32 v101, v64
	v_sub_f32_e32 v64, v70, v149
	v_exp_f32_e32 v134, v64
	v_sub_f32_e32 v64, v102, v149
	v_cndmask_b32_e32 v129, v201, v132, vcc
	v_exp_f32_e32 v132, v64
	v_sub_f32_e32 v64, v86, v150
	v_exp_f32_e32 v135, v64
	v_sub_f32_e32 v64, v118, v150
	v_exp_f32_e32 v117, v64
	v_sub_f32_e32 v64, v71, v149
	v_exp_f32_e32 v136, v64
	v_sub_f32_e32 v64, v103, v149
	v_sub_f32_e32 v129, v133, v129
	v_exp_f32_e32 v133, v64
	v_sub_f32_e32 v64, v87, v150
	v_exp_f32_e32 v137, v64
	v_sub_f32_e32 v64, v119, v150
	v_exp_f32_e32 v102, v64
	v_sub_f32_e32 v64, v72, v149
	v_exp_f32_e32 v103, v64
	v_sub_f32_e32 v64, v104, v149
	v_exp_f32_e32 v71, v64
	v_sub_f32_e32 v64, v88, v150
	v_exp_f32_e32 v104, v64
	v_sub_f32_e32 v64, v120, v150
	v_exp_f32_e32 v70, v64
	v_sub_f32_e32 v64, v73, v149
	v_exp_f32_e32 v118, v64
	v_sub_f32_e32 v64, v105, v149
	v_exp_f32_e32 v73, v64
	v_sub_f32_e32 v64, v89, v150
	v_exp_f32_e32 v105, v64
	v_sub_f32_e32 v64, v121, v150
	v_exp_f32_e32 v72, v64
	v_sub_f32_e32 v64, v74, v149
	v_exp_f32_e32 v119, v64
	v_sub_f32_e32 v64, v106, v149
	v_exp_f32_e32 v81, v64
	v_sub_f32_e32 v64, v90, v150
	v_exp_f32_e32 v89, v64
	v_sub_f32_e32 v64, v122, v150
	v_exp_f32_e32 v80, v64
	v_sub_f32_e32 v64, v75, v149
	v_exp_f32_e32 v90, v64
	v_sub_f32_e32 v64, v107, v149
	v_exp_f32_e32 v87, v64
	v_sub_f32_e32 v64, v91, v150
	v_exp_f32_e32 v91, v64
	v_sub_f32_e32 v64, v123, v150
	v_exp_f32_e32 v86, v64
	v_sub_f32_e32 v64, v76, v149
	v_exp_f32_e32 v74, v64
	v_sub_f32_e32 v64, v108, v149
	v_exp_f32_e32 v75, v64
	v_sub_f32_e32 v64, v92, v150
	v_exp_f32_e32 v76, v64
	v_sub_f32_e32 v64, v124, v150
	v_exp_f32_e32 v82, v64
	v_sub_f32_e32 v64, v77, v149
	v_exp_f32_e32 v77, v64
	v_sub_f32_e32 v64, v109, v149
	v_exp_f32_e32 v83, v64
	v_sub_f32_e32 v64, v93, v150
	v_exp_f32_e32 v84, v64
	v_sub_f32_e32 v64, v125, v150
	v_exp_f32_e32 v85, v64
	v_sub_f32_e32 v64, v78, v149
	v_exp_f32_e32 v78, v64
	v_sub_f32_e32 v64, v110, v149
	v_exp_f32_e32 v88, v64
	v_sub_f32_e32 v64, v94, v150
	v_exp_f32_e32 v66, v64
	v_sub_f32_e32 v64, v126, v150
	v_exp_f32_e32 v67, v64
	v_sub_f32_e32 v64, v79, v149
	v_exp_f32_e32 v68, v64
	v_sub_f32_e32 v64, v111, v149
	v_lshl_add_u32 v79, v181, 1, v144
	v_lshl_add_u32 v110, v180, 1, v144
	v_lshl_add_u32 v124, v179, 1, v145
	v_lshl_add_u32 v126, v178, 1, v145
	v_exp_f32_e32 v69, v64
	v_sub_f32_e32 v64, v95, v150
	v_sub_f32_e32 v65, v127, v150
	v_cvt_pk_bf16_f32 v92, v148, v152
	v_cvt_pk_bf16_f32 v93, v143, v147
	v_cvt_pk_bf16_f32 v94, v139, v141
	v_cvt_pk_bf16_f32 v95, v134, v136
	v_cvt_pk_bf16_f32 v106, v151, v158
	v_cvt_pk_bf16_f32 v107, v146, v138
	v_cvt_pk_bf16_f32 v108, v140, v142
	v_cvt_pk_bf16_f32 v109, v135, v137
	ds_read_b64 v[120:121], v79 offset:27648
	ds_read_b64 v[122:123], v110 offset:27648
	ds_read_b64 v[124:125], v124 offset:27648
	ds_read_b64 v[126:127], v126 offset:27648
	v_sub_f32_e32 v128, v209, v149
	v_exp_f32_e32 v130, v128
	v_sub_f32_e32 v128, v210, v150
	v_add_f32_e32 v111, 0, v151
	v_exp_f32_e32 v128, v128
	v_add_f32_e32 v110, 0, v148
	v_add_f32_e32 v111, v96, v111
	v_add_f32_e32 v110, v131, v110
	v_add_f32_e32 v111, v158, v111
	v_add_f32_e32 v110, v152, v110
	v_add_f32_e32 v111, v97, v111
	v_add_f32_e32 v110, v112, v110
	v_add_f32_e32 v111, v146, v111
	v_pk_mul_f32 v[46:47], v[46:47], v[128:129] op_sel_hi:[1,0]
	v_pk_mul_f32 v[44:45], v[44:45], v[128:129] op_sel_hi:[1,0]
	v_pk_mul_f32 v[42:43], v[42:43], v[128:129] op_sel_hi:[1,0]
	v_pk_mul_f32 v[40:41], v[40:41], v[128:129] op_sel_hi:[1,0]
	v_pk_mul_f32 v[38:39], v[38:39], v[128:129] op_sel_hi:[1,0]
	v_pk_mul_f32 v[36:37], v[36:37], v[128:129] op_sel_hi:[1,0]
	v_pk_mul_f32 v[34:35], v[34:35], v[128:129] op_sel_hi:[1,0]
	v_pk_mul_f32 v[32:33], v[32:33], v[128:129] op_sel_hi:[1,0]
	v_pk_mul_f32 v[14:15], v[14:15], v[128:129] op_sel_hi:[1,0]
	v_pk_mul_f32 v[12:13], v[12:13], v[128:129] op_sel_hi:[1,0]
	v_pk_mul_f32 v[10:11], v[10:11], v[128:129] op_sel_hi:[1,0]
	v_pk_mul_f32 v[8:9], v[8:9], v[128:129] op_sel_hi:[1,0]
	v_pk_mul_f32 v[6:7], v[6:7], v[128:129] op_sel_hi:[1,0]
	v_pk_mul_f32 v[4:5], v[4:5], v[128:129] op_sel_hi:[1,0]
	v_pk_mul_f32 v[2:3], v[2:3], v[128:129] op_sel_hi:[1,0]
	v_pk_mul_f32 v[0:1], v[0:1], v[128:129] op_sel_hi:[1,0]
	v_add_f32_e32 v110, v143, v110
	v_add_f32_e32 v111, v98, v111
	s_waitcnt lgkmcnt(2)
; #define MFMA32(a, b, c) __builtin_amdgcn_mfma_f32_32x32x16_bf16((a), (b), (c), 0, 0, 0)
; DI unsigned pack2(float a, float b) { unsigned r; asm volatile("v_cvt_pk_bf16_f32 %0, %1, %2" : "=v"(r) : "v"(a), "v"(b)); return r; }
; DI void attn_pass_da(const bfr* __restrict__ P, int b, int tq_wave, int qcol, int kcol, int vcol, int key0, int nkt, char* smem, f32x16 (&o0)[2], f32x16 (&o1)[2]) {
;     ...
; #pragma unroll
;     for (int t2 = 0; t2 < 2; ++t2)
; #pragma unroll
;       for (int j = 0; j < 2; ++j) {
;         u32x4 pk0, pk1;
;         pk0.x = pack2(s0[t2][8 * j + 0], s0[t2][8 * j + 1]); pk0.y = pack2(s0[t2][8 * j + 2], s0[t2][8 * j + 3]);
;         pk0.z = pack2(s0[t2][8 * j + 4], s0[t2][8 * j + 5]); pk0.w = pack2(s0[t2][8 * j + 6], s0[t2][8 * j + 7]);
;         pk1.x = pack2(s1[t2][8 * j + 0], s1[t2][8 * j + 1]); pk1.y = pack2(s1[t2][8 * j + 2], s1[t2][8 * j + 3]);
;         pk1.z = pack2(s1[t2][8 * j + 4], s1[t2][8 * j + 5]); pk1.w = pack2(s1[t2][8 * j + 6], s1[t2][8 * j + 7]);
;         const bf16x8 pf0 = __builtin_bit_cast(bf16x8, pk0), pf1 = __builtin_bit_cast(bf16x8, pk1);
; #pragma unroll
;         for (int dt = 0; dt < 2; ++dt) {
;           const int vsw = (((dt * 32 + r) >> 3) & 7) << 3;
;           const bfr* vrow = sV + (dt * 32 + r) * 72;
;           s16x4 lo = *(const s16x4*)(vrow + ((t2 * 32 + 16 * j + 4 * h) ^ vsw));
;           s16x4 hi = *(const s16x4*)(vrow + ((t2 * 32 + 16 * j + 4 * h + 8) ^ vsw));
;           bf16x8 vf = __builtin_shufflevector(lo, hi, 0, 1, 2, 3, 4, 5, 6, 7);
;           acc0[dt] = MFMA32(vf, pf0, acc0[dt]);
;           acc1[dt] = MFMA32(vf, pf1, acc1[dt]);
;         }
;       }
;   }
;   l0 += __shfl_xor(l0, 32); l1 += __shfl_xor(l1, 32);
	v_mfma_f32_32x32x16_bf16 v[32:47], v[120:123], v[106:109], v[32:47]
	v_add_f32_e32 v110, v113, v110
	v_add_f32_e32 v110, v147, v110
	v_add_f32_e32 v110, v114, v110
	v_mul_f32_e64 v62, v62, v130
	v_mul_f32_e64 v63, v63, v130
	v_pk_mul_f32 v[60:61], v[60:61], v[130:131] op_sel_hi:[1,0]
	v_pk_mul_f32 v[58:59], v[58:59], v[130:131] op_sel_hi:[1,0]
	v_pk_mul_f32 v[56:57], v[56:57], v[130:131] op_sel_hi:[1,0]
	s_waitcnt lgkmcnt(0)
	v_mfma_f32_32x32x16_bf16 v[0:15], v[124:127], v[106:109], v[0:15]
	v_add_f32_e32 v106, v138, v111
	v_add_f32_e32 v106, v99, v106
	v_add_f32_e32 v106, v140, v106
	v_add_f32_e32 v107, v139, v110
	v_add_f32_e32 v106, v100, v106
	v_add_f32_e32 v107, v115, v107
	v_add_f32_e32 v106, v142, v106
	v_pk_mul_f32 v[54:55], v[54:55], v[130:131] op_sel_hi:[1,0]
	v_pk_mul_f32 v[52:53], v[52:53], v[130:131] op_sel_hi:[1,0]
	v_pk_mul_f32 v[50:51], v[50:51], v[130:131] op_sel_hi:[1,0]
	v_pk_mul_f32 v[48:49], v[48:49], v[130:131] op_sel_hi:[1,0]
	v_pk_mul_f32 v[30:31], v[30:31], v[130:131] op_sel_hi:[1,0]
	v_pk_mul_f32 v[28:29], v[28:29], v[130:131] op_sel_hi:[1,0]
	v_pk_mul_f32 v[26:27], v[26:27], v[130:131] op_sel_hi:[1,0]
	v_pk_mul_f32 v[24:25], v[24:25], v[130:131] op_sel_hi:[1,0]
	v_pk_mul_f32 v[22:23], v[22:23], v[130:131] op_sel_hi:[1,0]
	v_pk_mul_f32 v[20:21], v[20:21], v[130:131] op_sel_hi:[1,0]
	v_pk_mul_f32 v[18:19], v[18:19], v[130:131] op_sel_hi:[1,0]
	v_pk_mul_f32 v[16:17], v[16:17], v[130:131] op_sel_hi:[1,0]
	v_lshl_add_u32 v143, v177, 1, v144
	v_add_f32_e32 v107, v141, v107
	v_add_f32_e32 v111, v101, v106
	v_lshl_add_u32 v106, v175, 1, v145
	v_lshl_add_u32 v108, v174, 1, v145
	v_exp_f32_e32 v64, v64
	v_mfma_f32_32x32x16_bf16 v[48:63], v[120:123], v[92:95], v[48:63]
	v_add_f32_e32 v110, v116, v107
	v_add_f32_e32 v110, v134, v110
	v_add_f32_e32 v110, v132, v110
	v_add_f32_e32 v110, v136, v110
	v_add_f32_e32 v111, v135, v111
	v_add_f32_e32 v111, v117, v111
	v_exp_f32_e32 v65, v65
	v_mfma_f32_32x32x16_bf16 v[16:31], v[124:127], v[92:95], v[16:31]
	v_cvt_pk_bf16_f32 v92, v103, v118
	v_cvt_pk_bf16_f32 v93, v119, v90
	v_cvt_pk_bf16_f32 v94, v74, v77
	v_cvt_pk_bf16_f32 v95, v78, v68
	v_cvt_pk_bf16_f32 v120, v104, v105
	v_cvt_pk_bf16_f32 v121, v89, v91
	v_cvt_pk_bf16_f32 v122, v76, v84
	v_cvt_pk_bf16_f32 v123, v66, v64
	ds_read_b64 v[146:147], v143 offset:27648
	ds_read_b64 v[106:107], v106 offset:27648
	ds_read_b64 v[108:109], v108 offset:27648
	v_lshl_add_u32 v143, v176, 1, v144
	ds_read_b64 v[148:149], v143 offset:27648
	v_add_f32_e32 v124, v133, v110
	s_waitcnt lgkmcnt(0)
	v_mfma_f32_32x32x16_bf16 v[48:63], v[146:149], v[92:95], v[48:63]
	v_add_f32_e32 v125, v137, v111
	v_lshlrev_b32_e32 v152, 1, v154
	v_mfma_f32_32x32x16_bf16 v[16:31], v[106:109], v[92:95], v[16:31]
	v_cvt_pk_bf16_f32 v92, v131, v112
	v_cvt_pk_bf16_f32 v93, v113, v114
	v_cvt_pk_bf16_f32 v94, v115, v116
	v_cvt_pk_bf16_f32 v95, v132, v133
	v_cvt_pk_bf16_f32 v96, v96, v97
	v_cvt_pk_bf16_f32 v97, v98, v99
	v_cvt_pk_bf16_f32 v98, v100, v101
	v_add_f32_e32 v100, v103, v124
	v_add_f32_e32 v100, v71, v100
	v_cvt_pk_bf16_f32 v99, v117, v102
	ds_read_b64 v[110:111], v79 offset:27712
	v_lshl_add_u32 v79, v173, 1, v144
	v_add_f32_e32 v100, v118, v100
	ds_read_b64 v[112:113], v79 offset:27648
	v_add_f32_e32 v79, v102, v125
	v_add_f32_e32 v100, v73, v100
	v_add_f32_e32 v79, v104, v79
	v_add_f32_e32 v104, v119, v100
	v_lshl_add_u32 v100, v172, 1, v145
	v_lshl_add_u32 v102, v171, 1, v145
	ds_read_b64 v[100:101], v100 offset:27648
	ds_read_b64 v[102:103], v102 offset:27648
	v_add_f32_e32 v79, v70, v79
	v_add_f32_e32 v79, v105, v79
	v_add_f32_e32 v79, v72, v79
	v_add_f32_e32 v104, v81, v104
	v_add_f32_e32 v79, v89, v79
	v_add_f32_e32 v79, v80, v79
	v_add_f32_e32 v89, v90, v104
	v_add_f32_e32 v89, v87, v89
	v_add_f32_e32 v79, v91, v79
	v_add_f32_e32 v79, v86, v79
	v_add_f32_e32 v74, v74, v89
	s_waitcnt lgkmcnt(2)
	v_mfma_f32_32x32x16_bf16 v[48:63], v[110:113], v[92:95], v[48:63]
	v_cvt_pk_bf16_f32 v90, v71, v73
	v_cvt_pk_bf16_f32 v91, v81, v87
	v_add_f32_e32 v74, v75, v74
	v_add_f32_e32 v74, v77, v74
	v_add_f32_e32 v74, v83, v74
	v_add_f32_e32 v74, v78, v74
	v_add_f32_e32 v78, v88, v74
	s_waitcnt lgkmcnt(0)
	v_mfma_f32_32x32x16_bf16 v[16:31], v[100:103], v[92:95], v[16:31]
	v_cvt_pk_bf16_f32 v92, v75, v83
	v_add_f32_e32 v75, v76, v79
	v_add_f32_e32 v75, v82, v75
	v_add_f32_e32 v75, v84, v75
	v_add_f32_e32 v79, v85, v75
	v_add_f32_e32 v66, v66, v79
	v_cvt_pk_bf16_f32 v93, v88, v69
	v_mfma_f32_32x32x16_bf16 v[32:47], v[146:149], v[120:123], v[32:47]
	v_cvt_pk_bf16_f32 v70, v70, v72
	v_cvt_pk_bf16_f32 v71, v80, v86
	v_cvt_pk_bf16_f32 v72, v82, v85
	v_cvt_pk_bf16_f32 v73, v67, v65
	v_add_f32_e32 v66, v67, v66
	v_add_f32_e32 v67, v68, v78
	v_add_f32_e32 v67, v69, v67
	v_mfma_f32_32x32x16_bf16 v[0:15], v[106:109], v[120:123], v[0:15]
	v_fmac_f32_e32 v67, v156, v130
	ds_bpermute_b32 v68, v166, v67
	v_lshl_add_u32 v80, v169, 1, v144
	v_lshl_add_u32 v74, v168, 1, v145
	v_lshl_add_u32 v76, v167, 1, v145
	ds_read_b64 v[104:105], v80 offset:27648
	ds_read_b64 v[74:75], v74 offset:27648
	ds_read_b64 v[76:77], v76 offset:27648
	v_lshl_add_u32 v80, v170, 1, v144
	v_add_f32_e32 v64, v64, v66
	ds_read_b64 v[106:107], v80 offset:27648
	v_add_f32_e32 v65, v65, v64
	v_mfma_f32_32x32x16_bf16 v[32:47], v[110:113], v[96:99], v[32:47]
	v_fmac_f32_e32 v65, v157, v128
	s_waitcnt lgkmcnt(4)
	v_add_f32_e32 v66, v67, v68
	ds_bpermute_b32 v67, v166, v65
	v_div_scale_f32 v68, s[10:11], v66, v66, 1.0
	v_rcp_f32_e32 v69, v68
	v_add_f32_e32 v64, v155, v129
	v_mfma_f32_32x32x16_bf16 v[0:15], v[100:103], v[96:99], v[0:15]
	s_waitcnt lgkmcnt(0)
; DI int otid() { int t = threadIdx.x & 255; asm volatile("" : "+v"(t)); return t; }
; DI int oidx(int i) { asm volatile("" : "+s"(i)); return i; }
; DI int vhalf() { int h = __builtin_amdgcn_readfirstlane(threadIdx.x >> 8); asm volatile("" : "+s"(h)); return h; }
; DI unsigned pack2(float a, float b) { unsigned r; asm volatile("v_cvt_pk_bf16_f32 %0, %1, %2" : "=v"(r) : "v"(a), "v"(b)); return r; }
; DI void attn_pass_da(const bfr* __restrict__ P, int b, int tq_wave, int qcol, int kcol, int vcol, int key0, int nkt, char* smem, f32x16 (&o0)[2], f32x16 (&o1)[2]) {
;     ...
;   l0 += __shfl_xor(l0, 32); l1 += __shfl_xor(l1, 32);
;   const float i0 = 1.f / l0, i1 = 1.f / l1;
; #pragma unroll
;   for (int i = 0; i < 16; ++i) { o0[0][i] = acc0[0][i] * i0; o0[1][i] = acc0[1][i] * i0; o1[0][i] = acc1[0][i] * i1; o1[1][i] = acc1[1][i] * i1; }
; }
; DI void store_o(bfr* O, int m, int colbase, int h, const f32x16 (&o)[2]) {
; #pragma unroll
;   for (int dt = 0; dt < 2; ++dt)
; #pragma unroll
;     for (int g4 = 0; g4 < 4; ++g4) {
;       int dv = dt * 32 + 8 * g4 + 4 * h;
;       uint2 pk; pk.x = pack2(o[dt][4 * g4], o[dt][4 * g4 + 1]); pk.y = pack2(o[dt][4 * g4 + 2], o[dt][4 * g4 + 3]);
;       *(uint2*)(O + (size_t)m * DM + colbase + dv) = pk;
;     }
; }
; DN void da_item(const Params& p, int l, int b, int hd, int tq0, int key0, int nkt, char* smem) {
;   const bfr* P = (const bfr*)(p.ws + OFF_P);
;   bfr* O = (bfr*)(p.ws + OFF_HO);
;   const int tid = otid(), lane = tid & 63, w = tid >> 6, r = lane & 31, h = lane >> 5;
;   const float* lv = p.in[oidx(22)] + l * 128;
;   float d01 = (lane < 32) ? lv[lane] * lv[32 + lane] : 0.f;
;   float d23 = (lane < 32) ? lv[64 + lane] * lv[96 + lane] : 0.f;
;   d01 = wave_sum(d01); d23 = wave_sum(d23);
;   float lam_init = 0.8f - 0.6f * expf(-0.3f * (float)l);
;   float lam = expf(d01) - expf(d23) + lam_init;
;   f32x16 o0[2], o1[2];
;   int tqw = tq0 + vhalf() * 128 + w * 32;
;   attn_pass_da(P, b, tqw, 1152 + hd * 64, 1408 + hd * 64, 1664 + hd * 64, key0, nkt, smem, o0, o1);
;   float ss = 0.f;
; #pragma unroll
;   for (int dt = 0; dt < 2; ++dt)
; #pragma unroll
;     for (int i = 0; i < 16; ++i) { float v = o0[dt][i] - lam * o1[dt][i]; o0[dt][i] = v; ss += v * v; }
;   ss += __shfl_xor(ss, 32);
;   float rstd = rsqrtf(ss * (1.f / 64.f) + 1e-6f) * (1.f - lam_init);
;   const float* sg = p.in[oidx(23)] + l * 64;
	v_add_f32_e32 v65, v65, v67
	v_fma_f32 v67, -v68, v69, 1.0
	v_fmac_f32_e32 v69, v67, v69
	v_div_scale_f32 v67, vcc, 1.0, v66, 1.0
	v_mfma_f32_32x32x16_bf16 v[32:47], v[104:107], v[70:73], v[32:47]
	v_mfma_f32_32x32x16_bf16 v[0:15], v[74:77], v[70:73], v[0:15]
	v_mul_f32_e32 v70, v67, v69
	v_fma_f32 v71, -v68, v70, v67
	v_fmac_f32_e32 v70, v71, v69
	v_fma_f32 v67, -v68, v70, v67
	v_div_scale_f32 v68, s[10:11], v65, v65, 1.0
	v_rcp_f32_e32 v71, v68
	v_div_fmas_f32 v67, v67, v69, v70
	v_div_fixup_f32 v66, v67, v66, 1.0
	v_mfma_f32_32x32x16_bf16 v[48:63], v[104:107], v[90:93], v[48:63]
	v_fma_f32 v67, -v68, v71, 1.0
	v_fmac_f32_e32 v71, v67, v71
	v_div_scale_f32 v67, vcc, 1.0, v65, 1.0
	v_mul_f32_e32 v69, v67, v71
	v_fma_f32 v70, -v68, v69, v67
	v_fmac_f32_e32 v69, v70, v71
	v_fma_f32 v67, -v68, v69, v67
	v_div_fmas_f32 v67, v67, v71, v69
	v_div_fixup_f32 v68, v67, v65, 1.0
	v_mul_f32_e32 v65, v0, v68
	v_mul_f32_e32 v0, v33, v68
	v_mul_f32_e32 v67, v1, v68
	v_mul_f32_e32 v1, v34, v68
	v_mul_f32_e32 v0, v64, v0
	v_mul_f32_e32 v32, v32, v68
	v_mul_f32_e32 v69, v2, v68
	v_mul_f32_e32 v2, v35, v68
	v_mul_f32_e32 v33, v37, v68
	v_mul_f32_e32 v37, v41, v68
	v_mul_f32_e32 v41, v45, v68
	v_fma_f32 v45, v49, v66, -v0
	v_mul_f32_e32 v0, v64, v1
	v_mul_f32_e32 v70, v3, v68
	v_mul_f32_e32 v3, v36, v68
	v_mul_f32_e32 v35, v39, v68
	v_mul_f32_e32 v39, v43, v68
	v_mul_f32_e32 v43, v47, v68
	v_mul_f32_e32 v32, v64, v32
	v_fma_f32 v47, v50, v66, -v0
	v_mul_f32_e32 v0, v64, v2
	v_mul_f32_e32 v36, v40, v68
	v_mul_f32_e32 v40, v44, v68
	v_fma_f32 v44, v48, v66, -v32
	v_fma_f32 v48, v51, v66, -v0
	v_mul_f32_e32 v0, v64, v3
	v_mul_f32_e32 v34, v38, v68
	v_fma_f32 v49, v52, v66, -v0
	v_mul_f32_e32 v0, v64, v33
	s_mov_b32 s10, 23
	v_fma_f32 v50, v53, v66, -v0
	v_mul_f32_e32 v0, v64, v34
	s_ashr_i32 s11, s10, 31
	v_fma_f32 v51, v54, v66, -v0
	v_mul_f32_e32 v0, v64, v35
	s_lshl_b64 s[10:11], s[10:11], 3
	v_fma_f32 v52, v55, v66, -v0
	v_mul_f32_e32 v0, v64, v36
	s_add_u32 s10, s0, s10
	v_mul_f32_e32 v38, v42, v68
	v_fma_f32 v53, v56, v66, -v0
	v_mul_f32_e32 v0, v64, v37
	s_addc_u32 s11, s1, s11
	v_fma_f32 v54, v57, v66, -v0
	v_mul_f32_e32 v0, v64, v38
	s_load_dwordx2 s[10:11], s[10:11], 0x0
	v_mul_f32_e32 v42, v46, v68
	v_mul_f32_e32 v46, v45, v45
	v_fma_f32 v55, v58, v66, -v0
	v_mul_f32_e32 v0, v64, v39
	v_fmac_f32_e32 v46, v44, v44
	v_fma_f32 v56, v59, v66, -v0
	v_mul_f32_e32 v0, v64, v40
	v_fmac_f32_e32 v46, v47, v47
	v_fma_f32 v57, v60, v66, -v0
	v_mul_f32_e32 v0, v64, v41
	v_fmac_f32_e32 v46, v48, v48
	v_fma_f32 v58, v61, v66, -v0
	s_lshl_b64 s[12:13], s[12:13], 2
	v_lshrrev_b32_e32 v0, 3, v164
	v_fmac_f32_e32 v46, v49, v49
	s_waitcnt lgkmcnt(0)
	s_add_u32 s10, s10, s12
	v_and_b32_e32 v59, 4, v0
	v_fmac_f32_e32 v46, v50, v50
	s_addc_u32 s11, s11, s13
	v_lshlrev_b32_e32 v60, 2, v59
	v_mfma_f32_32x32x16_bf16 v[16:31], v[74:77], v[90:93], v[16:31]
	v_fmac_f32_e32 v46, v51, v51
	global_load_dwordx4 v[0:3], v60, s[10:11]
	v_fmac_f32_e32 v46, v52, v52
	v_fmac_f32_e32 v46, v53, v53
	v_mul_f32_e32 v32, v64, v42
	v_fmac_f32_e32 v46, v54, v54
	v_fma_f32 v61, v62, v66, -v32
	v_mul_f32_e32 v32, v64, v43
	v_fmac_f32_e32 v46, v55, v55
	v_fma_f32 v62, v63, v66, -v32
	global_load_dwordx4 v[32:35], v60, s[10:11] offset:32
	v_fmac_f32_e32 v46, v56, v56
	v_fmac_f32_e32 v46, v57, v57
	v_fmac_f32_e32 v46, v58, v58
	v_mul_f32_e32 v36, v64, v65
	v_fmac_f32_e32 v46, v61, v61
	v_fma_f32 v63, v16, v66, -v36
	v_mul_f32_e32 v16, v64, v67
	global_load_dwordx4 v[36:39], v60, s[10:11] offset:64
	v_mul_f32_e32 v4, v4, v68
	v_fmac_f32_e32 v46, v62, v62
	v_fma_f32 v65, v17, v66, -v16
	v_mul_f32_e32 v16, v64, v69
	v_mul_f32_e32 v5, v5, v68
	v_fmac_f32_e32 v46, v63, v63
	v_fma_f32 v67, v18, v66, -v16
	v_mul_f32_e32 v16, v64, v70
	v_mul_f32_e32 v4, v64, v4
	v_fmac_f32_e32 v46, v65, v65
	v_fma_f32 v69, v19, v66, -v16
	v_fma_f32 v70, v20, v66, -v4
	v_mul_f32_e32 v4, v64, v5
	v_fmac_f32_e32 v46, v67, v67
	global_load_dwordx4 v[16:19], v60, s[10:11] offset:96
	v_fma_f32 v71, v21, v66, -v4
	v_pk_mul_f32 v[4:5], v[6:7], v[68:69] op_sel_hi:[1,0]
	v_fmac_f32_e32 v46, v69, v69
	v_pk_mul_f32 v[4:5], v[64:65], v[4:5] op_sel_hi:[0,1]
	v_fmac_f32_e32 v46, v70, v70
	v_pk_fma_f32 v[40:41], v[22:23], v[66:67], v[4:5] op_sel_hi:[1,0,1] neg_lo:[0,0,1] neg_hi:[0,0,1]
	v_pk_mul_f32 v[8:9], v[8:9], v[68:69] op_sel_hi:[1,0]
	v_fmac_f32_e32 v46, v71, v71
	v_pk_mul_f32 v[20:21], v[40:41], v[40:41]
	v_pk_mul_f32 v[8:9], v[64:65], v[8:9] op_sel_hi:[0,1]
	global_load_dwordx4 v[4:7], v60, s[10:11] offset:128
	v_add_f32_e32 v20, v20, v46
	v_pk_fma_f32 v[24:25], v[24:25], v[66:67], v[8:9] op_sel_hi:[1,0,1] neg_lo:[0,0,1] neg_hi:[0,0,1]
	v_add_f32_e32 v20, v21, v20
	v_pk_mul_f32 v[8:9], v[24:25], v[24:25]
	v_pk_mul_f32 v[12:13], v[12:13], v[68:69] op_sel_hi:[1,0]
	v_add_f32_e32 v8, v8, v20
	v_add_f32_e32 v42, v9, v8
	v_pk_mul_f32 v[8:9], v[10:11], v[68:69] op_sel_hi:[1,0]
	global_load_dwordx4 v[20:23], v60, s[10:11] offset:160
	v_pk_mul_f32 v[8:9], v[64:65], v[8:9] op_sel_hi:[0,1]
	v_pk_fma_f32 v[26:27], v[26:27], v[66:67], v[8:9] op_sel_hi:[1,0,1] neg_lo:[0,0,1] neg_hi:[0,0,1]
	v_pk_mul_f32 v[12:13], v[64:65], v[12:13] op_sel_hi:[0,1]
	v_pk_mul_f32 v[8:9], v[26:27], v[26:27]
	v_pk_fma_f32 v[28:29], v[28:29], v[66:67], v[12:13] op_sel_hi:[1,0,1] neg_lo:[0,0,1] neg_hi:[0,0,1]
	v_add_f32_e32 v8, v8, v42
	v_add_f32_e32 v42, v9, v8
	global_load_dwordx4 v[8:11], v60, s[10:11] offset:192
	v_pk_mul_f32 v[12:13], v[28:29], v[28:29]
	s_load_dwordx4 s[12:15], s[0:1], 0x100
	v_add_f32_e32 v12, v12, v42
	v_add_f32_e32 v46, v13, v12
	v_pk_mul_f32 v[42:43], v[14:15], v[68:69] op_sel_hi:[1,0]
	global_load_dwordx4 v[12:15], v60, s[10:11] offset:224
	v_pk_mul_f32 v[42:43], v[64:65], v[42:43] op_sel_hi:[0,1]
	v_pk_fma_f32 v[30:31], v[30:31], v[66:67], v[42:43] op_sel_hi:[1,0,1] neg_lo:[0,0,1] neg_hi:[0,0,1]
	s_mov_b64 s[10:11], 0x2b7c300
	v_pk_mul_f32 v[42:43], v[30:31], v[30:31]
	s_nop 0
	v_add_f32_e32 v42, v42, v46
	v_add_f32_e32 v42, v43, v42
	ds_bpermute_b32 v43, v166, v42
	s_waitcnt lgkmcnt(0)
; DI int oidx(int i) { asm volatile("" : "+s"(i)); return i; }
; DI unsigned pack2(float a, float b) { unsigned r; asm volatile("v_cvt_pk_bf16_f32 %0, %1, %2" : "=v"(r) : "v"(a), "v"(b)); return r; }
; DI void store_o(bfr* O, int m, int colbase, int h, const f32x16 (&o)[2]) {
; #pragma unroll
;   for (int dt = 0; dt < 2; ++dt)
; #pragma unroll
;     for (int g4 = 0; g4 < 4; ++g4) {
;       int dv = dt * 32 + 8 * g4 + 4 * h;
;       uint2 pk; pk.x = pack2(o[dt][4 * g4], o[dt][4 * g4 + 1]); pk.y = pack2(o[dt][4 * g4 + 2], o[dt][4 * g4 + 3]);
;       *(uint2*)(O + (size_t)m * DM + colbase + dv) = pk;
;     }
; }
; DN void da_item(const Params& p, int l, int b, int hd, int tq0, int key0, int nkt, char* smem) {
;     ...
;   ss += __shfl_xor(ss, 32);
;   float rstd = rsqrtf(ss * (1.f / 64.f) + 1e-6f) * (1.f - lam_init);
;   const float* sg = p.in[oidx(23)] + l * 64;
; #pragma unroll
;   for (int dt = 0; dt < 2; ++dt)
; #pragma unroll
;     for (int i = 0; i < 16; ++i) { int dv = dt * 32 + 8 * (i >> 2) + 4 * h + (i & 3); o0[dt][i] = o0[dt][i] * rstd * sg[dv]; }
;   store_o(O, b * TT + tqw + r, 256 + hd * 64, h, o0);
	v_add_f32_e32 v42, v42, v43
	v_fmamk_f32 v42, v42, 0x3c800000, v186
	v_cmp_gt_f32_e32 vcc, s33, v42
	v_mul_f32_e32 v43, 0x4b800000, v42
	s_nop 0
	v_cndmask_b32_e32 v42, v42, v43, vcc
	v_rsq_f32_e32 v42, v42
	s_nop 0
	v_mul_f32_e32 v43, 0x45800000, v42
	v_cndmask_b32_e32 v42, v42, v43, vcc
	v_mul_f32_e32 v42, v162, v42
	v_mul_f32_e32 v43, v44, v42
	s_waitcnt vmcnt(7)
	v_mul_f32_e32 v43, v0, v43
	v_mul_f32_e32 v0, v45, v42
	v_mul_f32_e32 v44, v1, v0
	v_mul_f32_e32 v0, v47, v42
	v_mul_f32_e32 v45, v2, v0
	v_mul_f32_e32 v0, v48, v42
	v_mul_f32_e32 v3, v3, v0
	v_mul_f32_e32 v0, v49, v42
	s_waitcnt vmcnt(6)
	v_mul_f32_e32 v32, v32, v0
	v_mul_f32_e32 v0, v50, v42
	v_mul_f32_e32 v33, v33, v0
	v_mul_f32_e32 v0, v51, v42
	v_mul_f32_e32 v34, v34, v0
	v_mul_f32_e32 v0, v52, v42
	v_mul_f32_e32 v35, v35, v0
	v_mul_f32_e32 v0, v53, v42
	s_waitcnt vmcnt(5)
	v_mul_f32_e32 v36, v36, v0
	v_mul_f32_e32 v0, v54, v42
	v_mul_f32_e32 v37, v37, v0
	v_mul_f32_e32 v0, v55, v42
	v_mul_f32_e32 v38, v38, v0
	v_mul_f32_e32 v0, v56, v42
	v_mul_f32_e32 v39, v39, v0
	v_mul_f32_e32 v0, v57, v42
	s_waitcnt vmcnt(4)
	v_mul_f32_e32 v16, v16, v0
	v_mul_f32_e32 v0, v58, v42
	v_mul_f32_e32 v17, v17, v0
	v_mul_f32_e32 v0, v61, v42
	v_mul_f32_e32 v18, v18, v0
	v_mul_f32_e32 v0, v62, v42
	v_mul_f32_e32 v19, v19, v0
	v_mul_f32_e32 v0, v63, v42
	s_waitcnt vmcnt(3)
	v_mul_f32_e32 v46, v4, v0
	v_mul_f32_e32 v0, v65, v42
	v_mul_f32_e32 v47, v5, v0
	v_mul_f32_e32 v0, v67, v42
	v_mul_f32_e32 v6, v6, v0
	v_mul_f32_e32 v0, v69, v42
	v_mul_f32_e32 v7, v7, v0
	v_mul_f32_e32 v0, v70, v42
	s_waitcnt vmcnt(2)
	v_mul_f32_e32 v20, v20, v0
	v_mul_f32_e32 v0, v71, v42
	v_mul_f32_e32 v21, v21, v0
	v_mul_f32_e32 v0, v40, v42
	v_mul_f32_e32 v22, v22, v0
	v_mul_f32_e32 v0, v41, v42
	v_mul_f32_e32 v23, v23, v0
	v_mul_f32_e32 v0, v24, v42
	s_waitcnt vmcnt(1)
	v_mul_f32_e32 v8, v8, v0
	v_mul_f32_e32 v0, v25, v42
	v_mul_f32_e32 v9, v9, v0
	v_mul_f32_e32 v0, v26, v42
	v_mul_f32_e32 v10, v10, v0
	v_mul_f32_e32 v0, v27, v42
	v_mul_f32_e32 v11, v11, v0
	v_mul_f32_e32 v0, v28, v42
	s_waitcnt vmcnt(0)
	v_mul_f32_e32 v12, v12, v0
	v_mul_f32_e32 v0, v29, v42
	v_mul_f32_e32 v13, v13, v0
	v_mul_f32_e32 v0, v30, v42
	v_mul_f32_e32 v14, v14, v0
	v_mul_f32_e32 v0, v31, v42
	v_mul_f32_e32 v15, v15, v0
	v_and_or_b32 v0, v164, 31, v165
	v_ashrrev_i32_e32 v1, 31, v0
	v_lshlrev_b64 v[0:1], 11, v[0:1]
	v_lshl_add_u64 v[0:1], s[14:15], 0, v[0:1]
	v_lshl_add_u64 v[0:1], v[0:1], 0, v[152:153]
	v_lshlrev_b32_e32 v152, 1, v59
	v_lshl_add_u64 v[0:1], v[0:1], 0, v[152:153]
	v_lshl_add_u64 v[4:5], v[0:1], 0, s[10:11]
	s_mov_b32 s10, 0x2b7c000
	v_add_co_u32_e32 v0, vcc, s10, v0
	v_cvt_pk_bf16_f32 v2, v43, v44
	v_cvt_pk_bf16_f32 v3, v45, v3
	s_nop 1
	v_addc_co_u32_e32 v1, vcc, 0, v1, vcc
	global_store_dwordx2 v[0:1], v[2:3], off offset:768
	v_cvt_pk_bf16_f32 v0, v32, v33
	v_cvt_pk_bf16_f32 v1, v34, v35
	global_store_dwordx2 v[4:5], v[0:1], off offset:16
	v_cvt_pk_bf16_f32 v0, v36, v37
	v_cvt_pk_bf16_f32 v1, v38, v39
	global_store_dwordx2 v[4:5], v[0:1], off offset:32
	v_cvt_pk_bf16_f32 v0, v16, v17
	v_cvt_pk_bf16_f32 v1, v18, v19
	global_store_dwordx2 v[4:5], v[0:1], off offset:48
	v_cvt_pk_bf16_f32 v0, v46, v47
	v_cvt_pk_bf16_f32 v1, v6, v7
	global_store_dwordx2 v[4:5], v[0:1], off offset:64
	v_cvt_pk_bf16_f32 v0, v20, v21
	v_cvt_pk_bf16_f32 v1, v22, v23
	global_store_dwordx2 v[4:5], v[0:1], off offset:80
	v_cvt_pk_bf16_f32 v0, v8, v9
	v_cvt_pk_bf16_f32 v1, v10, v11
	global_store_dwordx2 v[4:5], v[0:1], off offset:96
	v_cvt_pk_bf16_f32 v0, v12, v13
	v_cvt_pk_bf16_f32 v1, v14, v15
	global_store_dwordx2 v[4:5], v[0:1], off offset:112
	s_or_b64 exec, exec, s[8:9]

; #define MFMA32(a, b, c) __builtin_amdgcn_mfma_f32_32x32x16_bf16((a), (b), (c), 0, 0, 0)
; template <int D>
; DI void attn_pass(const bfr* __restrict__ P, int b, int tq_wave, int qcol, int kcol, int vcol, int key0, int nkt, char* smem, f32x16 (&o)[2]) {
;     ...
;   for (int kt = 0; kt < nkt; ++kt) {
;     bfr* sK = sbase + (kt & 1) * 9216;
;     bfr* sV = sK + 64 * 72;
;     { int c = gt, row = c >> 3, kc = c & 7; *(u32x4*)(sK + row * KP + kc * 8) = kreg[0]; }
;     for (int i = 0; i < 1; ++i) {
;       int c = gt, row = c >> 3, kc = c & 7;
;       unsigned wds[4] = {vreg[i].x, vreg[i].y, vreg[i].z, vreg[i].w};
; #pragma unroll
;       for (int e = 0; e < 4; ++e) {
;         sV[(kc * 8 + 2 * e) * 72 + (row ^ (kc << 3))] = (bfr)(wds[e] & 0xffffu);
;         sV[(kc * 8 + 2 * e + 1) * 72 + (row ^ (kc << 3))] = (bfr)(wds[e] >> 16);
;       }
;     }
;     __syncthreads();
;     if (kt + 1 < nkt) {
;       const bfr* Pn = Pb + (size_t)(kt + 1) * 64 * PW;
;       { int c = gt, row = c >> 3, kc = c & 7; kreg[0] = *(const u32x4*)(Pn + (size_t)row * PW + kcol + kc * 8); vreg[0] = *(const u32x4*)(Pn + (size_t)row * PW + vcol + kc * 8); }
;     }
;     f32x16 s[2];
; #pragma unroll
;     for (int t2 = 0; t2 < 2; ++t2) {
; #pragma unroll
;       for (int i = 0; i < 16; ++i) s[t2][i] = 0.f;
; #pragma unroll
;       for (int ks = 0; ks < KS; ++ks) {
;         bf16x8 a = *(const bf16x8*)(sK + (t2 * 32 + r) * KP + ks * 16 + h * 8);
;         s[t2] = MFMA32(a, qf[ks], s[t2]);
;       }
;     }
;     float mx = s[0][0];
; #pragma unroll
;     for (int i = 0; i < 16; ++i) { mx = fmaxf(mx, s[0][i]); mx = fmaxf(mx, s[1][i]); }
;     mx = fmaxf(mx, __shfl_xor(mx, 32));
;     float mnew = fmaxf(mrun, mx);
;     float alpha = __builtin_amdgcn_exp2f(mrun - mnew);
;     mrun = mnew;
;     float ps = 0.f;
; #pragma unroll
;     for (int i = 0; i < 16; ++i) {
;       s[0][i] = __builtin_amdgcn_exp2f(s[0][i] - mnew); ps += s[0][i];
;       s[1][i] = __builtin_amdgcn_exp2f(s[1][i] - mnew); ps += s[1][i];
;     }
;     lsum = lsum * alpha + ps;
.LBB0_412:
	s_bitcmp1_b32 s8, 0
	s_cselect_b32 s9, 0x4800, 0
	s_add_i32 s9, s9, 0
	v_add3_u32 v32, s9, v115, v90
	v_add_u32_e32 v121, s9, v114
	v_mov_b32_e32 v120, v113
	s_waitcnt vmcnt(1)
	ds_write_b128 v32, v[84:87]
	v_add3_u32 v32, s9, v117, v118
	v_add3_u32 v33, s9, v118, v117
	v_add_u32_e32 v113, v121, v152
	s_waitcnt vmcnt(0)
	ds_write_b16 v32, v80 offset:9216
	ds_write_b16_d16_hi v33, v80 offset:9360
	ds_write_b16 v32, v81 offset:9504
	ds_write_b16_d16_hi v33, v81 offset:9648
	ds_write_b16 v32, v82 offset:9792
	ds_write_b16_d16_hi v33, v82 offset:9936
	ds_write_b16 v32, v83 offset:10080
	ds_write_b16_d16_hi v33, v83 offset:10224
	s_waitcnt lgkmcnt(0)
	s_barrier
	global_load_dwordx4 v[84:87], v[92:93], off
	global_load_dwordx4 v[80:83], v[94:95], off
	ds_read_b128 v[126:129], v113
	ds_read_b128 v[130:133], v113 offset:32
	ds_read_b128 v[134:137], v113 offset:64
	ds_read_b128 v[138:141], v113 offset:96
	ds_read_b128 v[142:145], v113 offset:4608
	ds_read_b128 v[146:149], v113 offset:4640
	ds_read_b128 v[156:159], v113 offset:4672
	ds_read_b128 v[164:167], v113 offset:4704
	v_mov_b32_e32 v96, v119
	s_waitcnt lgkmcnt(7)
	v_mfma_f32_32x32x16_bf16 v[32:47], v[126:129], v[76:79], 0
	s_add_i32 s8, s8, 1
	s_waitcnt lgkmcnt(6)
	v_mfma_f32_32x32x16_bf16 v[32:47], v[130:133], v[72:75], v[32:47]
	v_lshl_add_u64 v[92:93], v[92:93], 0, s[10:11]
	s_waitcnt lgkmcnt(5)
	v_mfma_f32_32x32x16_bf16 v[32:47], v[134:137], v[68:71], v[32:47]
	v_lshl_add_u64 v[94:95], v[94:95], 0, s[10:11]
	s_waitcnt lgkmcnt(4)
	v_mfma_f32_32x32x16_bf16 v[32:47], v[138:141], v[64:67], v[32:47]
	s_cmp_lg_u32 s8, 35
	s_waitcnt lgkmcnt(3)
	v_mfma_f32_32x32x16_bf16 v[48:63], v[142:145], v[76:79], 0
	s_waitcnt lgkmcnt(2)
	v_mfma_f32_32x32x16_bf16 v[48:63], v[146:149], v[72:75], v[48:63]
	s_waitcnt lgkmcnt(1)
	v_mfma_f32_32x32x16_bf16 v[48:63], v[156:159], v[68:71], v[48:63]
	s_waitcnt lgkmcnt(0)
	v_mfma_f32_32x32x16_bf16 v[48:63], v[164:167], v[64:67], v[48:63]
	v_add_u32_e32 v154, s9, v116
	v_lshl_add_u32 v168, v112, 1, v121
	v_lshl_add_u32 v169, v111, 1, v121
	v_lshl_add_u32 v170, v110, 1, v154
	v_lshl_add_u32 v171, v109, 1, v154
	v_lshl_add_u32 v172, v108, 1, v121
	v_lshl_add_u32 v173, v107, 1, v121
	v_lshl_add_u32 v174, v106, 1, v154
	v_lshl_add_u32 v175, v105, 1, v154
	v_lshl_add_u32 v176, v104, 1, v121
	v_lshl_add_u32 v177, v103, 1, v154
	v_lshl_add_u32 v178, v102, 1, v154
	v_lshl_add_u32 v179, v100, 1, v121
	v_lshl_add_u32 v180, v101, 1, v121
	v_lshl_add_u32 v181, v99, 1, v154
	v_lshl_add_u32 v160, v98, 1, v154
	v_max_f32_e32 v119, v32, v32
	v_max_f32_e32 v113, v48, v48
	v_max_f32_e32 v113, v119, v113
	v_max3_f32 v113, v113, v33, v49
	v_max3_f32 v113, v113, v34, v50
	v_max3_f32 v113, v113, v35, v51
	v_max3_f32 v113, v113, v36, v52
	v_max3_f32 v113, v113, v37, v53
	v_max3_f32 v113, v113, v38, v54
	v_max3_f32 v113, v113, v39, v55
	v_max3_f32 v113, v113, v40, v56
	v_max3_f32 v113, v113, v41, v57
	v_max3_f32 v113, v113, v42, v58
	v_max3_f32 v113, v113, v43, v59
	v_max3_f32 v113, v113, v44, v60
	v_max3_f32 v113, v113, v45, v61
	v_max3_f32 v113, v113, v46, v62
	v_max3_f32 v113, v113, v47, v63
	v_mov_b32_e32 v119, v113
	s_nop 1
	v_permlane32_swap_b32_e32 v113, v119
	s_waitcnt lgkmcnt(0)
	ds_read_b64 v[126:127], v168 offset:9216
	ds_read_b64 v[128:129], v169 offset:9216
	ds_read_b64 v[130:131], v170 offset:9216
	ds_read_b64 v[132:133], v171 offset:9216
	ds_read_b64 v[134:135], v172 offset:9216
	ds_read_b64 v[136:137], v173 offset:9216
	ds_read_b64 v[138:139], v174 offset:9216
	ds_read_b64 v[140:141], v175 offset:9216
	v_max3_f32 v119, v96, v113, v119
	v_pk_add_f32 v[32:33], v[32:33], v[118:119] op_sel:[0,1] op_sel_hi:[1,1] neg_lo:[0,1] neg_hi:[0,1]
	v_pk_add_f32 v[38:39], v[38:39], v[118:119] op_sel:[0,1] op_sel_hi:[1,1] neg_lo:[0,1] neg_hi:[0,1]
	v_exp_f32_e32 v32, v32
	v_pk_add_f32 v[48:49], v[48:49], v[118:119] op_sel:[0,1] op_sel_hi:[1,1] neg_lo:[0,1] neg_hi:[0,1]
	v_pk_add_f32 v[36:37], v[36:37], v[118:119] op_sel:[0,1] op_sel_hi:[1,1] neg_lo:[0,1] neg_hi:[0,1]
	v_exp_f32_e32 v124, v38
	v_pk_add_f32 v[54:55], v[54:55], v[118:119] op_sel:[0,1] op_sel_hi:[1,1] neg_lo:[0,1] neg_hi:[0,1]
	v_exp_f32_e32 v48, v48
	v_exp_f32_e32 v122, v36
	v_sub_f32_e32 v36, v52, v119
	v_exp_f32_e32 v52, v54
	v_exp_f32_e32 v33, v33
	v_exp_f32_e32 v125, v39
	v_exp_f32_e32 v49, v49
	v_pk_add_f32 v[34:35], v[34:35], v[118:119] op_sel:[0,1] op_sel_hi:[1,1] neg_lo:[0,1] neg_hi:[0,1]
	v_exp_f32_e32 v123, v37
	v_sub_f32_e32 v37, v53, v119
	v_exp_f32_e32 v53, v55
	v_pk_add_f32 v[40:41], v[40:41], v[118:119] op_sel:[0,1] op_sel_hi:[1,1] neg_lo:[0,1] neg_hi:[0,1]
	v_pk_add_f32 v[42:43], v[42:43], v[118:119] op_sel:[0,1] op_sel_hi:[1,1] neg_lo:[0,1] neg_hi:[0,1]
	v_pk_add_f32 v[44:45], v[44:45], v[118:119] op_sel:[0,1] op_sel_hi:[1,1] neg_lo:[0,1] neg_hi:[0,1]
	v_exp_f32_e32 v34, v34
	v_pk_add_f32 v[50:51], v[50:51], v[118:119] op_sel:[0,1] op_sel_hi:[1,1] neg_lo:[0,1] neg_hi:[0,1]
	v_exp_f32_e32 v54, v40
	v_sub_f32_e32 v38, v56, v119
	v_exp_f32_e32 v56, v42
	v_sub_f32_e32 v40, v58, v119
	v_exp_f32_e32 v58, v44
	v_sub_f32_e32 v42, v60, v119
	s_waitcnt lgkmcnt(4)
; #define MFMA32(a, b, c) __builtin_amdgcn_mfma_f32_32x32x16_bf16((a), (b), (c), 0, 0, 0)
; DI unsigned pack2(float a, float b) { unsigned r; asm volatile("v_cvt_pk_bf16_f32 %0, %1, %2" : "=v"(r) : "v"(a), "v"(b)); return r; }
; template <int D>
; DI void attn_pass(const bfr* __restrict__ P, int b, int tq_wave, int qcol, int kcol, int vcol, int key0, int nkt, char* smem, f32x16 (&o)[2]) {
;     ...
;     float mnew = fmaxf(mrun, mx);
;     float alpha = __builtin_amdgcn_exp2f(mrun - mnew);
;     mrun = mnew;
;     float ps = 0.f;
; #pragma unroll
;     for (int i = 0; i < 16; ++i) {
;       s[0][i] = __builtin_amdgcn_exp2f(s[0][i] - mnew); ps += s[0][i];
;       s[1][i] = __builtin_amdgcn_exp2f(s[1][i] - mnew); ps += s[1][i];
;     }
;     lsum = lsum * alpha + ps;
; #pragma unroll
;     for (int i = 0; i < 16; ++i) { accO[0][i] *= alpha; accO[1][i] *= alpha; }
; #pragma unroll
;     for (int t2 = 0; t2 < 2; ++t2)
; #pragma unroll
;       for (int j = 0; j < 2; ++j) {
;         unsigned pk[4];
; #pragma unroll
;         for (int e = 0; e < 4; ++e) pk[e] = pack2(s[t2][8 * j + 2 * e], s[t2][8 * j + 2 * e + 1]);
;         u32x4 pku = {pk[0], pk[1], pk[2], pk[3]};
;         bf16x8 pf = __builtin_bit_cast(bf16x8, pku);
; #pragma unroll
;         for (int dt = 0; dt < 2; ++dt) {
;           const int vsw = (((dt * 32 + r) >> 3) & 7) << 3;
;           const bfr* vrow = sV + (dt * 32 + r) * 72;
;           s16x4 lo = *(const s16x4*)(vrow + ((t2 * 32 + 16 * j + 4 * h) ^ vsw));
;           s16x4 hi = *(const s16x4*)(vrow + ((t2 * 32 + 16 * j + 4 * h + 8) ^ vsw));
;           bf16x8 vf = __builtin_shufflevector(lo, hi, 0, 1, 2, 3, 4, 5, 6, 7);
;           accO[dt] = MFMA32(vf, pf, accO[dt]);
;         }
;       }
	ds_read_b64 v[142:143], v168 offset:9280
	ds_read_b64 v[144:145], v176 offset:9216
	ds_read_b64 v[146:147], v177 offset:9216
	ds_read_b64 v[148:149], v178 offset:9216
	ds_read_b64 v[156:157], v179 offset:9216
	ds_read_b64 v[158:159], v180 offset:9216
	ds_read_b64 v[164:165], v181 offset:9216
	ds_read_b64 v[166:167], v160 offset:9216
	v_add_f32_e32 v60, 0, v32
	v_exp_f32_e32 v50, v50
	v_add_f32_e32 v60, v48, v60
	v_exp_f32_e32 v35, v35
	v_add_f32_e32 v60, v33, v60
	v_exp_f32_e32 v51, v51
	v_add_f32_e32 v60, v49, v60
	v_add_f32_e32 v60, v34, v60
	v_exp_f32_e32 v36, v36
	v_add_f32_e32 v60, v50, v60
	v_add_f32_e32 v60, v35, v60
	v_exp_f32_e32 v37, v37
	v_add_f32_e32 v60, v51, v60
	v_add_f32_e32 v60, v122, v60
	v_add_f32_e32 v60, v36, v60
	v_add_f32_e32 v60, v123, v60
	v_add_f32_e32 v60, v37, v60
	v_add_f32_e32 v60, v124, v60
	v_exp_f32_e32 v38, v38
	v_add_f32_e32 v60, v52, v60
	v_exp_f32_e32 v55, v41
	v_sub_f32_e32 v39, v57, v119
	v_add_f32_e32 v60, v125, v60
	v_exp_f32_e32 v39, v39
	v_add_f32_e32 v60, v53, v60
	v_add_f32_e32 v60, v54, v60
	v_exp_f32_e32 v40, v40
	v_add_f32_e32 v60, v38, v60
	v_exp_f32_e32 v57, v43
	v_sub_f32_e32 v41, v59, v119
	v_add_f32_e32 v60, v55, v60
	v_exp_f32_e32 v41, v41
	v_add_f32_e32 v60, v39, v60
	v_add_f32_e32 v60, v56, v60
	v_exp_f32_e32 v42, v42
	v_add_f32_e32 v60, v40, v60
	v_exp_f32_e32 v59, v45
	v_sub_f32_e32 v43, v61, v119
	v_add_f32_e32 v60, v57, v60
	v_exp_f32_e32 v43, v43
	v_pk_add_f32 v[46:47], v[46:47], v[118:119] op_sel:[0,1] op_sel_hi:[1,1] neg_lo:[0,1] neg_hi:[0,1]
	v_add_f32_e32 v60, v41, v60
	v_exp_f32_e32 v46, v46
	v_pk_add_f32 v[62:63], v[62:63], v[118:119] op_sel:[0,1] op_sel_hi:[1,1] neg_lo:[0,1] neg_hi:[0,1]
	v_add_f32_e32 v60, v58, v60
	v_exp_f32_e32 v44, v62
	v_add_f32_e32 v60, v42, v60
	v_exp_f32_e32 v47, v47
	v_add_f32_e32 v60, v59, v60
	v_exp_f32_e32 v45, v63
	v_add_f32_e32 v60, v43, v60
	v_add_f32_e32 v60, v46, v60
	v_add_f32_e32 v60, v44, v60
	v_add_f32_e32 v60, v47, v60
	v_add_f32_e32 v113, v45, v60
	v_cvt_pk_bf16_f32 v32, v32, v33
	v_cvt_pk_bf16_f32 v33, v34, v35
	v_cvt_pk_bf16_f32 v34, v122, v123
	v_cvt_pk_bf16_f32 v35, v124, v125
	v_sub_f32_e32 v96, v96, v119
	v_exp_f32_e32 v96, v96
	s_nop 1
	v_pk_mul_f32 v[30:31], v[30:31], v[96:97] op_sel_hi:[1,0]
	v_pk_mul_f32 v[28:29], v[28:29], v[96:97] op_sel_hi:[1,0]
	v_pk_mul_f32 v[26:27], v[26:27], v[96:97] op_sel_hi:[1,0]
	v_pk_mul_f32 v[24:25], v[24:25], v[96:97] op_sel_hi:[1,0]
	v_pk_mul_f32 v[22:23], v[22:23], v[96:97] op_sel_hi:[1,0]
	v_pk_mul_f32 v[20:21], v[20:21], v[96:97] op_sel_hi:[1,0]
	v_pk_mul_f32 v[18:19], v[18:19], v[96:97] op_sel_hi:[1,0]
	v_pk_mul_f32 v[16:17], v[16:17], v[96:97] op_sel_hi:[1,0]
	v_pk_mul_f32 v[14:15], v[14:15], v[96:97] op_sel_hi:[1,0]
	v_pk_mul_f32 v[12:13], v[12:13], v[96:97] op_sel_hi:[1,0]
	s_waitcnt lgkmcnt(0)
	v_mfma_f32_32x32x16_bf16 v[16:31], v[126:129], v[32:35], v[16:31]
	v_mul_f32_e64 v10, v10, v96
	v_mul_f32_e64 v11, v11, v96
	v_pk_mul_f32 v[8:9], v[8:9], v[96:97] op_sel_hi:[1,0]
	v_pk_mul_f32 v[6:7], v[6:7], v[96:97] op_sel_hi:[1,0]
	v_pk_mul_f32 v[4:5], v[4:5], v[96:97] op_sel_hi:[1,0]
	v_pk_mul_f32 v[2:3], v[2:3], v[96:97] op_sel_hi:[1,0]
	v_pk_mul_f32 v[0:1], v[0:1], v[96:97] op_sel_hi:[1,0]
	v_fmac_f32_e32 v113, v120, v96
	s_nop 1
	v_mfma_f32_32x32x16_bf16 v[0:15], v[130:133], v[32:35], v[0:15]
	v_cvt_pk_bf16_f32 v32, v54, v55
	v_cvt_pk_bf16_f32 v33, v56, v57
	v_cvt_pk_bf16_f32 v34, v58, v59
	v_cvt_pk_bf16_f32 v35, v46, v47
	s_nop 1
	v_mfma_f32_32x32x16_bf16 v[16:31], v[134:137], v[32:35], v[16:31]
	s_nop 1
	v_mfma_f32_32x32x16_bf16 v[0:15], v[138:141], v[32:35], v[0:15]
	v_cvt_pk_bf16_f32 v32, v48, v49
	v_cvt_pk_bf16_f32 v33, v50, v51
	v_cvt_pk_bf16_f32 v34, v36, v37
	v_cvt_pk_bf16_f32 v35, v52, v53
	s_nop 1
	v_mfma_f32_32x32x16_bf16 v[16:31], v[142:145], v[32:35], v[16:31]
	s_nop 1
	v_mfma_f32_32x32x16_bf16 v[0:15], v[146:149], v[32:35], v[0:15]
	v_cvt_pk_bf16_f32 v32, v38, v39
	v_cvt_pk_bf16_f32 v33, v40, v41
	v_cvt_pk_bf16_f32 v34, v42, v43
	v_cvt_pk_bf16_f32 v35, v44, v45
	s_nop 1
	v_mfma_f32_32x32x16_bf16 v[16:31], v[156:159], v[32:35], v[16:31]
	s_nop 1
	v_mfma_f32_32x32x16_bf16 v[0:15], v[164:167], v[32:35], v[0:15]
	s_cbranch_scc1 .LBB0_412
	v_add3_u32 v32, 0, v115, v90
	s_waitcnt vmcnt(1)
	ds_write_b128 v32, v[84:87] offset:18432
	v_add3_u32 v32, 0, v117, v118
	v_add3_u32 v33, 0, v118, v117
	s_waitcnt vmcnt(0)
	ds_write_b16 v32, v80 offset:27648
	ds_write_b16_d16_hi v33, v80 offset:27792
	ds_write_b16 v32, v81 offset:27936
	ds_write_b16_d16_hi v33, v81 offset:28080
	ds_write_b16 v32, v82 offset:28224
	ds_write_b16_d16_hi v33, v82 offset:28368
	ds_write_b16 v32, v83 offset:28512
	ds_write_b16_d16_hi v33, v83 offset:28656
	v_add_u32_e32 v80, 0, v114
	v_add_u32_e32 v81, v80, v152
	s_waitcnt lgkmcnt(0)
	s_barrier
; #define MFMA32(a, b, c) __builtin_amdgcn_mfma_f32_32x32x16_bf16((a), (b), (c), 0, 0, 0)
; template <int D>
; DI void attn_pass(const bfr* __restrict__ P, int b, int tq_wave, int qcol, int kcol, int vcol, int key0, int nkt, char* smem, f32x16 (&o)[2]) {
;     ...
;     __syncthreads();
;     if (kt + 1 < nkt) {
;       const bfr* Pn = Pb + (size_t)(kt + 1) * 64 * PW;
;       { int c = gt, row = c >> 3, kc = c & 7; kreg[0] = *(const u32x4*)(Pn + (size_t)row * PW + kcol + kc * 8); vreg[0] = *(const u32x4*)(Pn + (size_t)row * PW + vcol + kc * 8); }
;     }
;     f32x16 s[2];
; #pragma unroll
;     for (int t2 = 0; t2 < 2; ++t2) {
; #pragma unroll
;       for (int i = 0; i < 16; ++i) s[t2][i] = 0.f;
; #pragma unroll
;       for (int ks = 0; ks < KS; ++ks) {
;         bf16x8 a = *(const bf16x8*)(sK + (t2 * 32 + r) * KP + ks * 16 + h * 8);
;         s[t2] = MFMA32(a, qf[ks], s[t2]);
;       }
;     }
;     float mx = s[0][0];
; #pragma unroll
;     for (int i = 0; i < 16; ++i) { mx = fmaxf(mx, s[0][i]); mx = fmaxf(mx, s[1][i]); }
;     mx = fmaxf(mx, __shfl_xor(mx, 32));
;     float mnew = fmaxf(mrun, mx);
;     float alpha = __builtin_amdgcn_exp2f(mrun - mnew);
;     mrun = mnew;
;     float ps = 0.f;
; #pragma unroll
;     for (int i = 0; i < 16; ++i) {
;       s[0][i] = __builtin_amdgcn_exp2f(s[0][i] - mnew); ps += s[0][i];
;       s[1][i] = __builtin_amdgcn_exp2f(s[1][i] - mnew); ps += s[1][i];
;     }
;     lsum = lsum * alpha + ps;
; #pragma unroll
;     for (int i = 0; i < 16; ++i) { accO[0][i] *= alpha; accO[1][i] *= alpha; }
	ds_read_b128 v[32:35], v81 offset:18432
	ds_read_b128 v[48:51], v81 offset:18464
	s_waitcnt lgkmcnt(1)
	v_mfma_f32_32x32x16_bf16 v[32:47], v[32:35], v[76:79], 0
	v_lshlrev_b32_e32 v152, 1, v88
	s_waitcnt lgkmcnt(0)
	v_mfma_f32_32x32x16_bf16 v[32:47], v[48:51], v[72:75], v[32:47]
	ds_read_b128 v[48:51], v81 offset:18496
	s_waitcnt lgkmcnt(0)
	v_mfma_f32_32x32x16_bf16 v[32:47], v[48:51], v[68:71], v[32:47]
	ds_read_b128 v[48:51], v81 offset:18528
	s_waitcnt lgkmcnt(0)
	v_mfma_f32_32x32x16_bf16 v[32:47], v[48:51], v[64:67], v[32:47]
	ds_read_b128 v[48:51], v81 offset:23040
	s_waitcnt lgkmcnt(0)
	v_mfma_f32_32x32x16_bf16 v[48:63], v[48:51], v[76:79], 0
	ds_read_b128 v[76:79], v81 offset:23072
	s_waitcnt lgkmcnt(0)
	v_mfma_f32_32x32x16_bf16 v[48:63], v[76:79], v[72:75], v[48:63]
	ds_read_b128 v[72:75], v81 offset:23104
	s_waitcnt lgkmcnt(0)
	v_mfma_f32_32x32x16_bf16 v[48:63], v[72:75], v[68:71], v[48:63]
	ds_read_b128 v[68:71], v81 offset:23136
	s_waitcnt lgkmcnt(0)
	v_mfma_f32_32x32x16_bf16 v[48:63], v[68:71], v[64:67], v[48:63]
	v_max_f32_e32 v65, v32, v32
	v_lshl_add_u32 v66, v112, 1, v80
	v_add_u32_e32 v67, 0x1200, v80
	s_nop 8
	v_max_f32_e32 v64, v48, v48
	v_max_f32_e32 v64, v65, v64
	v_max3_f32 v64, v64, v33, v49
	v_max3_f32 v64, v64, v34, v50
	v_max3_f32 v64, v64, v35, v51
	v_max3_f32 v64, v64, v36, v52
	v_max3_f32 v64, v64, v37, v53
	v_max3_f32 v64, v64, v38, v54
	v_max3_f32 v64, v64, v39, v55
	v_max3_f32 v64, v64, v40, v56
	v_max3_f32 v64, v64, v41, v57
	v_max3_f32 v64, v64, v42, v58
	v_max3_f32 v64, v64, v43, v59
	v_max3_f32 v64, v64, v44, v60
	v_max3_f32 v64, v64, v45, v61
	v_max3_f32 v64, v64, v46, v62
	v_max3_f32 v64, v64, v47, v63
	ds_bpermute_b32 v65, v91, v64
	s_waitcnt lgkmcnt(0)
	v_max3_f32 v65, v119, v64, v65
	v_sub_f32_e32 v64, v119, v65
	v_sub_f32_e32 v32, v32, v65
	v_exp_f32_e32 v64, v64
	v_exp_f32_e32 v32, v32
	v_sub_f32_e32 v48, v48, v65
	v_exp_f32_e32 v48, v48
	v_sub_f32_e32 v33, v33, v65
	v_exp_f32_e32 v33, v33
	v_sub_f32_e32 v49, v49, v65
	v_exp_f32_e32 v49, v49
	v_sub_f32_e32 v34, v34, v65
	v_exp_f32_e32 v34, v34
	v_sub_f32_e32 v50, v50, v65
	v_sub_f32_e32 v35, v35, v65
	v_sub_f32_e32 v51, v51, v65
	v_sub_f32_e32 v36, v36, v65
	v_sub_f32_e32 v52, v52, v65
	v_sub_f32_e32 v37, v37, v65
	v_sub_f32_e32 v53, v53, v65
	v_sub_f32_e32 v38, v38, v65
	v_sub_f32_e32 v54, v54, v65
	v_sub_f32_e32 v39, v39, v65
	v_sub_f32_e32 v55, v55, v65
	v_sub_f32_e32 v40, v40, v65
	v_sub_f32_e32 v56, v56, v65
	v_sub_f32_e32 v41, v41, v65
	v_sub_f32_e32 v57, v57, v65
	v_sub_f32_e32 v42, v42, v65
	v_sub_f32_e32 v58, v58, v65
	v_sub_f32_e32 v43, v43, v65
	v_sub_f32_e32 v59, v59, v65
	v_sub_f32_e32 v44, v44, v65
	v_sub_f32_e32 v60, v60, v65
	v_sub_f32_e32 v45, v45, v65
	v_sub_f32_e32 v61, v61, v65
	v_sub_f32_e32 v46, v46, v65
	v_sub_f32_e32 v62, v62, v65
	v_sub_f32_e32 v47, v47, v65
	v_sub_f32_e32 v63, v63, v65
	v_pk_mul_f32 v[30:31], v[30:31], v[64:65] op_sel_hi:[1,0]
	v_pk_mul_f32 v[28:29], v[28:29], v[64:65] op_sel_hi:[1,0]
	v_pk_mul_f32 v[26:27], v[26:27], v[64:65] op_sel_hi:[1,0]
	v_pk_mul_f32 v[24:25], v[24:25], v[64:65] op_sel_hi:[1,0]
	v_pk_mul_f32 v[22:23], v[22:23], v[64:65] op_sel_hi:[1,0]
	v_pk_mul_f32 v[20:21], v[20:21], v[64:65] op_sel_hi:[1,0]
	v_pk_mul_f32 v[18:19], v[18:19], v[64:65] op_sel_hi:[1,0]
	v_pk_mul_f32 v[16:17], v[16:17], v[64:65] op_sel_hi:[1,0]
	v_pk_mul_f32 v[14:15], v[14:15], v[64:65] op_sel_hi:[1,0]
	v_pk_mul_f32 v[12:13], v[12:13], v[64:65] op_sel_hi:[1,0]
	v_pk_mul_f32 v[10:11], v[10:11], v[64:65] op_sel_hi:[1,0]
	v_pk_mul_f32 v[8:9], v[8:9], v[64:65] op_sel_hi:[1,0]
	v_pk_mul_f32 v[6:7], v[6:7], v[64:65] op_sel_hi:[1,0]
	v_pk_mul_f32 v[4:5], v[4:5], v[64:65] op_sel_hi:[1,0]
	v_pk_mul_f32 v[2:3], v[2:3], v[64:65] op_sel_hi:[1,0]
	v_pk_mul_f32 v[0:1], v[0:1], v[64:65] op_sel_hi:[1,0]
	v_add_f32_e32 v65, 0, v32
	v_exp_f32_e32 v50, v50
	v_add_f32_e32 v65, v48, v65
	v_exp_f32_e32 v35, v35
	v_add_f32_e32 v65, v33, v65
	v_exp_f32_e32 v51, v51
	v_add_f32_e32 v65, v49, v65
	v_exp_f32_e32 v36, v36
	v_add_f32_e32 v65, v34, v65
	v_exp_f32_e32 v52, v52
	v_add_f32_e32 v65, v50, v65
	v_exp_f32_e32 v37, v37
	v_add_f32_e32 v65, v35, v65
	v_exp_f32_e32 v53, v53
	v_add_f32_e32 v65, v51, v65
	v_exp_f32_e32 v38, v38
	v_add_f32_e32 v65, v36, v65
	v_exp_f32_e32 v54, v54
	v_add_f32_e32 v65, v52, v65
	v_exp_f32_e32 v39, v39
	v_add_f32_e32 v65, v37, v65
	v_add_f32_e32 v65, v53, v65
	v_add_f32_e32 v65, v38, v65
	v_add_f32_e32 v65, v54, v65
	v_cvt_pk_bf16_f32 v32, v32, v33
	v_cvt_pk_bf16_f32 v33, v34, v35
	v_cvt_pk_bf16_f32 v34, v36, v37
	v_cvt_pk_bf16_f32 v35, v38, v39
	v_lshl_add_u32 v38, v111, 1, v80
	v_add_f32_e32 v65, v39, v65
	ds_read_b64 v[36:37], v66 offset:27648
	ds_read_b64 v[38:39], v38 offset:27648
	s_waitcnt lgkmcnt(0)
	v_mfma_f32_32x32x16_bf16 v[16:31], v[36:39], v[32:35], v[16:31]
	v_lshl_add_u32 v36, v110, 1, v67
	v_lshl_add_u32 v38, v109, 1, v67
	ds_read_b64 v[36:37], v36 offset:27648
	ds_read_b64 v[38:39], v38 offset:27648
	v_exp_f32_e32 v40, v40
	v_exp_f32_e32 v41, v41
	v_exp_f32_e32 v42, v42
	s_waitcnt lgkmcnt(0)
; #define MFMA32(a, b, c) __builtin_amdgcn_mfma_f32_32x32x16_bf16((a), (b), (c), 0, 0, 0)
; DI unsigned pack2(float a, float b) { unsigned r; asm volatile("v_cvt_pk_bf16_f32 %0, %1, %2" : "=v"(r) : "v"(a), "v"(b)); return r; }
; template <int D>
; DI void attn_pass(const bfr* __restrict__ P, int b, int tq_wave, int qcol, int kcol, int vcol, int key0, int nkt, char* smem, f32x16 (&o)[2]) {
;     ...
; #pragma unroll
;     for (int t2 = 0; t2 < 2; ++t2)
; #pragma unroll
;       for (int j = 0; j < 2; ++j) {
;         unsigned pk[4];
; #pragma unroll
;         for (int e = 0; e < 4; ++e) pk[e] = pack2(s[t2][8 * j + 2 * e], s[t2][8 * j + 2 * e + 1]);
;         u32x4 pku = {pk[0], pk[1], pk[2], pk[3]};
;         bf16x8 pf = __builtin_bit_cast(bf16x8, pku);
; #pragma unroll
;         for (int dt = 0; dt < 2; ++dt) {
;           const int vsw = (((dt * 32 + r) >> 3) & 7) << 3;
;           const bfr* vrow = sV + (dt * 32 + r) * 72;
;           s16x4 lo = *(const s16x4*)(vrow + ((t2 * 32 + 16 * j + 4 * h) ^ vsw));
;           s16x4 hi = *(const s16x4*)(vrow + ((t2 * 32 + 16 * j + 4 * h + 8) ^ vsw));
;           bf16x8 vf = __builtin_shufflevector(lo, hi, 0, 1, 2, 3, 4, 5, 6, 7);
;           accO[dt] = MFMA32(vf, pf, accO[dt]);
;         }
;       }
;   }
;   lsum += __shfl_xor(lsum, 32);
;   float inv = 1.f / lsum;
; #pragma unroll
;   for (int i = 0; i < 16; ++i) { o[0][i] = accO[0][i] * inv; o[1][i] = accO[1][i] * inv; }
; }
; DI void attn_pass_da(const bfr* __restrict__ P, int b, int tq_wave, int qcol, int kcol, int vcol, int key0, int nkt, char* smem, f32x16 (&o0)[2], f32x16 (&o1)[2]) {
;   constexpr int KP = 72;
;   bfr* sbase = (bfr*)dynlds;
; DI void store_o(bfr* O, int m, int colbase, int h, const f32x16 (&o)[2]) {
; #pragma unroll
;   for (int dt = 0; dt < 2; ++dt)
; #pragma unroll
;     for (int g4 = 0; g4 < 4; ++g4) {
;       int dv = dt * 32 + 8 * g4 + 4 * h;
;       uint2 pk; pk.x = pack2(o[dt][4 * g4], o[dt][4 * g4 + 1]); pk.y = pack2(o[dt][4 * g4 + 2], o[dt][4 * g4 + 3]);
;       *(uint2*)(O + (size_t)m * DM + colbase + dv) = pk;
;     }
; }
	v_mfma_f32_32x32x16_bf16 v[0:15], v[36:39], v[32:35], v[0:15]
	v_lshl_add_u32 v36, v108, 1, v80
	v_lshl_add_u32 v38, v107, 1, v80
	v_exp_f32_e32 v43, v43
	v_exp_f32_e32 v44, v44
	v_exp_f32_e32 v45, v45
	v_exp_f32_e32 v46, v46
	v_exp_f32_e32 v47, v47
	v_cvt_pk_bf16_f32 v32, v40, v41
	v_cvt_pk_bf16_f32 v33, v42, v43
	v_cvt_pk_bf16_f32 v34, v44, v45
	v_cvt_pk_bf16_f32 v35, v46, v47
	ds_read_b64 v[36:37], v36 offset:27648
	ds_read_b64 v[38:39], v38 offset:27648
	s_waitcnt lgkmcnt(0)
	v_mfma_f32_32x32x16_bf16 v[16:31], v[36:39], v[32:35], v[16:31]
	v_lshl_add_u32 v36, v106, 1, v67
	v_lshl_add_u32 v38, v105, 1, v67
	ds_read_b64 v[36:37], v36 offset:27648
	ds_read_b64 v[38:39], v38 offset:27648
	v_exp_f32_e32 v55, v55
	v_exp_f32_e32 v56, v56
	v_exp_f32_e32 v57, v57
	s_waitcnt lgkmcnt(0)
	v_mfma_f32_32x32x16_bf16 v[0:15], v[36:39], v[32:35], v[0:15]
	v_lshl_add_u32 v38, v104, 1, v80
	v_cvt_pk_bf16_f32 v32, v48, v49
	v_cvt_pk_bf16_f32 v33, v50, v51
	v_cvt_pk_bf16_f32 v34, v52, v53
	v_cvt_pk_bf16_f32 v35, v54, v55
	ds_read_b64 v[36:37], v66 offset:27712
	ds_read_b64 v[38:39], v38 offset:27648
	s_waitcnt lgkmcnt(0)
	v_mfma_f32_32x32x16_bf16 v[16:31], v[36:39], v[32:35], v[16:31]
	v_lshl_add_u32 v36, v103, 1, v67
	v_lshl_add_u32 v38, v102, 1, v67
	ds_read_b64 v[36:37], v36 offset:27648
	ds_read_b64 v[38:39], v38 offset:27648
	v_exp_f32_e32 v58, v58
	v_exp_f32_e32 v59, v59
	v_exp_f32_e32 v60, v60
	s_waitcnt lgkmcnt(0)
	v_mfma_f32_32x32x16_bf16 v[0:15], v[36:39], v[32:35], v[0:15]
	v_lshl_add_u32 v36, v100, 1, v80
	v_lshl_add_u32 v38, v101, 1, v80
	v_exp_f32_e32 v61, v61
	v_exp_f32_e32 v62, v62
	v_exp_f32_e32 v63, v63
	v_cvt_pk_bf16_f32 v32, v56, v57
	v_cvt_pk_bf16_f32 v33, v58, v59
	v_cvt_pk_bf16_f32 v34, v60, v61
	v_cvt_pk_bf16_f32 v35, v62, v63
	ds_read_b64 v[36:37], v36 offset:27648
	ds_read_b64 v[38:39], v38 offset:27648
	v_add_f32_e32 v65, v55, v65
	v_add_f32_e32 v65, v40, v65
	v_add_f32_e32 v65, v56, v65
	v_add_f32_e32 v65, v41, v65
	v_add_f32_e32 v65, v57, v65
	v_add_f32_e32 v65, v42, v65
	v_add_f32_e32 v65, v58, v65
	v_add_f32_e32 v65, v43, v65
	v_add_f32_e32 v65, v59, v65
	s_waitcnt lgkmcnt(0)
	v_mfma_f32_32x32x16_bf16 v[16:31], v[36:39], v[32:35], v[16:31]
	v_lshl_add_u32 v36, v99, 1, v67
	v_lshl_add_u32 v38, v98, 1, v67
	v_add_f32_e32 v65, v44, v65
	ds_read_b64 v[36:37], v36 offset:27648
	ds_read_b64 v[38:39], v38 offset:27648
	v_add_f32_e32 v65, v60, v65
	v_add_f32_e32 v65, v45, v65
	v_add_f32_e32 v65, v61, v65
	v_add_f32_e32 v65, v46, v65
	v_add_f32_e32 v65, v62, v65
	v_add_f32_e32 v65, v47, v65
	v_add_f32_e32 v65, v63, v65
	v_fmac_f32_e32 v65, v113, v64
	s_waitcnt lgkmcnt(0)
	v_mfma_f32_32x32x16_bf16 v[0:15], v[36:39], v[32:35], v[0:15]
	ds_bpermute_b32 v32, v91, v65
	s_waitcnt lgkmcnt(0)
	v_add_f32_e32 v32, v65, v32
	v_div_scale_f32 v33, s[8:9], v32, v32, 1.0
	v_rcp_f32_e32 v34, v33
	s_load_dwordx4 s[8:11], s[0:1], 0x100
	s_waitcnt lgkmcnt(0)
	s_mov_b64 s[8:9], 0x2b7c700
	v_fma_f32 v35, -v33, v34, 1.0
	v_fmac_f32_e32 v34, v35, v34
	v_div_scale_f32 v35, vcc, 1.0, v32, 1.0
	v_mul_f32_e32 v36, v35, v34
	v_fma_f32 v37, -v33, v36, v35
	v_fmac_f32_e32 v36, v37, v34
	v_fma_f32 v33, -v33, v36, v35
	v_div_fmas_f32 v33, v33, v34, v36
	v_div_fixup_f32 v32, v33, v32, 1.0
	v_mul_f32_e32 v33, v0, v32
	v_and_or_b32 v0, v89, 31, v97
	v_mul_f32_e32 v34, v1, v32
	v_ashrrev_i32_e32 v1, 31, v0
	v_lshlrev_b64 v[0:1], 11, v[0:1]
	v_mul_f32_e32 v37, v4, v32
	v_lshl_add_u64 v[0:1], s[10:11], 0, v[0:1]
	v_lshrrev_b32_e32 v4, 2, v89
	v_lshl_add_u64 v[0:1], v[0:1], 0, v[152:153]
	v_and_b32_e32 v152, 8, v4
	v_lshl_add_u64 v[0:1], v[0:1], 0, v[152:153]
	v_mul_f32_e32 v38, v5, v32
	v_lshl_add_u64 v[4:5], v[0:1], 0, s[8:9]
	s_mov_b32 s8, 0x2b7c000
	v_add_co_u32_e32 v0, vcc, s8, v0
	v_mul_f32_e32 v16, v16, v32
	s_nop 0
	v_addc_co_u32_e32 v1, vcc, 0, v1, vcc
	v_mul_f32_e32 v17, v17, v32
	v_mul_f32_e32 v18, v18, v32
	v_mul_f32_e32 v35, v2, v32
	v_mul_f32_e32 v19, v19, v32
	v_mul_f32_e32 v36, v3, v32
	v_mul_f32_e32 v20, v20, v32
	v_mul_f32_e32 v21, v21, v32
	v_mul_f32_e32 v22, v22, v32
	v_mul_f32_e32 v23, v23, v32
	v_cvt_pk_bf16_f32 v2, v16, v17
	v_cvt_pk_bf16_f32 v3, v18, v19
	global_store_dwordx2 v[0:1], v[2:3], off offset:1792
	v_cvt_pk_bf16_f32 v0, v20, v21
	v_cvt_pk_bf16_f32 v1, v22, v23
	v_mul_f32_e32 v24, v24, v32
	v_mul_f32_e32 v25, v25, v32
	v_mul_f32_e32 v26, v26, v32
	v_mul_f32_e32 v27, v27, v32
	global_store_dwordx2 v[4:5], v[0:1], off offset:16
	v_cvt_pk_bf16_f32 v0, v24, v25
	v_cvt_pk_bf16_f32 v1, v26, v27
	v_mul_f32_e32 v28, v28, v32
	v_mul_f32_e32 v29, v29, v32
	v_mul_f32_e32 v30, v30, v32
	v_mul_f32_e32 v31, v31, v32
	global_store_dwordx2 v[4:5], v[0:1], off offset:32
	v_cvt_pk_bf16_f32 v0, v28, v29
	v_cvt_pk_bf16_f32 v1, v30, v31
	global_store_dwordx2 v[4:5], v[0:1], off offset:48
	v_cvt_pk_bf16_f32 v0, v33, v34
	v_cvt_pk_bf16_f32 v1, v35, v36
	v_mul_f32_e32 v6, v6, v32
	v_mul_f32_e32 v7, v7, v32
	global_store_dwordx2 v[4:5], v[0:1], off offset:64
	v_cvt_pk_bf16_f32 v0, v37, v38
	v_cvt_pk_bf16_f32 v1, v6, v7
	v_mul_f32_e32 v8, v8, v32
	v_mul_f32_e32 v9, v9, v32
	v_mul_f32_e32 v10, v10, v32
	v_mul_f32_e32 v11, v11, v32
	global_store_dwordx2 v[4:5], v[0:1], off offset:80
	v_cvt_pk_bf16_f32 v0, v8, v9
	v_cvt_pk_bf16_f32 v1, v10, v11
	v_mul_f32_e32 v12, v12, v32
	v_mul_f32_e32 v13, v13, v32
	v_mul_f32_e32 v14, v14, v32
	v_mul_f32_e32 v15, v15, v32
	global_store_dwordx2 v[4:5], v[0:1], off offset:96
	v_cvt_pk_bf16_f32 v0, v12, v13
	v_cvt_pk_bf16_f32 v1, v14, v15
	global_store_dwordx2 v[4:5], v[0:1], off offset:112

; DI void attn_pass_da(const bfr* __restrict__ P, int b, int tq_wave, int qcol, int kcol, int vcol, int key0, int nkt, char* smem, f32x16 (&o0)[2], f32x16 (&o1)[2]) {
;     ...
;   for (int kt = 0; kt < nkt; ++kt) {
;     bfr* sK = sbase + (kt & 1) * 9216;
;     bfr* sV = sK + 64 * 72;
;     { int c = gt, row = c >> 3, kc = c & 7; *(u32x4*)(sK + row * KP + kc * 8) = kreg[0]; }
;     for (int i = 0; i < 1; ++i) {
;       int c = gt, row = c >> 3, kc = c & 7;
;       unsigned wds[4] = {vreg[i].x, vreg[i].y, vreg[i].z, vreg[i].w};
; #pragma unroll
;       for (int e = 0; e < 4; ++e) {
;         sV[(kc * 8 + 2 * e) * 72 + (row ^ (kc << 3))] = (bfr)(wds[e] & 0xffffu);
;         sV[(kc * 8 + 2 * e + 1) * 72 + (row ^ (kc << 3))] = (bfr)(wds[e] >> 16);
;       }
;     }
;     __syncthreads();
;     if (kt + 1 < nkt) {
;       const bfr* Pn = Pb + (size_t)(kt + 1) * 64 * PW;
;       { int c = gt, row = c >> 3, kc = c & 7; kreg[0] = *(const u32x4*)(Pn + (size_t)row * PW + kcol + kc * 8); vreg[0] = *(const u32x4*)(Pn + (size_t)row * PW + vcol + kc * 8); }
;     }
;     f32x16 s0[2], s1[2];
; #pragma unroll
;     for (int t2 = 0; t2 < 2; ++t2) {
; #pragma unroll
;       for (int i = 0; i < 16; ++i) { s0[t2][i] = 0.f; s1[t2][i] = 0.f; }
; #pragma unroll
;       for (int ks = 0; ks < 2; ++ks) {
;         bf16x8 a0 = *(const bf16x8*)(sK + (t2 * 32 + r) * KP + ks * 16 + h * 8);
;         bf16x8 a1 = *(const bf16x8*)(sK + (t2 * 32 + r) * KP + 32 + ks * 16 + h * 8);
;         s0[t2] = MFMA32(a0, qf[ks], s0[t2]);
;         s1[t2] = MFMA32(a1, qf[2 + ks], s1[t2]);
;       }
;     }
;     float mx0 = s0[0][0], mx1 = s1[0][0];
; #pragma unroll
;     for (int i = 0; i < 16; ++i) { mx0 = fmaxf(mx0, fmaxf(s0[0][i], s0[1][i])); mx1 = fmaxf(mx1, fmaxf(s1[0][i], s1[1][i])); }
;     mx0 = fmaxf(mx0, __shfl_xor(mx0, 32)); mx1 = fmaxf(mx1, __shfl_xor(mx1, 32));
;     const float mn0 = fmaxf(m0, mx0), mn1 = fmaxf(m1, mx1);
;     const float al0 = __builtin_amdgcn_exp2f(m0 - mn0), al1 = __builtin_amdgcn_exp2f(m1 - mn1);
;     m0 = mn0; m1 = mn1;
;     float ps0 = 0.f, ps1 = 0.f;
; #pragma unroll
;     for (int i = 0; i < 16; ++i) {
;       s0[0][i] = __builtin_amdgcn_exp2f(s0[0][i] - mn0); ps0 += s0[0][i];
;       s0[1][i] = __builtin_amdgcn_exp2f(s0[1][i] - mn0); ps0 += s0[1][i];
;       s1[0][i] = __builtin_amdgcn_exp2f(s1[0][i] - mn1); ps1 += s1[0][i];
.LBB0_421:
	s_bitcmp1_b32 s10, 0
	s_cselect_b32 s11, 0x4800, 0
	s_add_i32 s11, s11, 0
	v_add3_u32 v64, s11, v206, v152
	v_add_u32_e32 v194, s11, v205
	s_waitcnt vmcnt(1)
	ds_write_b128 v64, v[148:151]
	v_add3_u32 v64, s11, v207, v208
	v_add3_u32 v65, s11, v208, v207
	v_add_u32_e32 v100, v194, v204
	s_waitcnt vmcnt(0)
	ds_write_b16 v64, v144 offset:9216
	ds_write_b16_d16_hi v65, v144 offset:9360
	ds_write_b16 v64, v145 offset:9504
	ds_write_b16_d16_hi v65, v145 offset:9648
	ds_write_b16 v64, v146 offset:9792
	ds_write_b16_d16_hi v65, v146 offset:9936
	ds_write_b16 v64, v147 offset:10080
	ds_write_b16_d16_hi v65, v147 offset:10224
	s_waitcnt lgkmcnt(0)
	s_barrier
	global_load_dwordx4 v[148:151], v[158:159], off
	global_load_dwordx4 v[144:147], v[158:159], off offset:512
	ds_read_b128 v[64:67], v100 offset:64
	ds_read_b128 v[68:71], v100
	ds_read_b128 v[96:99], v100 offset:32
	ds_read_b128 v[100:103], v100 offset:96
	s_waitcnt lgkmcnt(2)
	v_mfma_f32_32x32x16_bf16 v[80:95], v[68:71], v[140:143], 0
	v_add_u32_e32 v195, s11, v211
	v_add_u32_e32 v192, v195, v204
	v_mov_b32_e32 v160, v209
	v_mov_b32_e32 v161, v210
	s_add_i32 s10, s10, 1
	v_lshl_add_u64 v[158:159], v[158:159], 0, s[12:13]
	s_cmp_lg_u32 s10, 35
	v_mfma_f32_32x32x16_bf16 v[64:79], v[64:67], v[136:139], 0
	s_waitcnt lgkmcnt(1)
	v_mfma_f32_32x32x16_bf16 v[80:95], v[96:99], v[132:135], v[80:95]
	s_waitcnt lgkmcnt(0)
	v_mfma_f32_32x32x16_bf16 v[64:79], v[100:103], v[128:131], v[64:79]
	ds_read_b128 v[96:99], v192 offset:64
	ds_read_b128 v[100:103], v192
	ds_read_b128 v[212:215], v192 offset:32
	ds_read_b128 v[216:219], v192 offset:96
	s_nop 5
	v_max3_f32 v209, v80, v81, v82
	v_max3_f32 v209, v209, v83, v84
	v_max3_f32 v193, v64, v65, v66
	s_waitcnt lgkmcnt(2)
	v_mfma_f32_32x32x16_bf16 v[112:127], v[100:103], v[140:143], 0
	v_mfma_f32_32x32x16_bf16 v[96:111], v[96:99], v[136:139], 0
	s_waitcnt lgkmcnt(1)
	v_mfma_f32_32x32x16_bf16 v[112:127], v[212:215], v[132:135], v[112:127]
	v_max3_f32 v193, v193, v67, v68
	v_max3_f32 v209, v209, v85, v86
	s_waitcnt lgkmcnt(0)
	v_mfma_f32_32x32x16_bf16 v[96:111], v[216:219], v[128:131], v[96:111]
	v_max3_f32 v193, v193, v69, v70
	v_max3_f32 v209, v209, v87, v88
	v_max3_f32 v193, v193, v71, v72
	v_max3_f32 v209, v209, v89, v90
	v_max3_f32 v193, v193, v73, v74
	v_max3_f32 v209, v209, v91, v92
	v_max3_f32 v193, v193, v75, v76
	v_max3_f32 v209, v209, v93, v94
	v_max3_f32 v193, v193, v77, v78
	v_max3_f32 v209, v209, v95, v112
	v_max3_f32 v209, v209, v113, v114
	v_max3_f32 v209, v209, v115, v116
	v_max3_f32 v209, v209, v117, v118
	v_max3_f32 v209, v209, v119, v120
	v_max3_f32 v209, v209, v121, v122
	v_max3_f32 v209, v209, v123, v124
	v_max3_f32 v209, v209, v125, v126
	v_max_f32_e32 v192, v209, v127
	v_max3_f32 v193, v193, v79, v96
	v_max3_f32 v193, v193, v97, v98
	v_max3_f32 v193, v193, v99, v100
	v_max3_f32 v193, v193, v101, v102
	v_max3_f32 v193, v193, v103, v104
	v_max3_f32 v193, v193, v105, v106
	v_max3_f32 v193, v193, v107, v108
	v_max3_f32 v193, v193, v109, v110
	v_max_f32_e32 v193, v193, v111
	v_mov_b32_e32 v210, v193
	v_mov_b32_e32 v209, v192
	s_nop 1
	v_permlane32_swap_b32_e32 v193, v210
	v_permlane32_swap_b32_e32 v192, v209
	s_waitcnt lgkmcnt(1)
	v_max3_f32 v210, v161, v193, v210
	s_waitcnt lgkmcnt(0)
	v_max3_f32 v209, v160, v192, v209
	v_pk_add_f32 v[64:65], v[64:65], v[210:211] op_sel_hi:[1,0] neg_lo:[0,1] neg_hi:[0,1]
	v_pk_add_f32 v[80:81], v[80:81], v[208:209] op_sel:[0,1] op_sel_hi:[1,1] neg_lo:[0,1] neg_hi:[0,1]
	v_exp_f32_e32 v193, v64
	v_pk_add_f32 v[96:97], v[96:97], v[210:211] op_sel_hi:[1,0] neg_lo:[0,1] neg_hi:[0,1]
	v_exp_f32_e32 v192, v80
	v_pk_add_f32 v[112:113], v[112:113], v[208:209] op_sel:[0,1] op_sel_hi:[1,1] neg_lo:[0,1] neg_hi:[0,1]
	v_exp_f32_e32 v213, v96
	v_exp_f32_e32 v212, v112
	v_exp_f32_e32 v80, v81
	v_exp_f32_e32 v96, v113
	v_exp_f32_e32 v81, v65
	v_exp_f32_e32 v97, v97
	v_pk_add_f32 v[82:83], v[82:83], v[208:209] op_sel:[0,1] op_sel_hi:[1,1] neg_lo:[0,1] neg_hi:[0,1]
	v_exp_f32_e32 v112, v82
	v_pk_add_f32 v[114:115], v[114:115], v[208:209] op_sel:[0,1] op_sel_hi:[1,1] neg_lo:[0,1] neg_hi:[0,1]
	v_exp_f32_e32 v214, v114
	v_pk_add_f32 v[66:67], v[66:67], v[210:211] op_sel_hi:[1,0] neg_lo:[0,1] neg_hi:[0,1]
	v_exp_f32_e32 v113, v66
	v_pk_add_f32 v[98:99], v[98:99], v[210:211] op_sel_hi:[1,0] neg_lo:[0,1] neg_hi:[0,1]
	v_exp_f32_e32 v215, v98
	v_exp_f32_e32 v82, v83
	v_exp_f32_e32 v98, v115
	v_exp_f32_e32 v83, v67
	v_exp_f32_e32 v99, v99
	v_pk_add_f32 v[84:85], v[84:85], v[208:209] op_sel:[0,1] op_sel_hi:[1,1] neg_lo:[0,1] neg_hi:[0,1]
	v_exp_f32_e32 v114, v84
	v_pk_add_f32 v[116:117], v[116:117], v[208:209] op_sel:[0,1] op_sel_hi:[1,1] neg_lo:[0,1] neg_hi:[0,1]
	v_exp_f32_e32 v216, v116
	v_pk_add_f32 v[68:69], v[68:69], v[210:211] op_sel_hi:[1,0] neg_lo:[0,1] neg_hi:[0,1]
	v_exp_f32_e32 v115, v68
	v_pk_add_f32 v[100:101], v[100:101], v[210:211] op_sel_hi:[1,0] neg_lo:[0,1] neg_hi:[0,1]
	v_exp_f32_e32 v217, v100
	v_exp_f32_e32 v84, v85
	v_exp_f32_e32 v100, v117
	v_exp_f32_e32 v85, v69
	v_exp_f32_e32 v101, v101
	v_pk_add_f32 v[86:87], v[86:87], v[208:209] op_sel:[0,1] op_sel_hi:[1,1] neg_lo:[0,1] neg_hi:[0,1]
	v_exp_f32_e32 v116, v86
	v_pk_add_f32 v[118:119], v[118:119], v[208:209] op_sel:[0,1] op_sel_hi:[1,1] neg_lo:[0,1] neg_hi:[0,1]
	v_exp_f32_e32 v218, v118
	v_pk_add_f32 v[70:71], v[70:71], v[210:211] op_sel_hi:[1,0] neg_lo:[0,1] neg_hi:[0,1]
	v_exp_f32_e32 v117, v70
	v_pk_add_f32 v[102:103], v[102:103], v[210:211] op_sel_hi:[1,0] neg_lo:[0,1] neg_hi:[0,1]
	v_exp_f32_e32 v219, v102
	v_exp_f32_e32 v70, v87
	v_exp_f32_e32 v86, v119
	v_exp_f32_e32 v71, v71
	v_exp_f32_e32 v87, v103
; #define MFMA32(a, b, c) __builtin_amdgcn_mfma_f32_32x32x16_bf16((a), (b), (c), 0, 0, 0)
; DI unsigned pack2(float a, float b) { unsigned r; asm volatile("v_cvt_pk_bf16_f32 %0, %1, %2" : "=v"(r) : "v"(a), "v"(b)); return r; }
; DI void attn_pass_da(const bfr* __restrict__ P, int b, int tq_wave, int qcol, int kcol, int vcol, int key0, int nkt, char* smem, f32x16 (&o0)[2], f32x16 (&o1)[2]) {
;     ...
;     const float mn0 = fmaxf(m0, mx0), mn1 = fmaxf(m1, mx1);
;     const float al0 = __builtin_amdgcn_exp2f(m0 - mn0), al1 = __builtin_amdgcn_exp2f(m1 - mn1);
;     m0 = mn0; m1 = mn1;
;     float ps0 = 0.f, ps1 = 0.f;
; #pragma unroll
;     for (int i = 0; i < 16; ++i) {
;       s0[0][i] = __builtin_amdgcn_exp2f(s0[0][i] - mn0); ps0 += s0[0][i];
;       s0[1][i] = __builtin_amdgcn_exp2f(s0[1][i] - mn0); ps0 += s0[1][i];
;       s1[0][i] = __builtin_amdgcn_exp2f(s1[0][i] - mn1); ps1 += s1[0][i];
;       s1[1][i] = __builtin_amdgcn_exp2f(s1[1][i] - mn1); ps1 += s1[1][i];
;     }
;     l0 = l0 * al0 + ps0; l1 = l1 * al1 + ps1;
; #pragma unroll
;     for (int i = 0; i < 16; ++i) { acc0[0][i] *= al0; acc0[1][i] *= al0; acc1[0][i] *= al1; acc1[1][i] *= al1; }
; #pragma unroll
;     for (int t2 = 0; t2 < 2; ++t2)
; #pragma unroll
;       for (int j = 0; j < 2; ++j) {
;         u32x4 pk0, pk1;
;         pk0.x = pack2(s0[t2][8 * j + 0], s0[t2][8 * j + 1]); pk0.y = pack2(s0[t2][8 * j + 2], s0[t2][8 * j + 3]);
;         pk0.z = pack2(s0[t2][8 * j + 4], s0[t2][8 * j + 5]); pk0.w = pack2(s0[t2][8 * j + 6], s0[t2][8 * j + 7]);
;         pk1.x = pack2(s1[t2][8 * j + 0], s1[t2][8 * j + 1]); pk1.y = pack2(s1[t2][8 * j + 2], s1[t2][8 * j + 3]);
;         pk1.z = pack2(s1[t2][8 * j + 4], s1[t2][8 * j + 5]); pk1.w = pack2(s1[t2][8 * j + 6], s1[t2][8 * j + 7]);
;         const bf16x8 pf0 = __builtin_bit_cast(bf16x8, pk0), pf1 = __builtin_bit_cast(bf16x8, pk1);
; #pragma unroll
;         for (int dt = 0; dt < 2; ++dt) {
;           const int vsw = (((dt * 32 + r) >> 3) & 7) << 3;
;           const bfr* vrow = sV + (dt * 32 + r) * 72;
;           s16x4 lo = *(const s16x4*)(vrow + ((t2 * 32 + 16 * j + 4 * h) ^ vsw));
;           s16x4 hi = *(const s16x4*)(vrow + ((t2 * 32 + 16 * j + 4 * h + 8) ^ vsw));
;           bf16x8 vf = __builtin_shufflevector(lo, hi, 0, 1, 2, 3, 4, 5, 6, 7);
;           acc0[dt] = MFMA32(vf, pf0, acc0[dt]);
;           acc1[dt] = MFMA32(vf, pf1, acc1[dt]);
	v_pk_add_f32 v[88:89], v[88:89], v[208:209] op_sel:[0,1] op_sel_hi:[1,1] neg_lo:[0,1] neg_hi:[0,1]
	v_exp_f32_e32 v102, v88
	v_pk_add_f32 v[120:121], v[120:121], v[208:209] op_sel:[0,1] op_sel_hi:[1,1] neg_lo:[0,1] neg_hi:[0,1]
	v_exp_f32_e32 v118, v120
	v_pk_add_f32 v[72:73], v[72:73], v[210:211] op_sel_hi:[1,0] neg_lo:[0,1] neg_hi:[0,1]
	v_exp_f32_e32 v103, v72
	v_pk_add_f32 v[104:105], v[104:105], v[210:211] op_sel_hi:[1,0] neg_lo:[0,1] neg_hi:[0,1]
	v_exp_f32_e32 v119, v104
	v_exp_f32_e32 v88, v89
	v_exp_f32_e32 v104, v121
	v_exp_f32_e32 v89, v73
	v_exp_f32_e32 v105, v105
	v_pk_add_f32 v[90:91], v[90:91], v[208:209] op_sel:[0,1] op_sel_hi:[1,1] neg_lo:[0,1] neg_hi:[0,1]
	v_exp_f32_e32 v120, v90
	v_pk_add_f32 v[122:123], v[122:123], v[208:209] op_sel:[0,1] op_sel_hi:[1,1] neg_lo:[0,1] neg_hi:[0,1]
	v_exp_f32_e32 v220, v122
	v_pk_add_f32 v[74:75], v[74:75], v[210:211] op_sel_hi:[1,0] neg_lo:[0,1] neg_hi:[0,1]
	v_exp_f32_e32 v121, v74
	v_pk_add_f32 v[106:107], v[106:107], v[210:211] op_sel_hi:[1,0] neg_lo:[0,1] neg_hi:[0,1]
	v_exp_f32_e32 v221, v106
	v_exp_f32_e32 v90, v91
	v_exp_f32_e32 v106, v123
	v_exp_f32_e32 v91, v75
	v_exp_f32_e32 v107, v107
	v_pk_add_f32 v[92:93], v[92:93], v[208:209] op_sel:[0,1] op_sel_hi:[1,1] neg_lo:[0,1] neg_hi:[0,1]
	v_exp_f32_e32 v122, v92
	v_pk_add_f32 v[124:125], v[124:125], v[208:209] op_sel:[0,1] op_sel_hi:[1,1] neg_lo:[0,1] neg_hi:[0,1]
	v_exp_f32_e32 v222, v124
	v_pk_add_f32 v[76:77], v[76:77], v[210:211] op_sel_hi:[1,0] neg_lo:[0,1] neg_hi:[0,1]
	v_exp_f32_e32 v123, v76
	v_pk_add_f32 v[108:109], v[108:109], v[210:211] op_sel_hi:[1,0] neg_lo:[0,1] neg_hi:[0,1]
	v_exp_f32_e32 v223, v108
	v_exp_f32_e32 v92, v93
	v_exp_f32_e32 v108, v125
	v_exp_f32_e32 v93, v77
	v_exp_f32_e32 v109, v109
	v_pk_add_f32 v[94:95], v[94:95], v[208:209] op_sel:[0,1] op_sel_hi:[1,1] neg_lo:[0,1] neg_hi:[0,1]
	v_exp_f32_e32 v124, v94
	v_pk_add_f32 v[126:127], v[126:127], v[208:209] op_sel:[0,1] op_sel_hi:[1,1] neg_lo:[0,1] neg_hi:[0,1]
	v_exp_f32_e32 v224, v126
	v_pk_add_f32 v[78:79], v[78:79], v[210:211] op_sel_hi:[1,0] neg_lo:[0,1] neg_hi:[0,1]
	v_exp_f32_e32 v125, v78
	v_pk_add_f32 v[110:111], v[110:111], v[210:211] op_sel_hi:[1,0] neg_lo:[0,1] neg_hi:[0,1]
	v_exp_f32_e32 v225, v110
	v_exp_f32_e32 v94, v95
	v_exp_f32_e32 v110, v127
	v_exp_f32_e32 v95, v79
	v_exp_f32_e32 v111, v111
	v_pk_add_f32 v[64:65], v[192:193], 0 op_sel_hi:[1,0]
	v_sub_f32_e32 v161, v161, v210
	v_pk_add_f32 v[64:65], v[212:213], v[64:65]
	v_exp_f32_e32 v161, v161
	v_pk_add_f32 v[64:65], v[80:81], v[64:65]
	v_lshl_add_u32 v74, v180, 1, v194
	v_pk_add_f32 v[64:65], v[96:97], v[64:65]
	v_lshl_add_u32 v76, v179, 1, v195
	v_pk_add_f32 v[64:65], v[112:113], v[64:65]
	v_lshl_add_u32 v78, v178, 1, v195
	v_pk_add_f32 v[64:65], v[214:215], v[64:65]
	v_sub_f32_e32 v160, v160, v209
	v_pk_add_f32 v[64:65], v[82:83], v[64:65]
	v_exp_f32_e32 v160, v160
	v_pk_add_f32 v[64:65], v[98:99], v[64:65]
	v_pk_mul_f32 v[62:63], v[62:63], v[160:161] op_sel_hi:[1,0]
	v_pk_add_f32 v[64:65], v[114:115], v[64:65]
	v_pk_mul_f32 v[60:61], v[60:61], v[160:161] op_sel_hi:[1,0]
	v_pk_add_f32 v[64:65], v[216:217], v[64:65]
	v_pk_mul_f32 v[58:59], v[58:59], v[160:161] op_sel_hi:[1,0]
	v_pk_add_f32 v[64:65], v[84:85], v[64:65]
	v_pk_mul_f32 v[56:57], v[56:57], v[160:161] op_sel_hi:[1,0]
	v_pk_add_f32 v[64:65], v[100:101], v[64:65]
	v_pk_mul_f32 v[54:55], v[54:55], v[160:161] op_sel_hi:[1,0]
	v_pk_add_f32 v[64:65], v[116:117], v[64:65]
	v_pk_mul_f32 v[52:53], v[52:53], v[160:161] op_sel_hi:[1,0]
	v_pk_add_f32 v[64:65], v[218:219], v[64:65]
	v_pk_mul_f32 v[50:51], v[50:51], v[160:161] op_sel_hi:[1,0]
	v_pk_add_f32 v[64:65], v[70:71], v[64:65]
	v_pk_mul_f32 v[48:49], v[48:49], v[160:161] op_sel_hi:[1,0]
	v_pk_add_f32 v[64:65], v[86:87], v[64:65]
	v_pk_mul_f32 v[30:31], v[30:31], v[160:161] op_sel_hi:[1,0]
	v_pk_add_f32 v[64:65], v[102:103], v[64:65]
	v_pk_mul_f32 v[28:29], v[28:29], v[160:161] op_sel_hi:[1,0]
	v_pk_add_f32 v[64:65], v[118:119], v[64:65]
	v_pk_mul_f32 v[26:27], v[26:27], v[160:161] op_sel_hi:[1,0]
	v_pk_add_f32 v[64:65], v[88:89], v[64:65]
	v_pk_mul_f32 v[24:25], v[24:25], v[160:161] op_sel_hi:[1,0]
	v_pk_add_f32 v[64:65], v[104:105], v[64:65]
	v_pk_mul_f32 v[22:23], v[22:23], v[160:161] op_sel_hi:[1,0]
	v_pk_add_f32 v[64:65], v[120:121], v[64:65]
	v_pk_mul_f32 v[20:21], v[20:21], v[160:161] op_sel_hi:[1,0]
	v_pk_add_f32 v[126:127], v[220:221], v[64:65]
	v_cvt_pk_bf16_f32 v64, v192, v80
	v_cvt_pk_bf16_f32 v65, v112, v82
	v_lshl_add_u32 v112, v181, 1, v194
	v_cvt_pk_bf16_f32 v66, v114, v84
	v_cvt_pk_bf16_f32 v67, v116, v70
	v_cvt_pk_bf16_f32 v68, v193, v81
	v_cvt_pk_bf16_f32 v69, v113, v83
	v_cvt_pk_bf16_f32 v70, v115, v85
	v_cvt_pk_bf16_f32 v71, v117, v71
	ds_read_b64 v[72:73], v112 offset:9216
	ds_read_b64 v[74:75], v74 offset:9216
	ds_read_b64 v[76:77], v76 offset:9216
	ds_read_b64 v[78:79], v78 offset:9216
	v_mov_b32_e32 v82, v161
	v_pk_mul_f32 v[46:47], v[46:47], v[82:83] op_sel_hi:[1,0]
	v_pk_mul_f32 v[44:45], v[44:45], v[82:83] op_sel_hi:[1,0]
	v_pk_mul_f32 v[42:43], v[42:43], v[82:83] op_sel_hi:[1,0]
	v_pk_mul_f32 v[40:41], v[40:41], v[82:83] op_sel_hi:[1,0]
	v_pk_mul_f32 v[38:39], v[38:39], v[82:83] op_sel_hi:[1,0]
	v_pk_mul_f32 v[36:37], v[36:37], v[82:83] op_sel_hi:[1,0]
	v_pk_mul_f32 v[34:35], v[34:35], v[82:83] op_sel_hi:[1,0]
	v_pk_mul_f32 v[32:33], v[32:33], v[82:83] op_sel_hi:[1,0]
	v_pk_mul_f32 v[14:15], v[14:15], v[82:83] op_sel_hi:[1,0]
	v_pk_mul_f32 v[12:13], v[12:13], v[82:83] op_sel_hi:[1,0]
	v_pk_mul_f32 v[10:11], v[10:11], v[82:83] op_sel_hi:[1,0]
	v_pk_mul_f32 v[8:9], v[8:9], v[82:83] op_sel_hi:[1,0]
	v_pk_mul_f32 v[6:7], v[6:7], v[82:83] op_sel_hi:[1,0]
	v_pk_mul_f32 v[4:5], v[4:5], v[82:83] op_sel_hi:[1,0]
	v_pk_mul_f32 v[2:3], v[2:3], v[82:83] op_sel_hi:[1,0]
	v_pk_mul_f32 v[0:1], v[0:1], v[82:83] op_sel_hi:[1,0]
	v_pk_add_f32 v[82:83], v[90:91], v[126:127]
	s_waitcnt lgkmcnt(2)
; DI void attn_pass_da(const bfr* __restrict__ P, int b, int tq_wave, int qcol, int kcol, int vcol, int key0, int nkt, char* smem, f32x16 (&o0)[2], f32x16 (&o1)[2]) {
;     ...
;   for (int kt = 0; kt < nkt; ++kt) {
;     bfr* sK = sbase + (kt & 1) * 9216;
;     bfr* sV = sK + 64 * 72;
;     { int c = gt, row = c >> 3, kc = c & 7; *(u32x4*)(sK + row * KP + kc * 8) = kreg[0]; }
;     for (int i = 0; i < 1; ++i) {
;       int c = gt, row = c >> 3, kc = c & 7;
;       unsigned wds[4] = {vreg[i].x, vreg[i].y, vreg[i].z, vreg[i].w};
; #pragma unroll
;       for (int e = 0; e < 4; ++e) {
;         sV[(kc * 8 + 2 * e) * 72 + (row ^ (kc << 3))] = (bfr)(wds[e] & 0xffffu);
;         sV[(kc * 8 + 2 * e + 1) * 72 + (row ^ (kc << 3))] = (bfr)(wds[e] >> 16);
;       }
;     }
;     __syncthreads();
;     if (kt + 1 < nkt) {
;       const bfr* Pn = Pb + (size_t)(kt + 1) * 64 * PW;
;       { int c = gt, row = c >> 3, kc = c & 7; kreg[0] = *(const u32x4*)(Pn + (size_t)row * PW + kcol + kc * 8); vreg[0] = *(const u32x4*)(Pn + (size_t)row * PW + vcol + kc * 8); }
;     }
;     f32x16 s0[2], s1[2];
; #pragma unroll
;     for (int t2 = 0; t2 < 2; ++t2) {
; #pragma unroll
;     ...
;     for (int t2 = 0; t2 < 2; ++t2)
; #pragma unroll
;       for (int j = 0; j < 2; ++j) {
;         u32x4 pk0, pk1;
;         pk0.x = pack2(s0[t2][8 * j + 0], s0[t2][8 * j + 1]); pk0.y = pack2(s0[t2][8 * j + 2], s0[t2][8 * j + 3]);
;         pk0.z = pack2(s0[t2][8 * j + 4], s0[t2][8 * j + 5]); pk0.w = pack2(s0[t2][8 * j + 6], s0[t2][8 * j + 7]);
;         pk1.x = pack2(s1[t2][8 * j + 0], s1[t2][8 * j + 1]); pk1.y = pack2(s1[t2][8 * j + 2], s1[t2][8 * j + 3]);
;         pk1.z = pack2(s1[t2][8 * j + 4], s1[t2][8 * j + 5]); pk1.w = pack2(s1[t2][8 * j + 6], s1[t2][8 * j + 7]);
;         const bf16x8 pf0 = __builtin_bit_cast(bf16x8, pk0), pf1 = __builtin_bit_cast(bf16x8, pk1);
; #pragma unroll
;         for (int dt = 0; dt < 2; ++dt) {
;           const int vsw = (((dt * 32 + r) >> 3) & 7) << 3;
;           const bfr* vrow = sV + (dt * 32 + r) * 72;
;           s16x4 lo = *(const s16x4*)(vrow + ((t2 * 32 + 16 * j + 4 * h) ^ vsw));
;           s16x4 hi = *(const s16x4*)(vrow + ((t2 * 32 + 16 * j + 4 * h + 8) ^ vsw));
;           bf16x8 vf = __builtin_shufflevector(lo, hi, 0, 1, 2, 3, 4, 5, 6, 7);
;           acc0[dt] = MFMA32(vf, pf0, acc0[dt]);
;           acc1[dt] = MFMA32(vf, pf1, acc1[dt]);
;         }
;       }
	v_mfma_f32_32x32x16_bf16 v[48:63], v[72:75], v[64:67], v[48:63]
	v_add_f32_e64 v82, v106, v82
	v_add_f32_e64 v83, v107, v83
	v_cvt_pk_bf16_f32 v80, v102, v88
	v_lshl_add_u32 v88, v177, 1, v194
	v_add_f32_e64 v82, v122, v82
	v_add_f32_e64 v83, v123, v83
	v_pk_mul_f32 v[18:19], v[18:19], v[160:161] op_sel_hi:[1,0]
	v_pk_add_f32 v[82:83], v[222:223], v[82:83]
	v_pk_mul_f32 v[16:17], v[16:17], v[160:161] op_sel_hi:[1,0]
	v_pk_add_f32 v[82:83], v[92:93], v[82:83]
	v_mfma_f32_32x32x16_bf16 v[32:47], v[72:75], v[68:71], v[32:47]
	v_add_f32_e64 v82, v108, v82
	v_add_f32_e64 v83, v109, v83
	v_cvt_pk_bf16_f32 v81, v120, v90
	v_lshl_add_u32 v102, v176, 1, v194
	v_add_f32_e64 v82, v124, v82
	v_add_f32_e64 v83, v125, v83
	v_lshl_add_u32 v113, v175, 1, v195
	v_pk_add_f32 v[82:83], v[224:225], v[82:83]
	v_lshl_add_u32 v114, v174, 1, v195
	v_pk_add_f32 v[82:83], v[94:95], v[82:83]
	s_waitcnt lgkmcnt(0)
	v_mfma_f32_32x32x16_bf16 v[16:31], v[76:79], v[64:67], v[16:31]
	v_add_f32_e64 v84, v110, v82
	v_add_f32_e64 v85, v111, v83
	v_cvt_pk_bf16_f32 v82, v122, v92
	v_cvt_pk_bf16_f32 v83, v124, v94
	v_cvt_pk_bf16_f32 v64, v103, v89
	v_cvt_pk_bf16_f32 v65, v121, v91
	v_cvt_pk_bf16_f32 v66, v123, v93
	v_cvt_pk_bf16_f32 v67, v125, v95
	v_mfma_f32_32x32x16_bf16 v[0:15], v[76:79], v[68:71], v[0:15]
	ds_read_b64 v[68:69], v88 offset:9216
	ds_read_b64 v[70:71], v102 offset:9216
	v_lshl_add_u32 v115, v173, 1, v194
	v_lshl_add_u32 v116, v172, 1, v195
	v_lshl_add_u32 v117, v171, 1, v195
	v_lshl_add_u32 v120, v169, 1, v194
	v_lshl_add_u32 v192, v170, 1, v194
	v_lshl_add_u32 v193, v168, 1, v195
	s_waitcnt lgkmcnt(0)
	v_mfma_f32_32x32x16_bf16 v[48:63], v[68:71], v[80:83], v[48:63]
	v_lshl_add_u32 v194, v167, 1, v195
	v_fma_f32 v156, v156, v160, v84
	v_fma_f32 v157, v157, v161, v85
	v_mfma_f32_32x32x16_bf16 v[32:47], v[68:71], v[64:67], v[32:47]
	ds_read_b64 v[68:69], v113 offset:9216
	ds_read_b64 v[70:71], v114 offset:9216
	s_waitcnt lgkmcnt(0)
	v_mfma_f32_32x32x16_bf16 v[16:31], v[68:71], v[80:83], v[16:31]
	v_mfma_f32_32x32x16_bf16 v[0:15], v[68:71], v[64:67], v[0:15]
	v_cvt_pk_bf16_f32 v64, v212, v96
	v_cvt_pk_bf16_f32 v65, v214, v98
	v_cvt_pk_bf16_f32 v66, v216, v100
	v_cvt_pk_bf16_f32 v67, v218, v86
	v_cvt_pk_bf16_f32 v68, v213, v97
	v_cvt_pk_bf16_f32 v69, v215, v99
	v_cvt_pk_bf16_f32 v70, v217, v101
	v_cvt_pk_bf16_f32 v71, v219, v87
	ds_read_b64 v[72:73], v112 offset:9280
	ds_read_b64 v[74:75], v115 offset:9216
	s_waitcnt lgkmcnt(0)
	v_mfma_f32_32x32x16_bf16 v[48:63], v[72:75], v[64:67], v[48:63]
	v_mfma_f32_32x32x16_bf16 v[32:47], v[72:75], v[68:71], v[32:47]
	ds_read_b64 v[72:73], v116 offset:9216
	ds_read_b64 v[74:75], v117 offset:9216
	s_waitcnt lgkmcnt(0)
	v_mfma_f32_32x32x16_bf16 v[16:31], v[72:75], v[64:67], v[16:31]
	v_cvt_pk_bf16_f32 v64, v118, v104
	v_cvt_pk_bf16_f32 v65, v220, v106
	v_cvt_pk_bf16_f32 v66, v222, v108
	v_cvt_pk_bf16_f32 v67, v224, v110
	v_mfma_f32_32x32x16_bf16 v[0:15], v[72:75], v[68:71], v[0:15]
	v_cvt_pk_bf16_f32 v68, v119, v105
	v_cvt_pk_bf16_f32 v69, v221, v107
	v_cvt_pk_bf16_f32 v70, v223, v109
	v_cvt_pk_bf16_f32 v71, v225, v111
	ds_read_b64 v[72:73], v120 offset:9216
	ds_read_b64 v[74:75], v192 offset:9216
	s_waitcnt lgkmcnt(0)
	v_mfma_f32_32x32x16_bf16 v[48:63], v[72:75], v[64:67], v[48:63]
	v_mfma_f32_32x32x16_bf16 v[32:47], v[72:75], v[68:71], v[32:47]
	ds_read_b64 v[72:73], v193 offset:9216
	ds_read_b64 v[74:75], v194 offset:9216
	s_waitcnt lgkmcnt(0)
	v_mfma_f32_32x32x16_bf16 v[16:31], v[72:75], v[64:67], v[16:31]
	v_mfma_f32_32x32x16_bf16 v[0:15], v[72:75], v[68:71], v[0:15]
	s_cbranch_scc1 .LBB0_421
	v_add3_u32 v64, 0, v206, v152
	s_waitcnt vmcnt(1)
	ds_write_b128 v64, v[148:151] offset:18432
	v_add3_u32 v64, 0, v207, v208
	v_add3_u32 v65, 0, v208, v207
	s_waitcnt vmcnt(0)
	ds_write_b16 v64, v144 offset:27648
	ds_write_b16_d16_hi v65, v144 offset:27792
	ds_write_b16 v64, v145 offset:27936
	ds_write_b16_d16_hi v65, v145 offset:28080
	ds_write_b16 v64, v146 offset:28224
	ds_write_b16_d16_hi v65, v146 offset:28368
	ds_write_b16 v64, v147 offset:28512
	ds_write_b16_d16_hi v65, v147 offset:28656
	v_add_u32_e32 v144, 0, v205
	v_add_u32_e32 v102, v144, v204
	s_waitcnt lgkmcnt(0)
	s_barrier
	ds_read_b128 v[64:67], v102 offset:18432
	ds_read_b128 v[96:99], v102 offset:18464
	s_waitcnt lgkmcnt(1)
	v_mfma_f32_32x32x16_bf16 v[64:79], v[64:67], v[140:143], 0
	ds_read_b128 v[80:83], v102 offset:18496
	v_readlane_b32 s10, v203, 16
	v_readlane_b32 s11, v203, 48
	v_add_u32_e32 v145, 0x1200, v144
	v_mov_b32_e32 v100, s10
	v_mov_b32_e32 v101, s11
	v_pk_add_f32 v[100:101], s[8:9], v[100:101]
	s_mov_b32 s10, 0x3fb8aa3b
	v_add_f32_e32 v146, v100, v101
	v_mul_f32_e32 v104, 0x3fb8aa3b, v146
	v_fma_f32 v105, v146, s10, -v104
	v_rndne_f32_e32 v106, v104
	s_waitcnt lgkmcnt(1)
	v_mfma_f32_32x32x16_bf16 v[64:79], v[96:99], v[132:135], v[64:79]
	v_fmac_f32_e32 v105, 0x32a5705f, v146
	v_sub_f32_e32 v96, v104, v106
	v_add_u32_e32 v147, v145, v204
	v_add_f32_e32 v104, v96, v105
	ds_read_b128 v[96:99], v147 offset:18432
	ds_read_b128 v[100:103], v102 offset:18528
	ds_read_b128 v[112:115], v147 offset:18496
	s_waitcnt lgkmcnt(3)
	v_mfma_f32_32x32x16_bf16 v[80:95], v[80:83], v[136:139], 0
	v_readlane_b32 s8, v202, 16
	v_readlane_b32 s9, v202, 48
	s_mov_b32 s11, 0xc2ce8ed0
	v_mov_b32_e32 v116, s8
	v_mov_b32_e32 v117, s9
	v_pk_add_f32 v[116:117], s[6:7], v[116:117]
	v_cmp_ngt_f32_e32 vcc, s11, v146
	s_waitcnt lgkmcnt(1)
	v_mfma_f32_32x32x16_bf16 v[80:95], v[100:103], v[128:131], v[80:95]
	v_exp_f32_e32 v100, v104
	v_cvt_i32_f32_e32 v101, v106
	v_add_f32_e32 v149, v116, v117
	v_mul_f32_e32 v150, 0x3fb8aa3b, v149
	v_rndne_f32_e32 v151, v150
	v_ldexp_f32 v148, v100, v101
	s_mov_b32 s6, 0x42b17218
	s_waitcnt lgkmcnt(0)
; #define MFMA32(a, b, c) __builtin_amdgcn_mfma_f32_32x32x16_bf16((a), (b), (c), 0, 0, 0)
; DI void attn_pass_da(const bfr* __restrict__ P, int b, int tq_wave, int qcol, int kcol, int vcol, int key0, int nkt, char* smem, f32x16 (&o0)[2], f32x16 (&o1)[2]) {
;     ...
;     f32x16 s0[2], s1[2];
; #pragma unroll
;     for (int t2 = 0; t2 < 2; ++t2) {
; #pragma unroll
;       for (int i = 0; i < 16; ++i) { s0[t2][i] = 0.f; s1[t2][i] = 0.f; }
; #pragma unroll
;       for (int ks = 0; ks < 2; ++ks) {
;         bf16x8 a0 = *(const bf16x8*)(sK + (t2 * 32 + r) * KP + ks * 16 + h * 8);
;         bf16x8 a1 = *(const bf16x8*)(sK + (t2 * 32 + r) * KP + 32 + ks * 16 + h * 8);
;         s0[t2] = MFMA32(a0, qf[ks], s0[t2]);
;         s1[t2] = MFMA32(a1, qf[2 + ks], s1[t2]);
;       }
;     }
;     float mx0 = s0[0][0], mx1 = s1[0][0];
; #pragma unroll
;     for (int i = 0; i < 16; ++i) { mx0 = fmaxf(mx0, fmaxf(s0[0][i], s0[1][i])); mx1 = fmaxf(mx1, fmaxf(s1[0][i], s1[1][i])); }
;     mx0 = fmaxf(mx0, __shfl_xor(mx0, 32)); mx1 = fmaxf(mx1, __shfl_xor(mx1, 32));
;     const float mn0 = fmaxf(m0, mx0), mn1 = fmaxf(m1, mx1);
;     const float al0 = __builtin_amdgcn_exp2f(m0 - mn0), al1 = __builtin_amdgcn_exp2f(m1 - mn1);
; DN void da_item(const Params& p, int l, int b, int hd, int tq0, int key0, int nkt, char* smem) {
;     ...
;   float lam_init = 0.8f - 0.6f * expf(-0.3f * (float)l);
;   float lam = expf(d01) - expf(d23) + lam_init;
	v_mfma_f32_32x32x16_bf16 v[112:127], v[112:115], v[136:139], 0
	v_fma_f32 v136, v149, s10, -v150
	v_fmac_f32_e32 v136, 0x32a5705f, v149
	v_sub_f32_e32 v137, v150, v151
	v_add_f32_e32 v136, v137, v136
	v_exp_f32_e32 v150, v136
	ds_read_b128 v[136:139], v147 offset:18528
	v_readlane_b32 s8, v253, 28
	v_mfma_f32_32x32x16_bf16 v[96:111], v[96:99], v[140:143], 0
	ds_read_b128 v[140:143], v147 offset:18464
	v_readlane_b32 s9, v253, 29
	s_waitcnt lgkmcnt(0)
	v_mfma_f32_32x32x16_bf16 v[96:111], v[140:143], v[132:135], v[96:111]
	v_max_f32_e32 v134, v82, v82
	v_max_f32_e32 v135, v67, v67
	v_cvt_i32_f32_e32 v132, v151
	v_cndmask_b32_e32 v133, 0, v148, vcc
	v_cmp_nlt_f32_e32 vcc, s6, v146
	v_ldexp_f32 v132, v150, v132
	v_mfma_f32_32x32x16_bf16 v[112:127], v[136:139], v[128:131], v[112:127]
	s_nop 4
	v_max_f32_e32 v128, v97, v97
	v_max_f32_e32 v129, v65, v65
	v_max_f32_e32 v128, v129, v128
	v_max_f32_e32 v130, v81, v81
	v_max_f32_e32 v131, v66, v66
	v_max3_f32 v128, v64, v96, v128
	v_cndmask_b32_e32 v133, v201, v133, vcc
	v_max_f32_e32 v129, v113, v113
	v_max_f32_e32 v129, v130, v129
	v_max_f32_e32 v130, v98, v98
	v_max_f32_e32 v130, v131, v130
	v_max_f32_e32 v131, v114, v114
	v_max_f32_e32 v131, v134, v131
	v_max_f32_e32 v134, v99, v99
	v_max_f32_e32 v134, v135, v134
	v_max3_f32 v128, v128, v130, v134
	v_max_f32_e32 v130, v115, v115
	v_max_f32_e32 v134, v83, v83
	v_max3_f32 v129, v80, v112, v129
	v_max_f32_e32 v130, v134, v130
	v_max3_f32 v129, v129, v131, v130
	v_max_f32_e32 v130, v100, v100
	v_max_f32_e32 v131, v68, v68
	v_max_f32_e32 v130, v131, v130
	v_max_f32_e32 v131, v116, v116
	v_max_f32_e32 v134, v84, v84
	v_max_f32_e32 v131, v134, v131
	v_max_f32_e32 v134, v101, v101
	v_max_f32_e32 v135, v69, v69
	v_max_f32_e32 v134, v135, v134
	v_max3_f32 v128, v128, v130, v134
	v_max_f32_e32 v130, v117, v117
	v_max_f32_e32 v134, v85, v85
	v_max_f32_e32 v130, v134, v130
	v_max3_f32 v129, v129, v131, v130
	v_max_f32_e32 v130, v102, v102
	v_max_f32_e32 v131, v70, v70
	v_max_f32_e32 v130, v131, v130
	v_max_f32_e32 v131, v118, v118
	v_max_f32_e32 v134, v86, v86
	v_max_f32_e32 v131, v134, v131
	v_max_f32_e32 v134, v103, v103
	v_max_f32_e32 v135, v71, v71
	v_max_f32_e32 v134, v135, v134
	v_max3_f32 v128, v128, v130, v134
	v_max_f32_e32 v130, v119, v119
	v_max_f32_e32 v134, v87, v87
	v_max_f32_e32 v130, v134, v130
	v_max3_f32 v129, v129, v131, v130
	v_max_f32_e32 v130, v104, v104
	v_max_f32_e32 v131, v72, v72
	v_max_f32_e32 v130, v131, v130
	v_max_f32_e32 v131, v120, v120
	v_max_f32_e32 v134, v88, v88
	v_max_f32_e32 v131, v134, v131
	v_max_f32_e32 v134, v105, v105
	v_max_f32_e32 v135, v73, v73
	v_max_f32_e32 v134, v135, v134
	v_max3_f32 v128, v128, v130, v134
	v_max_f32_e32 v130, v121, v121
	v_max_f32_e32 v134, v89, v89
	v_max_f32_e32 v130, v134, v130
	v_max3_f32 v129, v129, v131, v130
	v_max_f32_e32 v130, v106, v106
	v_max_f32_e32 v131, v74, v74
	v_max_f32_e32 v130, v131, v130
	v_max_f32_e32 v131, v122, v122
	v_max_f32_e32 v134, v90, v90
	v_max_f32_e32 v131, v134, v131
	v_max_f32_e32 v134, v107, v107
	v_max_f32_e32 v135, v75, v75
	v_max_f32_e32 v134, v135, v134
	v_max3_f32 v128, v128, v130, v134
	v_max_f32_e32 v130, v123, v123
	v_max_f32_e32 v134, v91, v91
	v_max_f32_e32 v130, v134, v130
	v_max3_f32 v129, v129, v131, v130
	v_max_f32_e32 v130, v108, v108
	v_max_f32_e32 v131, v76, v76
	v_max_f32_e32 v130, v131, v130
	v_max_f32_e32 v131, v124, v124
	v_max_f32_e32 v134, v92, v92
	v_max_f32_e32 v131, v134, v131
	v_max_f32_e32 v134, v109, v109
	v_max_f32_e32 v135, v77, v77
	v_max_f32_e32 v134, v135, v134
	v_max3_f32 v128, v128, v130, v134
	v_max_f32_e32 v130, v125, v125
	v_max_f32_e32 v134, v93, v93
	v_max_f32_e32 v130, v134, v130
	v_max3_f32 v129, v129, v131, v130
	v_max_f32_e32 v130, v110, v110
	v_max_f32_e32 v131, v78, v78
	v_max_f32_e32 v130, v131, v130
	v_max_f32_e32 v131, v126, v126
	v_max_f32_e32 v134, v94, v94
	v_max_f32_e32 v131, v134, v131
	v_max_f32_e32 v134, v111, v111
	v_max_f32_e32 v135, v79, v79
	v_max_f32_e32 v134, v135, v134
	v_max3_f32 v128, v128, v130, v134
	v_max_f32_e32 v130, v127, v127
	v_max_f32_e32 v134, v95, v95
	v_max_f32_e32 v130, v134, v130
	v_max3_f32 v130, v129, v131, v130
	ds_bpermute_b32 v131, v166, v128
	ds_bpermute_b32 v134, v166, v130
	v_cmp_ngt_f32_e32 vcc, s11, v149
	s_waitcnt lgkmcnt(0)
; DI unsigned pack2(float a, float b) { unsigned r; asm volatile("v_cvt_pk_bf16_f32 %0, %1, %2" : "=v"(r) : "v"(a), "v"(b)); return r; }
; DI void attn_pass_da(const bfr* __restrict__ P, int b, int tq_wave, int qcol, int kcol, int vcol, int key0, int nkt, char* smem, f32x16 (&o0)[2], f32x16 (&o1)[2]) {
;     ...
;     const float mn0 = fmaxf(m0, mx0), mn1 = fmaxf(m1, mx1);
;     const float al0 = __builtin_amdgcn_exp2f(m0 - mn0), al1 = __builtin_amdgcn_exp2f(m1 - mn1);
;     m0 = mn0; m1 = mn1;
;     float ps0 = 0.f, ps1 = 0.f;
; #pragma unroll
;     for (int i = 0; i < 16; ++i) {
;       s0[0][i] = __builtin_amdgcn_exp2f(s0[0][i] - mn0); ps0 += s0[0][i];
;       s0[1][i] = __builtin_amdgcn_exp2f(s0[1][i] - mn0); ps0 += s0[1][i];
;       s1[0][i] = __builtin_amdgcn_exp2f(s1[0][i] - mn1); ps1 += s1[0][i];
;       s1[1][i] = __builtin_amdgcn_exp2f(s1[1][i] - mn1); ps1 += s1[1][i];
;     }
;     l0 = l0 * al0 + ps0; l1 = l1 * al1 + ps1;
; #pragma unroll
;     for (int i = 0; i < 16; ++i) { acc0[0][i] *= al0; acc0[1][i] *= al0; acc1[0][i] *= al1; acc1[1][i] *= al1; }
; #pragma unroll
;     for (int t2 = 0; t2 < 2; ++t2)
; #pragma unroll
;       for (int j = 0; j < 2; ++j) {
;         u32x4 pk0, pk1;
;         pk0.x = pack2(s0[t2][8 * j + 0], s0[t2][8 * j + 1]); pk0.y = pack2(s0[t2][8 * j + 2], s0[t2][8 * j + 3]);
;         pk0.z = pack2(s0[t2][8 * j + 4], s0[t2][8 * j + 5]); pk0.w = pack2(s0[t2][8 * j + 6], s0[t2][8 * j + 7]);
;         pk1.x = pack2(s1[t2][8 * j + 0], s1[t2][8 * j + 1]); pk1.y = pack2(s1[t2][8 * j + 2], s1[t2][8 * j + 3]);
	v_max3_f32 v150, v210, v130, v134
	v_cndmask_b32_e32 v132, 0, v132, vcc
	v_cmp_nlt_f32_e32 vcc, s6, v149
	v_max3_f32 v149, v209, v128, v131
	v_sub_f32_e32 v64, v64, v149
	v_exp_f32_e32 v148, v64
	v_sub_f32_e32 v64, v96, v149
	v_exp_f32_e32 v131, v64
	v_sub_f32_e32 v64, v80, v150
	v_exp_f32_e32 v151, v64
	v_sub_f32_e32 v64, v112, v150
	v_exp_f32_e32 v96, v64
	v_sub_f32_e32 v64, v65, v149
	v_exp_f32_e32 v152, v64
	v_sub_f32_e32 v64, v97, v149
	v_exp_f32_e32 v112, v64
	v_sub_f32_e32 v64, v81, v150
	v_exp_f32_e32 v158, v64
	v_sub_f32_e32 v64, v113, v150
	v_exp_f32_e32 v97, v64
	v_sub_f32_e32 v64, v66, v149
	v_exp_f32_e32 v143, v64
	v_sub_f32_e32 v64, v98, v149
	v_exp_f32_e32 v113, v64
	v_sub_f32_e32 v64, v82, v150
	v_exp_f32_e32 v146, v64
	v_sub_f32_e32 v64, v114, v150
	v_exp_f32_e32 v98, v64
	v_sub_f32_e32 v64, v67, v149
	v_exp_f32_e32 v147, v64
	v_sub_f32_e32 v64, v99, v149
	v_exp_f32_e32 v114, v64
	v_sub_f32_e32 v64, v83, v150
	v_exp_f32_e32 v138, v64
	v_sub_f32_e32 v64, v115, v150
	v_exp_f32_e32 v99, v64
	v_sub_f32_e32 v64, v68, v149
	v_exp_f32_e32 v139, v64
	v_sub_f32_e32 v64, v100, v149
	v_exp_f32_e32 v115, v64
	v_sub_f32_e32 v64, v84, v150
	v_exp_f32_e32 v140, v64
	v_sub_f32_e32 v64, v116, v150
	v_exp_f32_e32 v100, v64
	v_sub_f32_e32 v64, v69, v149
	v_exp_f32_e32 v141, v64
	v_sub_f32_e32 v64, v101, v149
	v_exp_f32_e32 v116, v64
	v_sub_f32_e32 v64, v85, v150
	v_exp_f32_e32 v142, v64
	v_sub_f32_e32 v64, v117, v150
	v_exp_f32_e32 v101, v64
	v_sub_f32_e32 v64, v70, v149
	v_exp_f32_e32 v134, v64
	v_sub_f32_e32 v64, v102, v149
	v_cndmask_b32_e32 v129, v201, v132, vcc
	v_exp_f32_e32 v132, v64
	v_sub_f32_e32 v64, v86, v150
	v_exp_f32_e32 v135, v64
	v_sub_f32_e32 v64, v118, v150
	v_exp_f32_e32 v117, v64
	v_sub_f32_e32 v64, v71, v149
	v_exp_f32_e32 v136, v64
	v_sub_f32_e32 v64, v103, v149
	v_sub_f32_e32 v129, v133, v129
	v_exp_f32_e32 v133, v64
	v_sub_f32_e32 v64, v87, v150
	v_exp_f32_e32 v137, v64
	v_sub_f32_e32 v64, v119, v150
	v_exp_f32_e32 v102, v64
	v_sub_f32_e32 v64, v72, v149
	v_exp_f32_e32 v103, v64
	v_sub_f32_e32 v64, v104, v149
	v_exp_f32_e32 v71, v64
	v_sub_f32_e32 v64, v88, v150
	v_exp_f32_e32 v104, v64
	v_sub_f32_e32 v64, v120, v150
	v_exp_f32_e32 v70, v64
	v_sub_f32_e32 v64, v73, v149
	v_exp_f32_e32 v118, v64
	v_sub_f32_e32 v64, v105, v149
	v_exp_f32_e32 v73, v64
	v_sub_f32_e32 v64, v89, v150
	v_exp_f32_e32 v105, v64
	v_sub_f32_e32 v64, v121, v150
	v_exp_f32_e32 v72, v64
	v_sub_f32_e32 v64, v74, v149
	v_exp_f32_e32 v119, v64
	v_sub_f32_e32 v64, v106, v149
	v_exp_f32_e32 v81, v64
	v_sub_f32_e32 v64, v90, v150
	v_exp_f32_e32 v89, v64
	v_sub_f32_e32 v64, v122, v150
	v_exp_f32_e32 v80, v64
	v_sub_f32_e32 v64, v75, v149
	v_exp_f32_e32 v90, v64
	v_sub_f32_e32 v64, v107, v149
	v_exp_f32_e32 v87, v64
	v_sub_f32_e32 v64, v91, v150
	v_exp_f32_e32 v91, v64
	v_sub_f32_e32 v64, v123, v150
	v_exp_f32_e32 v86, v64
	v_sub_f32_e32 v64, v76, v149
	v_exp_f32_e32 v74, v64
	v_sub_f32_e32 v64, v108, v149
	v_exp_f32_e32 v75, v64
	v_sub_f32_e32 v64, v92, v150
	v_exp_f32_e32 v76, v64
	v_sub_f32_e32 v64, v124, v150
	v_exp_f32_e32 v82, v64
	v_sub_f32_e32 v64, v77, v149
	v_exp_f32_e32 v77, v64
	v_sub_f32_e32 v64, v109, v149
	v_exp_f32_e32 v83, v64
	v_sub_f32_e32 v64, v93, v150
	v_exp_f32_e32 v84, v64
	v_sub_f32_e32 v64, v125, v150
	v_exp_f32_e32 v85, v64
	v_sub_f32_e32 v64, v78, v149
	v_exp_f32_e32 v78, v64
	v_sub_f32_e32 v64, v110, v149
	v_exp_f32_e32 v88, v64
	v_sub_f32_e32 v64, v94, v150
	v_exp_f32_e32 v66, v64
	v_sub_f32_e32 v64, v126, v150
	v_exp_f32_e32 v67, v64
	v_sub_f32_e32 v64, v79, v149
	v_exp_f32_e32 v68, v64
	v_sub_f32_e32 v64, v111, v149
	v_lshl_add_u32 v79, v181, 1, v144
	v_lshl_add_u32 v110, v180, 1, v144
	v_lshl_add_u32 v124, v179, 1, v145
	v_lshl_add_u32 v126, v178, 1, v145
	v_exp_f32_e32 v69, v64
	v_sub_f32_e32 v64, v95, v150
	v_sub_f32_e32 v65, v127, v150
	v_cvt_pk_bf16_f32 v92, v148, v152
	v_cvt_pk_bf16_f32 v93, v143, v147
	v_cvt_pk_bf16_f32 v94, v139, v141
	v_cvt_pk_bf16_f32 v95, v134, v136
	v_cvt_pk_bf16_f32 v106, v151, v158
	v_cvt_pk_bf16_f32 v107, v146, v138
	v_cvt_pk_bf16_f32 v108, v140, v142
	v_cvt_pk_bf16_f32 v109, v135, v137
	ds_read_b64 v[120:121], v79 offset:27648
	ds_read_b64 v[122:123], v110 offset:27648
	ds_read_b64 v[124:125], v124 offset:27648
	ds_read_b64 v[126:127], v126 offset:27648
	v_sub_f32_e32 v128, v209, v149
	v_exp_f32_e32 v130, v128
	v_sub_f32_e32 v128, v210, v150
	v_add_f32_e32 v111, 0, v151
	v_exp_f32_e32 v128, v128
	v_add_f32_e32 v110, 0, v148
	v_add_f32_e32 v111, v96, v111
	v_add_f32_e32 v110, v131, v110
	v_add_f32_e32 v111, v158, v111
	v_add_f32_e32 v110, v152, v110
	v_add_f32_e32 v111, v97, v111
	v_add_f32_e32 v110, v112, v110
	v_add_f32_e32 v111, v146, v111
	v_pk_mul_f32 v[46:47], v[46:47], v[128:129] op_sel_hi:[1,0]
	v_pk_mul_f32 v[44:45], v[44:45], v[128:129] op_sel_hi:[1,0]
	v_pk_mul_f32 v[42:43], v[42:43], v[128:129] op_sel_hi:[1,0]
	v_pk_mul_f32 v[40:41], v[40:41], v[128:129] op_sel_hi:[1,0]
	v_pk_mul_f32 v[38:39], v[38:39], v[128:129] op_sel_hi:[1,0]
	v_pk_mul_f32 v[36:37], v[36:37], v[128:129] op_sel_hi:[1,0]
	v_pk_mul_f32 v[34:35], v[34:35], v[128:129] op_sel_hi:[1,0]
	v_pk_mul_f32 v[32:33], v[32:33], v[128:129] op_sel_hi:[1,0]
	v_pk_mul_f32 v[14:15], v[14:15], v[128:129] op_sel_hi:[1,0]
	v_pk_mul_f32 v[12:13], v[12:13], v[128:129] op_sel_hi:[1,0]
	v_pk_mul_f32 v[10:11], v[10:11], v[128:129] op_sel_hi:[1,0]
	v_pk_mul_f32 v[8:9], v[8:9], v[128:129] op_sel_hi:[1,0]
	v_pk_mul_f32 v[6:7], v[6:7], v[128:129] op_sel_hi:[1,0]
	v_pk_mul_f32 v[4:5], v[4:5], v[128:129] op_sel_hi:[1,0]
	v_pk_mul_f32 v[2:3], v[2:3], v[128:129] op_sel_hi:[1,0]
	v_pk_mul_f32 v[0:1], v[0:1], v[128:129] op_sel_hi:[1,0]
	v_add_f32_e32 v110, v143, v110
	v_add_f32_e32 v111, v98, v111
	s_waitcnt lgkmcnt(2)
; #define MFMA32(a, b, c) __builtin_amdgcn_mfma_f32_32x32x16_bf16((a), (b), (c), 0, 0, 0)
; DI unsigned pack2(float a, float b) { unsigned r; asm volatile("v_cvt_pk_bf16_f32 %0, %1, %2" : "=v"(r) : "v"(a), "v"(b)); return r; }
; DI void attn_pass_da(const bfr* __restrict__ P, int b, int tq_wave, int qcol, int kcol, int vcol, int key0, int nkt, char* smem, f32x16 (&o0)[2], f32x16 (&o1)[2]) {
;     ...
;     l0 = l0 * al0 + ps0; l1 = l1 * al1 + ps1;
; #pragma unroll
;     for (int i = 0; i < 16; ++i) { acc0[0][i] *= al0; acc0[1][i] *= al0; acc1[0][i] *= al1; acc1[1][i] *= al1; }
; #pragma unroll
;     for (int t2 = 0; t2 < 2; ++t2)
; #pragma unroll
;       for (int j = 0; j < 2; ++j) {
;         u32x4 pk0, pk1;
;         pk0.x = pack2(s0[t2][8 * j + 0], s0[t2][8 * j + 1]); pk0.y = pack2(s0[t2][8 * j + 2], s0[t2][8 * j + 3]);
;         pk0.z = pack2(s0[t2][8 * j + 4], s0[t2][8 * j + 5]); pk0.w = pack2(s0[t2][8 * j + 6], s0[t2][8 * j + 7]);
;         pk1.x = pack2(s1[t2][8 * j + 0], s1[t2][8 * j + 1]); pk1.y = pack2(s1[t2][8 * j + 2], s1[t2][8 * j + 3]);
;         pk1.z = pack2(s1[t2][8 * j + 4], s1[t2][8 * j + 5]); pk1.w = pack2(s1[t2][8 * j + 6], s1[t2][8 * j + 7]);
;         const bf16x8 pf0 = __builtin_bit_cast(bf16x8, pk0), pf1 = __builtin_bit_cast(bf16x8, pk1);
; #pragma unroll
;         for (int dt = 0; dt < 2; ++dt) {
;           const int vsw = (((dt * 32 + r) >> 3) & 7) << 3;
;           const bfr* vrow = sV + (dt * 32 + r) * 72;
;           s16x4 lo = *(const s16x4*)(vrow + ((t2 * 32 + 16 * j + 4 * h) ^ vsw));
;           s16x4 hi = *(const s16x4*)(vrow + ((t2 * 32 + 16 * j + 4 * h + 8) ^ vsw));
;           bf16x8 vf = __builtin_shufflevector(lo, hi, 0, 1, 2, 3, 4, 5, 6, 7);
;           acc0[dt] = MFMA32(vf, pf0, acc0[dt]);
;           acc1[dt] = MFMA32(vf, pf1, acc1[dt]);
;         }
;       }
;   }
;   l0 += __shfl_xor(l0, 32); l1 += __shfl_xor(l1, 32);
	v_mfma_f32_32x32x16_bf16 v[32:47], v[120:123], v[106:109], v[32:47]
	v_add_f32_e32 v110, v113, v110
	v_add_f32_e32 v110, v147, v110
	v_add_f32_e32 v110, v114, v110
	v_mul_f32_e64 v62, v62, v130
	v_mul_f32_e64 v63, v63, v130
	v_pk_mul_f32 v[60:61], v[60:61], v[130:131] op_sel_hi:[1,0]
	v_pk_mul_f32 v[58:59], v[58:59], v[130:131] op_sel_hi:[1,0]
	v_pk_mul_f32 v[56:57], v[56:57], v[130:131] op_sel_hi:[1,0]
	s_waitcnt lgkmcnt(0)
	v_mfma_f32_32x32x16_bf16 v[0:15], v[124:127], v[106:109], v[0:15]
	v_add_f32_e32 v106, v138, v111
	v_add_f32_e32 v106, v99, v106
	v_add_f32_e32 v106, v140, v106
	v_add_f32_e32 v107, v139, v110
	v_add_f32_e32 v106, v100, v106
	v_add_f32_e32 v107, v115, v107
	v_add_f32_e32 v106, v142, v106
	v_pk_mul_f32 v[54:55], v[54:55], v[130:131] op_sel_hi:[1,0]
	v_pk_mul_f32 v[52:53], v[52:53], v[130:131] op_sel_hi:[1,0]
	v_pk_mul_f32 v[50:51], v[50:51], v[130:131] op_sel_hi:[1,0]
	v_pk_mul_f32 v[48:49], v[48:49], v[130:131] op_sel_hi:[1,0]
	v_pk_mul_f32 v[30:31], v[30:31], v[130:131] op_sel_hi:[1,0]
	v_pk_mul_f32 v[28:29], v[28:29], v[130:131] op_sel_hi:[1,0]
	v_pk_mul_f32 v[26:27], v[26:27], v[130:131] op_sel_hi:[1,0]
	v_pk_mul_f32 v[24:25], v[24:25], v[130:131] op_sel_hi:[1,0]
	v_pk_mul_f32 v[22:23], v[22:23], v[130:131] op_sel_hi:[1,0]
	v_pk_mul_f32 v[20:21], v[20:21], v[130:131] op_sel_hi:[1,0]
	v_pk_mul_f32 v[18:19], v[18:19], v[130:131] op_sel_hi:[1,0]
	v_pk_mul_f32 v[16:17], v[16:17], v[130:131] op_sel_hi:[1,0]
	v_lshl_add_u32 v143, v177, 1, v144
	v_add_f32_e32 v107, v141, v107
	v_add_f32_e32 v111, v101, v106
	v_lshl_add_u32 v106, v175, 1, v145
	v_lshl_add_u32 v108, v174, 1, v145
	v_exp_f32_e32 v64, v64
	v_mfma_f32_32x32x16_bf16 v[48:63], v[120:123], v[92:95], v[48:63]
	v_add_f32_e32 v110, v116, v107
	v_add_f32_e32 v110, v134, v110
	v_add_f32_e32 v110, v132, v110
	v_add_f32_e32 v110, v136, v110
	v_add_f32_e32 v111, v135, v111
	v_add_f32_e32 v111, v117, v111
	v_exp_f32_e32 v65, v65
	v_mfma_f32_32x32x16_bf16 v[16:31], v[124:127], v[92:95], v[16:31]
	v_cvt_pk_bf16_f32 v92, v103, v118
	v_cvt_pk_bf16_f32 v93, v119, v90
	v_cvt_pk_bf16_f32 v94, v74, v77
	v_cvt_pk_bf16_f32 v95, v78, v68
	v_cvt_pk_bf16_f32 v120, v104, v105
	v_cvt_pk_bf16_f32 v121, v89, v91
	v_cvt_pk_bf16_f32 v122, v76, v84
	v_cvt_pk_bf16_f32 v123, v66, v64
	ds_read_b64 v[146:147], v143 offset:27648
	ds_read_b64 v[106:107], v106 offset:27648
	ds_read_b64 v[108:109], v108 offset:27648
	v_lshl_add_u32 v143, v176, 1, v144
	ds_read_b64 v[148:149], v143 offset:27648
	v_add_f32_e32 v124, v133, v110
	s_waitcnt lgkmcnt(0)
	v_mfma_f32_32x32x16_bf16 v[48:63], v[146:149], v[92:95], v[48:63]
	v_add_f32_e32 v125, v137, v111
	v_lshlrev_b32_e32 v152, 1, v154
	v_mfma_f32_32x32x16_bf16 v[16:31], v[106:109], v[92:95], v[16:31]
	v_cvt_pk_bf16_f32 v92, v131, v112
	v_cvt_pk_bf16_f32 v93, v113, v114
	v_cvt_pk_bf16_f32 v94, v115, v116
	v_cvt_pk_bf16_f32 v95, v132, v133
	v_cvt_pk_bf16_f32 v96, v96, v97
	v_cvt_pk_bf16_f32 v97, v98, v99
	v_cvt_pk_bf16_f32 v98, v100, v101
	v_add_f32_e32 v100, v103, v124
	v_add_f32_e32 v100, v71, v100
	v_cvt_pk_bf16_f32 v99, v117, v102
	ds_read_b64 v[110:111], v79 offset:27712
	v_lshl_add_u32 v79, v173, 1, v144
	v_add_f32_e32 v100, v118, v100
	ds_read_b64 v[112:113], v79 offset:27648
	v_add_f32_e32 v79, v102, v125
	v_add_f32_e32 v100, v73, v100
	v_add_f32_e32 v79, v104, v79
	v_add_f32_e32 v104, v119, v100
	v_lshl_add_u32 v100, v172, 1, v145
	v_lshl_add_u32 v102, v171, 1, v145
	ds_read_b64 v[100:101], v100 offset:27648
	ds_read_b64 v[102:103], v102 offset:27648
	v_add_f32_e32 v79, v70, v79
	v_add_f32_e32 v79, v105, v79
	v_add_f32_e32 v79, v72, v79
	v_add_f32_e32 v104, v81, v104
	v_add_f32_e32 v79, v89, v79
	v_add_f32_e32 v79, v80, v79
	v_add_f32_e32 v89, v90, v104
	v_add_f32_e32 v89, v87, v89
	v_add_f32_e32 v79, v91, v79
	v_add_f32_e32 v79, v86, v79
	v_add_f32_e32 v74, v74, v89
	s_waitcnt lgkmcnt(2)
	v_mfma_f32_32x32x16_bf16 v[48:63], v[110:113], v[92:95], v[48:63]
	v_cvt_pk_bf16_f32 v90, v71, v73
	v_cvt_pk_bf16_f32 v91, v81, v87
	v_add_f32_e32 v74, v75, v74
	v_add_f32_e32 v74, v77, v74
	v_add_f32_e32 v74, v83, v74
	v_add_f32_e32 v74, v78, v74
	v_add_f32_e32 v78, v88, v74
	s_waitcnt lgkmcnt(0)
	v_mfma_f32_32x32x16_bf16 v[16:31], v[100:103], v[92:95], v[16:31]
	v_cvt_pk_bf16_f32 v92, v75, v83
	v_add_f32_e32 v75, v76, v79
	v_add_f32_e32 v75, v82, v75
	v_add_f32_e32 v75, v84, v75
	v_add_f32_e32 v79, v85, v75
	v_add_f32_e32 v66, v66, v79
	v_cvt_pk_bf16_f32 v93, v88, v69
	v_mfma_f32_32x32x16_bf16 v[32:47], v[146:149], v[120:123], v[32:47]
	v_cvt_pk_bf16_f32 v70, v70, v72
	v_cvt_pk_bf16_f32 v71, v80, v86
	v_cvt_pk_bf16_f32 v72, v82, v85
	v_cvt_pk_bf16_f32 v73, v67, v65
	v_add_f32_e32 v66, v67, v66
	v_add_f32_e32 v67, v68, v78
	v_add_f32_e32 v67, v69, v67
	v_mfma_f32_32x32x16_bf16 v[0:15], v[106:109], v[120:123], v[0:15]
	v_fmac_f32_e32 v67, v156, v130
	ds_bpermute_b32 v68, v166, v67
	v_lshl_add_u32 v80, v169, 1, v144
	v_lshl_add_u32 v74, v168, 1, v145
	v_lshl_add_u32 v76, v167, 1, v145
	ds_read_b64 v[104:105], v80 offset:27648
	ds_read_b64 v[74:75], v74 offset:27648
	ds_read_b64 v[76:77], v76 offset:27648
	v_lshl_add_u32 v80, v170, 1, v144
	v_add_f32_e32 v64, v64, v66
	ds_read_b64 v[106:107], v80 offset:27648
	v_add_f32_e32 v65, v65, v64
	v_mfma_f32_32x32x16_bf16 v[32:47], v[110:113], v[96:99], v[32:47]
	v_fmac_f32_e32 v65, v157, v128
	s_waitcnt lgkmcnt(4)
	v_add_f32_e32 v66, v67, v68
	ds_bpermute_b32 v67, v166, v65
	v_div_scale_f32 v68, s[6:7], v66, v66, 1.0
	v_rcp_f32_e32 v69, v68
	v_add_f32_e32 v64, v155, v129
	v_mfma_f32_32x32x16_bf16 v[0:15], v[100:103], v[96:99], v[0:15]
	s_waitcnt lgkmcnt(0)
; DI int otid() { int t = threadIdx.x & 255; asm volatile("" : "+v"(t)); return t; }
; DI int oidx(int i) { asm volatile("" : "+s"(i)); return i; }
; DI void attn_pass_da(const bfr* __restrict__ P, int b, int tq_wave, int qcol, int kcol, int vcol, int key0, int nkt, char* smem, f32x16 (&o0)[2], f32x16 (&o1)[2]) {
;     ...
;   l0 += __shfl_xor(l0, 32); l1 += __shfl_xor(l1, 32);
;   const float i0 = 1.f / l0, i1 = 1.f / l1;
; #pragma unroll
;   for (int i = 0; i < 16; ++i) { o0[0][i] = acc0[0][i] * i0; o0[1][i] = acc0[1][i] * i0; o1[0][i] = acc1[0][i] * i1; o1[1][i] = acc1[1][i] * i1; }
; }
; DI void store_o(bfr* O, int m, int colbase, int h, const f32x16 (&o)[2]) {
; #pragma unroll
;   for (int dt = 0; dt < 2; ++dt)
; #pragma unroll
;     for (int g4 = 0; g4 < 4; ++g4) {
;       int dv = dt * 32 + 8 * g4 + 4 * h;
;       uint2 pk; pk.x = pack2(o[dt][4 * g4], o[dt][4 * g4 + 1]); pk.y = pack2(o[dt][4 * g4 + 2], o[dt][4 * g4 + 3]);
;       *(uint2*)(O + (size_t)m * DM + colbase + dv) = pk;
;     }
; }
; DN void da_item(const Params& p, int l, int b, int hd, int tq0, int key0, int nkt, char* smem) {
;   const bfr* P = (const bfr*)(p.ws + OFF_P);
;   bfr* O = (bfr*)(p.ws + OFF_HO);
;   const int tid = otid(), lane = tid & 63, w = tid >> 6, r = lane & 31, h = lane >> 5;
;   const float* lv = p.in[oidx(22)] + l * 128;
;   float d01 = (lane < 32) ? lv[lane] * lv[32 + lane] : 0.f;
;   float d23 = (lane < 32) ? lv[64 + lane] * lv[96 + lane] : 0.f;
;   d01 = wave_sum(d01); d23 = wave_sum(d23);
;   float lam_init = 0.8f - 0.6f * expf(-0.3f * (float)l);
;   float lam = expf(d01) - expf(d23) + lam_init;
;   f32x16 o0[2], o1[2];
;   int tqw = tq0 + vhalf() * 128 + w * 32;
;   attn_pass_da(P, b, tqw, 1152 + hd * 64, 1408 + hd * 64, 1664 + hd * 64, key0, nkt, smem, o0, o1);
;   float ss = 0.f;
; #pragma unroll
;   for (int dt = 0; dt < 2; ++dt)
; #pragma unroll
;     for (int i = 0; i < 16; ++i) { float v = o0[dt][i] - lam * o1[dt][i]; o0[dt][i] = v; ss += v * v; }
;   ss += __shfl_xor(ss, 32);
;   float rstd = rsqrtf(ss * (1.f / 64.f) + 1e-6f) * (1.f - lam_init);
;   const float* sg = p.in[oidx(23)] + l * 64;
; #pragma unroll
;   for (int dt = 0; dt < 2; ++dt)
; #pragma unroll
;     for (int i = 0; i < 16; ++i) { int dv = dt * 32 + 8 * (i >> 2) + 4 * h + (i & 3); o0[dt][i] = o0[dt][i] * rstd * sg[dv]; }
	v_add_f32_e32 v65, v65, v67
	v_fma_f32 v67, -v68, v69, 1.0
	v_fmac_f32_e32 v69, v67, v69
	v_div_scale_f32 v67, vcc, 1.0, v66, 1.0
	v_mfma_f32_32x32x16_bf16 v[32:47], v[104:107], v[70:73], v[32:47]
	v_mfma_f32_32x32x16_bf16 v[0:15], v[74:77], v[70:73], v[0:15]
	v_mul_f32_e32 v70, v67, v69
	v_fma_f32 v71, -v68, v70, v67
	v_fmac_f32_e32 v70, v71, v69
	v_fma_f32 v67, -v68, v70, v67
	v_div_scale_f32 v68, s[6:7], v65, v65, 1.0
	v_rcp_f32_e32 v71, v68
	v_div_fmas_f32 v67, v67, v69, v70
	v_div_fixup_f32 v66, v67, v66, 1.0
	v_mfma_f32_32x32x16_bf16 v[48:63], v[104:107], v[90:93], v[48:63]
	v_fma_f32 v67, -v68, v71, 1.0
	v_fmac_f32_e32 v71, v67, v71
	v_div_scale_f32 v67, vcc, 1.0, v65, 1.0
	v_mul_f32_e32 v69, v67, v71
	v_fma_f32 v70, -v68, v69, v67
	v_fmac_f32_e32 v69, v70, v71
	v_fma_f32 v67, -v68, v69, v67
	v_div_fmas_f32 v67, v67, v71, v69
	v_div_fixup_f32 v68, v67, v65, 1.0
	v_mul_f32_e32 v65, v0, v68
	v_mul_f32_e32 v0, v33, v68
	v_mul_f32_e32 v67, v1, v68
	v_mul_f32_e32 v1, v34, v68
	v_mul_f32_e32 v0, v64, v0
	v_mul_f32_e32 v32, v32, v68
	v_mul_f32_e32 v69, v2, v68
	v_mul_f32_e32 v2, v35, v68
	v_mul_f32_e32 v33, v37, v68
	v_mul_f32_e32 v37, v41, v68
	v_mul_f32_e32 v41, v45, v68
	v_fma_f32 v45, v49, v66, -v0
	v_mul_f32_e32 v0, v64, v1
	v_mul_f32_e32 v70, v3, v68
	v_mul_f32_e32 v3, v36, v68
	v_mul_f32_e32 v35, v39, v68
	v_mul_f32_e32 v39, v43, v68
	v_mul_f32_e32 v43, v47, v68
	v_mul_f32_e32 v32, v64, v32
	v_fma_f32 v47, v50, v66, -v0
	v_mul_f32_e32 v0, v64, v2
	v_mul_f32_e32 v36, v40, v68
	v_mul_f32_e32 v40, v44, v68
	v_fma_f32 v44, v48, v66, -v32
	v_fma_f32 v48, v51, v66, -v0
	v_mul_f32_e32 v0, v64, v3
	v_mul_f32_e32 v34, v38, v68
	v_fma_f32 v49, v52, v66, -v0
	v_mul_f32_e32 v0, v64, v33
	s_mov_b32 s6, 23
	v_fma_f32 v50, v53, v66, -v0
	v_mul_f32_e32 v0, v64, v34
	s_ashr_i32 s7, s6, 31
	v_fma_f32 v51, v54, v66, -v0
	v_mul_f32_e32 v0, v64, v35
	s_lshl_b64 s[6:7], s[6:7], 3
	v_fma_f32 v52, v55, v66, -v0
	v_mul_f32_e32 v0, v64, v36
	s_add_u32 s6, s0, s6
	v_mul_f32_e32 v38, v42, v68
	v_fma_f32 v53, v56, v66, -v0
	v_mul_f32_e32 v0, v64, v37
	s_addc_u32 s7, s1, s7
	v_fma_f32 v54, v57, v66, -v0
	v_mul_f32_e32 v0, v64, v38
	s_load_dwordx2 s[6:7], s[6:7], 0x0
	v_mul_f32_e32 v42, v46, v68
	v_mul_f32_e32 v46, v45, v45
	v_fma_f32 v55, v58, v66, -v0
	v_mul_f32_e32 v0, v64, v39
	v_fmac_f32_e32 v46, v44, v44
	v_fma_f32 v56, v59, v66, -v0
	v_mul_f32_e32 v0, v64, v40
	v_fmac_f32_e32 v46, v47, v47
	v_fma_f32 v57, v60, v66, -v0
	v_mul_f32_e32 v0, v64, v41
	v_fmac_f32_e32 v46, v48, v48
	v_fma_f32 v58, v61, v66, -v0
	s_lshl_b64 s[8:9], s[8:9], 2
	v_lshrrev_b32_e32 v0, 3, v164
	v_fmac_f32_e32 v46, v49, v49
	s_waitcnt lgkmcnt(0)
	s_add_u32 s6, s6, s8
	v_and_b32_e32 v59, 4, v0
	v_fmac_f32_e32 v46, v50, v50
	s_addc_u32 s7, s7, s9
	v_lshlrev_b32_e32 v60, 2, v59
	v_mfma_f32_32x32x16_bf16 v[16:31], v[74:77], v[90:93], v[16:31]
	v_fmac_f32_e32 v46, v51, v51
	global_load_dwordx4 v[0:3], v60, s[6:7]
	v_fmac_f32_e32 v46, v52, v52
	v_fmac_f32_e32 v46, v53, v53
	v_mul_f32_e32 v32, v64, v42
	v_fmac_f32_e32 v46, v54, v54
	v_fma_f32 v61, v62, v66, -v32
	v_mul_f32_e32 v32, v64, v43
	v_fmac_f32_e32 v46, v55, v55
	v_fma_f32 v62, v63, v66, -v32
	global_load_dwordx4 v[32:35], v60, s[6:7] offset:32
	v_fmac_f32_e32 v46, v56, v56
	v_fmac_f32_e32 v46, v57, v57
	v_fmac_f32_e32 v46, v58, v58
	v_mul_f32_e32 v36, v64, v65
	v_fmac_f32_e32 v46, v61, v61
	v_fma_f32 v63, v16, v66, -v36
	v_mul_f32_e32 v16, v64, v67
	global_load_dwordx4 v[36:39], v60, s[6:7] offset:64
	v_mul_f32_e32 v4, v4, v68
	v_fmac_f32_e32 v46, v62, v62
	v_fma_f32 v65, v17, v66, -v16
	v_mul_f32_e32 v16, v64, v69
	v_mul_f32_e32 v5, v5, v68
	v_fmac_f32_e32 v46, v63, v63
	v_fma_f32 v67, v18, v66, -v16
	v_mul_f32_e32 v16, v64, v70
	v_mul_f32_e32 v4, v64, v4
	v_fmac_f32_e32 v46, v65, v65
	v_fma_f32 v69, v19, v66, -v16
	v_fma_f32 v70, v20, v66, -v4
	v_mul_f32_e32 v4, v64, v5
	v_fmac_f32_e32 v46, v67, v67
	global_load_dwordx4 v[16:19], v60, s[6:7] offset:96
	v_fma_f32 v71, v21, v66, -v4
	v_pk_mul_f32 v[4:5], v[6:7], v[68:69] op_sel_hi:[1,0]
	v_fmac_f32_e32 v46, v69, v69
	v_pk_mul_f32 v[4:5], v[64:65], v[4:5] op_sel_hi:[0,1]
	v_fmac_f32_e32 v46, v70, v70
	v_pk_fma_f32 v[40:41], v[22:23], v[66:67], v[4:5] op_sel_hi:[1,0,1] neg_lo:[0,0,1] neg_hi:[0,0,1]
	v_pk_mul_f32 v[8:9], v[8:9], v[68:69] op_sel_hi:[1,0]
	v_fmac_f32_e32 v46, v71, v71
	v_pk_mul_f32 v[20:21], v[40:41], v[40:41]
	v_pk_mul_f32 v[8:9], v[64:65], v[8:9] op_sel_hi:[0,1]
	global_load_dwordx4 v[4:7], v60, s[6:7] offset:128
	v_add_f32_e32 v20, v20, v46
	v_pk_fma_f32 v[24:25], v[24:25], v[66:67], v[8:9] op_sel_hi:[1,0,1] neg_lo:[0,0,1] neg_hi:[0,0,1]
	v_add_f32_e32 v20, v21, v20
	v_pk_mul_f32 v[8:9], v[24:25], v[24:25]
	v_pk_mul_f32 v[12:13], v[12:13], v[68:69] op_sel_hi:[1,0]
	v_add_f32_e32 v8, v8, v20
	v_add_f32_e32 v42, v9, v8
	v_pk_mul_f32 v[8:9], v[10:11], v[68:69] op_sel_hi:[1,0]
	global_load_dwordx4 v[20:23], v60, s[6:7] offset:160
	v_pk_mul_f32 v[8:9], v[64:65], v[8:9] op_sel_hi:[0,1]
	v_pk_fma_f32 v[26:27], v[26:27], v[66:67], v[8:9] op_sel_hi:[1,0,1] neg_lo:[0,0,1] neg_hi:[0,0,1]
	v_pk_mul_f32 v[12:13], v[64:65], v[12:13] op_sel_hi:[0,1]
	v_pk_mul_f32 v[8:9], v[26:27], v[26:27]
	v_pk_fma_f32 v[28:29], v[28:29], v[66:67], v[12:13] op_sel_hi:[1,0,1] neg_lo:[0,0,1] neg_hi:[0,0,1]
	v_add_f32_e32 v8, v8, v42
	v_add_f32_e32 v42, v9, v8
	global_load_dwordx4 v[8:11], v60, s[6:7] offset:192
	v_pk_mul_f32 v[12:13], v[28:29], v[28:29]
	s_load_dwordx4 s[8:11], s[0:1], 0x100
	v_add_f32_e32 v12, v12, v42
	v_add_f32_e32 v46, v13, v12
	v_pk_mul_f32 v[42:43], v[14:15], v[68:69] op_sel_hi:[1,0]
	global_load_dwordx4 v[12:15], v60, s[6:7] offset:224
	v_pk_mul_f32 v[42:43], v[64:65], v[42:43] op_sel_hi:[0,1]
	v_pk_fma_f32 v[30:31], v[30:31], v[66:67], v[42:43] op_sel_hi:[1,0,1] neg_lo:[0,0,1] neg_hi:[0,0,1]
	s_mov_b64 s[6:7], 0x2b7c300
	v_pk_mul_f32 v[42:43], v[30:31], v[30:31]
	s_nop 0
	v_add_f32_e32 v42, v42, v46
	v_add_f32_e32 v42, v43, v42
	ds_bpermute_b32 v43, v166, v42
	s_waitcnt lgkmcnt(0)
; DI int oidx(int i) { asm volatile("" : "+s"(i)); return i; }
; DI unsigned pack2(float a, float b) { unsigned r; asm volatile("v_cvt_pk_bf16_f32 %0, %1, %2" : "=v"(r) : "v"(a), "v"(b)); return r; }
; DI void store_o(bfr* O, int m, int colbase, int h, const f32x16 (&o)[2]) {
; #pragma unroll
;   for (int dt = 0; dt < 2; ++dt)
; #pragma unroll
;     for (int g4 = 0; g4 < 4; ++g4) {
;       int dv = dt * 32 + 8 * g4 + 4 * h;
;       uint2 pk; pk.x = pack2(o[dt][4 * g4], o[dt][4 * g4 + 1]); pk.y = pack2(o[dt][4 * g4 + 2], o[dt][4 * g4 + 3]);
;       *(uint2*)(O + (size_t)m * DM + colbase + dv) = pk;
;     }
; DN void da_item(const Params& p, int l, int b, int hd, int tq0, int key0, int nkt, char* smem) {
;     ...
;   ss += __shfl_xor(ss, 32);
;   float rstd = rsqrtf(ss * (1.f / 64.f) + 1e-6f) * (1.f - lam_init);
;   const float* sg = p.in[oidx(23)] + l * 64;
; #pragma unroll
;   for (int dt = 0; dt < 2; ++dt)
; #pragma unroll
;     for (int i = 0; i < 16; ++i) { int dv = dt * 32 + 8 * (i >> 2) + 4 * h + (i & 3); o0[dt][i] = o0[dt][i] * rstd * sg[dv]; }
;   store_o(O, b * TT + tqw + r, 256 + hd * 64, h, o0);
	v_add_f32_e32 v42, v42, v43
	v_fmamk_f32 v42, v42, 0x3c800000, v186
	v_cmp_gt_f32_e32 vcc, s33, v42
	v_mul_f32_e32 v43, 0x4b800000, v42
	s_nop 0
	v_cndmask_b32_e32 v42, v42, v43, vcc
	v_rsq_f32_e32 v42, v42
	s_nop 0
	v_mul_f32_e32 v43, 0x45800000, v42
	v_cndmask_b32_e32 v42, v42, v43, vcc
	v_mul_f32_e32 v42, v162, v42
	v_mul_f32_e32 v43, v44, v42
	s_waitcnt vmcnt(7)
	v_mul_f32_e32 v43, v0, v43
	v_mul_f32_e32 v0, v45, v42
	v_mul_f32_e32 v44, v1, v0
	v_mul_f32_e32 v0, v47, v42
	v_mul_f32_e32 v45, v2, v0
	v_mul_f32_e32 v0, v48, v42
	v_mul_f32_e32 v3, v3, v0
	v_mul_f32_e32 v0, v49, v42
	s_waitcnt vmcnt(6)
	v_mul_f32_e32 v32, v32, v0
	v_mul_f32_e32 v0, v50, v42
	v_mul_f32_e32 v33, v33, v0
	v_mul_f32_e32 v0, v51, v42
	v_mul_f32_e32 v34, v34, v0
	v_mul_f32_e32 v0, v52, v42
	v_mul_f32_e32 v35, v35, v0
	v_mul_f32_e32 v0, v53, v42
	s_waitcnt vmcnt(5)
	v_mul_f32_e32 v36, v36, v0
	v_mul_f32_e32 v0, v54, v42
	v_mul_f32_e32 v37, v37, v0
	v_mul_f32_e32 v0, v55, v42
	v_mul_f32_e32 v38, v38, v0
	v_mul_f32_e32 v0, v56, v42
	v_mul_f32_e32 v39, v39, v0
	v_mul_f32_e32 v0, v57, v42
	s_waitcnt vmcnt(4)
	v_mul_f32_e32 v16, v16, v0
	v_mul_f32_e32 v0, v58, v42
	v_mul_f32_e32 v17, v17, v0
	v_mul_f32_e32 v0, v61, v42
	v_mul_f32_e32 v18, v18, v0
	v_mul_f32_e32 v0, v62, v42
	v_mul_f32_e32 v19, v19, v0
	v_mul_f32_e32 v0, v63, v42
	s_waitcnt vmcnt(3)
	v_mul_f32_e32 v46, v4, v0
	v_mul_f32_e32 v0, v65, v42
	v_mul_f32_e32 v47, v5, v0
	v_mul_f32_e32 v0, v67, v42
	v_mul_f32_e32 v6, v6, v0
	v_mul_f32_e32 v0, v69, v42
	v_mul_f32_e32 v7, v7, v0
	v_mul_f32_e32 v0, v70, v42
	s_waitcnt vmcnt(2)
	v_mul_f32_e32 v20, v20, v0
	v_mul_f32_e32 v0, v71, v42
	v_mul_f32_e32 v21, v21, v0
	v_mul_f32_e32 v0, v40, v42
	v_mul_f32_e32 v22, v22, v0
	v_mul_f32_e32 v0, v41, v42
	v_mul_f32_e32 v23, v23, v0
	v_mul_f32_e32 v0, v24, v42
	s_waitcnt vmcnt(1)
	v_mul_f32_e32 v8, v8, v0
	v_mul_f32_e32 v0, v25, v42
	v_mul_f32_e32 v9, v9, v0
	v_mul_f32_e32 v0, v26, v42
	v_mul_f32_e32 v10, v10, v0
	v_mul_f32_e32 v0, v27, v42
	v_mul_f32_e32 v11, v11, v0
	v_mul_f32_e32 v0, v28, v42
	s_waitcnt vmcnt(0)
	v_mul_f32_e32 v12, v12, v0
	v_mul_f32_e32 v0, v29, v42
	v_mul_f32_e32 v13, v13, v0
	v_mul_f32_e32 v0, v30, v42
	v_mul_f32_e32 v14, v14, v0
	v_mul_f32_e32 v0, v31, v42
	v_mul_f32_e32 v15, v15, v0
	v_and_or_b32 v0, v164, 31, v165
	v_ashrrev_i32_e32 v1, 31, v0
	v_lshlrev_b64 v[0:1], 11, v[0:1]
	v_lshl_add_u64 v[0:1], s[10:11], 0, v[0:1]
	v_lshl_add_u64 v[0:1], v[0:1], 0, v[152:153]
	v_lshlrev_b32_e32 v152, 1, v59
	v_lshl_add_u64 v[0:1], v[0:1], 0, v[152:153]
	v_lshl_add_u64 v[4:5], v[0:1], 0, s[6:7]
	s_mov_b32 s6, 0x2b7c000
	v_add_co_u32_e32 v0, vcc, s6, v0
	v_cvt_pk_bf16_f32 v2, v43, v44
	v_cvt_pk_bf16_f32 v3, v45, v3
	s_nop 1
	v_addc_co_u32_e32 v1, vcc, 0, v1, vcc
	global_store_dwordx2 v[0:1], v[2:3], off offset:768
	v_cvt_pk_bf16_f32 v0, v32, v33
	v_cvt_pk_bf16_f32 v1, v34, v35
	global_store_dwordx2 v[4:5], v[0:1], off offset:16
	v_cvt_pk_bf16_f32 v0, v36, v37
	v_cvt_pk_bf16_f32 v1, v38, v39
	global_store_dwordx2 v[4:5], v[0:1], off offset:32
	v_cvt_pk_bf16_f32 v0, v16, v17
	v_cvt_pk_bf16_f32 v1, v18, v19
	global_store_dwordx2 v[4:5], v[0:1], off offset:48
	v_cvt_pk_bf16_f32 v0, v46, v47
	v_cvt_pk_bf16_f32 v1, v6, v7
	global_store_dwordx2 v[4:5], v[0:1], off offset:64
	v_cvt_pk_bf16_f32 v0, v20, v21
	v_cvt_pk_bf16_f32 v1, v22, v23
	global_store_dwordx2 v[4:5], v[0:1], off offset:80
	v_cvt_pk_bf16_f32 v0, v8, v9
	v_cvt_pk_bf16_f32 v1, v10, v11
	global_store_dwordx2 v[4:5], v[0:1], off offset:96
	v_cvt_pk_bf16_f32 v0, v12, v13
	v_cvt_pk_bf16_f32 v1, v14, v15
	global_store_dwordx2 v[4:5], v[0:1], off offset:112
